# residual epilogue: x read-modify-write as full 128-byte lines (8 rows per instruction; accumulators exchanged once across lanes fr and fr+8 by DPP) instead of 16 half lines per instruction
# speedup vs baseline: 1.0124x; 1.0050x over previous
; #define PG8_STAGE(bufoff, gbase, voff) do { _Pragma("unroll") for (int _i = 0; _i < 2; ++_i) \
;         __builtin_amdgcn_global_load_lds((const unsigned*)((const char*)(gbase) + (voff)[_i]), (LAS unsigned*)(lds + (bufoff) + ldsw + _i * 8192), 16, 0, 0); } while (0)
; #define PG8_LDA(dst, b, h) do { _Pragma("unroll") for (int m = 0; m < 4; ++m) _Pragma("unroll") for (int k = 0; k < 2; ++k) dst[m][k] = *(const LAS bf16x8*)(lds + PG8_SA(b, h) + aoff + m * 2048 + k * 1024); } while (0)
; #define PG8_LDB(dst, b, h) do { _Pragma("unroll") for (int n = 0; n < 2; ++n) _Pragma("unroll") for (int k = 0; k < 2; ++k) dst[n][k] = *(const LAS bf16x8*)(lds + PG8_SB(b, h) + boff + n * 2048 + k * 1024); } while (0)
; #define PG8_MMA(ai, bj, At, Bt) do { __builtin_amdgcn_s_setprio(1); _Pragma("unroll") for (int m = 0; m < 4; ++m) _Pragma("unroll") for (int n = 0; n < 2; ++n) _Pragma("unroll") for (int k = 0; k < 2; ++k) \
;         acc[ai][bj][m][n] = __builtin_amdgcn_mfma_f32_16x16x32_bf16(Bt[n][k], At[m][k], acc[ai][bj][m][n], 0, 0, 0); __builtin_amdgcn_s_setprio(0); } while (0)
; #define PG8_WAIT_V(n) asm volatile("s_waitcnt vmcnt(" #n ")" ::: "memory")
; #define PG8_WAIT_L(n) asm volatile("s_waitcnt lgkmcnt(" #n ")" ::: "memory")
; template <class Epi>
; __device__ __forceinline__ void gemm_phase(LAS unsigned char* lds, const Gemm g, const StaticOrder& S, const Epi& E) {
;     ...
;         for (int t = 0; t < nt; t += 2) {
;             const bool last = (t == nt - 2);
;             const char* a1 = cA + (size_t)(t + 1) * kstep;
;             const char* a2 = last ? nA : cA + (size_t)(t + 2) * kstep; const char* b2 = last ? nB : cB + (size_t)(t + 2) * kstep;
;             const char* a3 = a2 + kstep; const char* b3 = b2 + kstep;
;             PG8_LDB(B0, 0, 0); PG8_SCHED; PG8_LDA(At, 0, 0); PG8_STAGE(PG8_SA(1, 1), a1 + hstepA, voffA);
;             PG8_WAIT_L(8); PG8_BAR; PG8_WAIT_L(0); PG8_MMA(0, 0, At, B0); PG8_BAR; PG8_SCHED;
;             PG8_LDB(B1, 0, 1); PG8_STAGE(PG8_SB(0, 0), b2, voffB);
;             PG8_BAR; PG8_WAIT_L(0); PG8_MMA(0, 1, At, B1); PG8_BAR;
;             PG8_LDA(At, 0, 1); PG8_STAGE(PG8_SA(0, 0), a2, voffA);
;             PG8_BAR; PG8_WAIT_L(0); PG8_MMA(1, 0, At, B0); PG8_BAR; PG8_SCHED;
;             PG8_STAGE(PG8_SB(0, 1), b2 + hstepB, voffB);
;             PG8_WAIT_V(6); PG8_BAR; PG8_MMA(1, 1, At, B1); PG8_BAR;
.LBB0_411:
	ds_read_b128 v[140:143], v149
	ds_read_b128 v[152:155], v149 offset:1024
	ds_read_b128 v[156:159], v149 offset:2048
	ds_read_b128 v[160:163], v149 offset:3072
	s_add_u32 s28, s26, 0x100
	s_addc_u32 s29, s27, 0
	s_cmp_eq_u32 s68, 40
	s_cselect_b32 s35, s11, s29
	s_cselect_b32 s34, s10, s28
	s_cselect_b32 s31, s13, s63
	s_cselect_b32 s30, s12, s49
	v_lshl_add_u64 v[144:145], s[26:27], 0, v[132:133]
	s_add_i32 m0, s36, 0xc000
	ds_read_b128 v[164:167], v150
	ds_read_b128 v[168:171], v150 offset:1024
	ds_read_b128 v[172:175], v150 offset:2048
	ds_read_b128 v[176:179], v150 offset:3072
	ds_read_b128 v[180:183], v150 offset:4096
	ds_read_b128 v[184:187], v150 offset:5120
	ds_read_b128 v[188:191], v150 offset:6144
	ds_read_b128 v[192:195], v150 offset:7168
	global_load_lds_dwordx4 v[144:145], off
	v_lshl_add_u64 v[144:145], s[26:27], 0, v[134:135]
	s_add_i32 m0, s36, 0xe000
	s_nop 0
	global_load_lds_dwordx4 v[144:145], off
	ds_read_b128 v[196:199], v151
	ds_read_b128 v[200:203], v151 offset:1024
	ds_read_b128 v[204:207], v151 offset:2048
	ds_read_b128 v[208:211], v151 offset:3072
	s_waitcnt lgkmcnt(0)
	s_barrier
	s_setprio 1
	v_mfma_f32_16x16x32_bf16 v[124:127], v[140:143], v[164:167], v[124:127]
	v_mfma_f32_16x16x32_bf16 v[120:123], v[156:159], v[164:167], v[120:123]
	v_mfma_f32_16x16x32_bf16 v[112:115], v[140:143], v[172:175], v[112:115]
	v_mfma_f32_16x16x32_bf16 v[104:107], v[156:159], v[172:175], v[104:107]
	v_mfma_f32_16x16x32_bf16 v[92:95], v[140:143], v[180:183], v[92:95]
	v_mfma_f32_16x16x32_bf16 v[88:91], v[156:159], v[180:183], v[88:91]
	v_mfma_f32_16x16x32_bf16 v[80:83], v[140:143], v[188:191], v[80:83]
	v_mfma_f32_16x16x32_bf16 v[72:75], v[156:159], v[188:191], v[72:75]
	v_mfma_f32_16x16x32_bf16 v[124:127], v[152:155], v[168:171], v[124:127]
	v_mfma_f32_16x16x32_bf16 v[120:123], v[160:163], v[168:171], v[120:123]
	v_mfma_f32_16x16x32_bf16 v[112:115], v[152:155], v[176:179], v[112:115]
	v_mfma_f32_16x16x32_bf16 v[104:107], v[160:163], v[176:179], v[104:107]
	v_mfma_f32_16x16x32_bf16 v[92:95], v[152:155], v[184:187], v[92:95]
	v_mfma_f32_16x16x32_bf16 v[88:91], v[160:163], v[184:187], v[88:91]
	v_mfma_f32_16x16x32_bf16 v[80:83], v[152:155], v[192:195], v[80:83]
	v_mfma_f32_16x16x32_bf16 v[72:75], v[160:163], v[192:195], v[72:75]
	v_mfma_f32_16x16x32_bf16 v[116:119], v[196:199], v[164:167], v[116:119]
	v_mfma_f32_16x16x32_bf16 v[108:111], v[204:207], v[164:167], v[108:111]
	v_mfma_f32_16x16x32_bf16 v[100:103], v[196:199], v[172:175], v[100:103]
	v_mfma_f32_16x16x32_bf16 v[96:99], v[204:207], v[172:175], v[96:99]
	v_mfma_f32_16x16x32_bf16 v[84:87], v[196:199], v[180:183], v[84:87]
	v_mfma_f32_16x16x32_bf16 v[76:79], v[204:207], v[180:183], v[76:79]
	v_mfma_f32_16x16x32_bf16 v[68:71], v[196:199], v[188:191], v[68:71]
	v_mfma_f32_16x16x32_bf16 v[64:67], v[204:207], v[188:191], v[64:67]
	v_mfma_f32_16x16x32_bf16 v[116:119], v[200:203], v[168:171], v[116:119]
	v_mfma_f32_16x16x32_bf16 v[108:111], v[208:211], v[168:171], v[108:111]
	v_mfma_f32_16x16x32_bf16 v[100:103], v[200:203], v[176:179], v[100:103]
	v_mfma_f32_16x16x32_bf16 v[96:99], v[208:211], v[176:179], v[96:99]
	v_mfma_f32_16x16x32_bf16 v[84:87], v[200:203], v[184:187], v[84:87]
	v_mfma_f32_16x16x32_bf16 v[76:79], v[208:211], v[184:187], v[76:79]
	v_mfma_f32_16x16x32_bf16 v[68:71], v[200:203], v[192:195], v[68:71]
	v_mfma_f32_16x16x32_bf16 v[64:67], v[208:211], v[192:195], v[64:67]
	s_setprio 0
	s_barrier
	s_nop 1
	ds_read_b128 v[164:167], v150 offset:16384
	ds_read_b128 v[168:171], v150 offset:17408
	ds_read_b128 v[172:175], v150 offset:18432
	ds_read_b128 v[176:179], v150 offset:19456
	ds_read_b128 v[180:183], v150 offset:20480
	ds_read_b128 v[184:187], v150 offset:21504
	ds_read_b128 v[188:191], v150 offset:22528
	ds_read_b128 v[192:195], v150 offset:23552
	s_add_i32 s26, s43, s7
	v_lshl_add_u64 v[144:145], s[30:31], 0, v[128:129]
	s_mov_b32 m0, s26
	s_nop 0
	global_load_lds_dwordx4 v[144:145], off
	v_lshl_add_u64 v[212:213], s[30:31], 0, v[130:131]
	s_add_i32 m0, s26, 0x2000
	s_nop 0
	global_load_lds_dwordx4 v[212:213], off
	s_mov_b32 m0, s36
	v_lshl_add_u64 v[214:215], s[34:35], 0, v[128:129]
	global_load_lds_dwordx4 v[214:215], off
	v_lshl_add_u64 v[216:217], s[34:35], 0, v[130:131]
	s_mov_b32 m0, s37
	s_nop 0
	global_load_lds_dwordx4 v[216:217], off
	s_add_u32 s26, s30, 0xb0000
	s_addc_u32 s27, s31, 0
	s_add_i32 s69, s44, s7
	v_lshl_add_u64 v[254:255], s[26:27], 0, v[128:129]
	s_mov_b32 m0, s69
	s_nop 0
	global_load_lds_dwordx4 v[254:255], off
	v_lshl_add_u64 v[254:255], s[26:27], 0, v[130:131]
	s_add_i32 m0, s69, 0x2000
	s_nop 0
	global_load_lds_dwordx4 v[254:255], off
	s_waitcnt vmcnt(6)
	s_waitcnt lgkmcnt(0)
	s_barrier
; #define PG8_STAGE(bufoff, gbase, voff) do { _Pragma("unroll") for (int _i = 0; _i < 2; ++_i) \
;         __builtin_amdgcn_global_load_lds((const unsigned*)((const char*)(gbase) + (voff)[_i]), (LAS unsigned*)(lds + (bufoff) + ldsw + _i * 8192), 16, 0, 0); } while (0)
; #define PG8_LDA(dst, b, h) do { _Pragma("unroll") for (int m = 0; m < 4; ++m) _Pragma("unroll") for (int k = 0; k < 2; ++k) dst[m][k] = *(const LAS bf16x8*)(lds + PG8_SA(b, h) + aoff + m * 2048 + k * 1024); } while (0)
; #define PG8_LDB(dst, b, h) do { _Pragma("unroll") for (int n = 0; n < 2; ++n) _Pragma("unroll") for (int k = 0; k < 2; ++k) dst[n][k] = *(const LAS bf16x8*)(lds + PG8_SB(b, h) + boff + n * 2048 + k * 1024); } while (0)
; #define PG8_MMA(ai, bj, At, Bt) do { __builtin_amdgcn_s_setprio(1); _Pragma("unroll") for (int m = 0; m < 4; ++m) _Pragma("unroll") for (int n = 0; n < 2; ++n) _Pragma("unroll") for (int k = 0; k < 2; ++k) \
;         acc[ai][bj][m][n] = __builtin_amdgcn_mfma_f32_16x16x32_bf16(Bt[n][k], At[m][k], acc[ai][bj][m][n], 0, 0, 0); __builtin_amdgcn_s_setprio(0); } while (0)
; #define PG8_WAIT_V(n) asm volatile("s_waitcnt vmcnt(" #n ")" ::: "memory")
; #define PG8_WAIT_L(n) asm volatile("s_waitcnt lgkmcnt(" #n ")" ::: "memory")
; #define PG8_BAR __builtin_amdgcn_s_barrier()
; #define PG8_SCHED __builtin_amdgcn_sched_barrier(0)
; template <class Epi>
; __device__ __forceinline__ void gemm_phase(LAS unsigned char* lds, const Gemm g, const StaticOrder& S, const Epi& E) {
;     ...
;             PG8_BAR; PG8_WAIT_L(0); PG8_MMA(0, 1, At, B1); PG8_BAR;
;             PG8_LDA(At, 0, 1); PG8_STAGE(PG8_SA(0, 0), a2, voffA);
;             PG8_BAR; PG8_WAIT_L(0); PG8_MMA(1, 0, At, B0); PG8_BAR; PG8_SCHED;
;             PG8_STAGE(PG8_SB(0, 1), b2 + hstepB, voffB);
;             PG8_WAIT_V(6); PG8_BAR; PG8_MMA(1, 1, At, B1); PG8_BAR;
;             PG8_LDB(B0, 1, 0); PG8_SCHED; PG8_LDA(At, 1, 0); PG8_STAGE(PG8_SA(0, 1), a2 + hstepA, voffA);
;             PG8_WAIT_L(8); PG8_BAR; PG8_WAIT_L(0); PG8_MMA(0, 0, At, B0); PG8_BAR; PG8_SCHED;
;             PG8_LDB(B1, 1, 1); PG8_STAGE(PG8_SB(1, 0), b3, voffB);
;             PG8_BAR; PG8_WAIT_L(0); PG8_MMA(0, 1, At, B1); PG8_BAR;
	s_setprio 1
	v_mfma_f32_16x16x32_bf16 v[60:63], v[140:143], v[164:167], v[60:63]
	v_mfma_f32_16x16x32_bf16 v[56:59], v[156:159], v[164:167], v[56:59]
	v_mfma_f32_16x16x32_bf16 v[48:51], v[140:143], v[172:175], v[48:51]
	v_mfma_f32_16x16x32_bf16 v[40:43], v[156:159], v[172:175], v[40:43]
	v_mfma_f32_16x16x32_bf16 v[28:31], v[140:143], v[180:183], v[28:31]
	v_mfma_f32_16x16x32_bf16 v[24:27], v[156:159], v[180:183], v[24:27]
	v_mfma_f32_16x16x32_bf16 v[16:19], v[140:143], v[188:191], v[16:19]
	v_mfma_f32_16x16x32_bf16 v[8:11], v[156:159], v[188:191], v[8:11]
	v_mfma_f32_16x16x32_bf16 v[60:63], v[152:155], v[168:171], v[60:63]
	v_mfma_f32_16x16x32_bf16 v[56:59], v[160:163], v[168:171], v[56:59]
	v_mfma_f32_16x16x32_bf16 v[48:51], v[152:155], v[176:179], v[48:51]
	v_mfma_f32_16x16x32_bf16 v[40:43], v[160:163], v[176:179], v[40:43]
	v_mfma_f32_16x16x32_bf16 v[28:31], v[152:155], v[184:187], v[28:31]
	v_mfma_f32_16x16x32_bf16 v[24:27], v[160:163], v[184:187], v[24:27]
	v_mfma_f32_16x16x32_bf16 v[16:19], v[152:155], v[192:195], v[16:19]
	v_mfma_f32_16x16x32_bf16 v[8:11], v[160:163], v[192:195], v[8:11]
	v_mfma_f32_16x16x32_bf16 v[52:55], v[196:199], v[164:167], v[52:55]
	v_mfma_f32_16x16x32_bf16 v[44:47], v[204:207], v[164:167], v[44:47]
	v_mfma_f32_16x16x32_bf16 v[36:39], v[196:199], v[172:175], v[36:39]
	v_mfma_f32_16x16x32_bf16 v[32:35], v[204:207], v[172:175], v[32:35]
	v_mfma_f32_16x16x32_bf16 v[20:23], v[196:199], v[180:183], v[20:23]
	v_mfma_f32_16x16x32_bf16 v[12:15], v[204:207], v[180:183], v[12:15]
	v_mfma_f32_16x16x32_bf16 v[4:7], v[196:199], v[188:191], v[4:7]
	v_mfma_f32_16x16x32_bf16 v[0:3], v[204:207], v[188:191], v[0:3]
	v_mfma_f32_16x16x32_bf16 v[52:55], v[200:203], v[168:171], v[52:55]
	v_mfma_f32_16x16x32_bf16 v[44:47], v[208:211], v[168:171], v[44:47]
	v_mfma_f32_16x16x32_bf16 v[36:39], v[200:203], v[176:179], v[36:39]
	v_mfma_f32_16x16x32_bf16 v[32:35], v[208:211], v[176:179], v[32:35]
	v_mfma_f32_16x16x32_bf16 v[20:23], v[200:203], v[184:187], v[20:23]
	v_mfma_f32_16x16x32_bf16 v[12:15], v[208:211], v[184:187], v[12:15]
	v_mfma_f32_16x16x32_bf16 v[4:7], v[200:203], v[192:195], v[4:7]
	v_mfma_f32_16x16x32_bf16 v[0:3], v[208:211], v[192:195], v[0:3]
	s_setprio 0
	s_add_i32 s69, 0, 0x18000
	v_add_u32_e32 v160, s69, v147
	s_barrier
	ds_read_b128 v[140:143], v160
	ds_read_b128 v[152:155], v160 offset:1024
	ds_read_b128 v[156:159], v160 offset:2048
	ds_read_b128 v[160:163], v160 offset:3072
	s_add_u32 s26, s34, 0xb0000
	s_addc_u32 s27, s35, 0
	s_mov_b32 m0, s38
	v_lshl_add_u64 v[196:197], s[26:27], 0, v[128:129]
	ds_read_b128 v[164:167], v150 offset:32768
	ds_read_b128 v[168:171], v150 offset:33792
	ds_read_b128 v[172:175], v150 offset:34816
	ds_read_b128 v[176:179], v150 offset:35840
	ds_read_b128 v[180:183], v150 offset:36864
	ds_read_b128 v[184:187], v150 offset:37888
	ds_read_b128 v[188:191], v150 offset:38912
	ds_read_b128 v[192:195], v150 offset:39936
	global_load_lds_dwordx4 v[196:197], off
	v_lshl_add_u64 v[196:197], s[26:27], 0, v[130:131]
	s_mov_b32 m0, s39
	s_nop 0
	global_load_lds_dwordx4 v[196:197], off
	s_add_i32 s34, 0, 0x1c000
	v_add_u32_e32 v208, s34, v147
	ds_read_b128 v[196:199], v208
	ds_read_b128 v[200:203], v208 offset:1024
	ds_read_b128 v[204:207], v208 offset:2048
	ds_read_b128 v[208:211], v208 offset:3072
	s_waitcnt lgkmcnt(0)
	s_barrier
	s_setprio 1
	v_mfma_f32_16x16x32_bf16 v[124:127], v[140:143], v[164:167], v[124:127]
	v_mfma_f32_16x16x32_bf16 v[120:123], v[156:159], v[164:167], v[120:123]
	v_mfma_f32_16x16x32_bf16 v[112:115], v[140:143], v[172:175], v[112:115]
	v_mfma_f32_16x16x32_bf16 v[104:107], v[156:159], v[172:175], v[104:107]
	v_mfma_f32_16x16x32_bf16 v[92:95], v[140:143], v[180:183], v[92:95]
	v_mfma_f32_16x16x32_bf16 v[88:91], v[156:159], v[180:183], v[88:91]
	v_mfma_f32_16x16x32_bf16 v[80:83], v[140:143], v[188:191], v[80:83]
	v_mfma_f32_16x16x32_bf16 v[72:75], v[156:159], v[188:191], v[72:75]
	v_mfma_f32_16x16x32_bf16 v[124:127], v[152:155], v[168:171], v[124:127]
	v_mfma_f32_16x16x32_bf16 v[120:123], v[160:163], v[168:171], v[120:123]
	v_mfma_f32_16x16x32_bf16 v[112:115], v[152:155], v[176:179], v[112:115]
	v_mfma_f32_16x16x32_bf16 v[104:107], v[160:163], v[176:179], v[104:107]
	v_mfma_f32_16x16x32_bf16 v[92:95], v[152:155], v[184:187], v[92:95]
	v_mfma_f32_16x16x32_bf16 v[88:91], v[160:163], v[184:187], v[88:91]
	v_mfma_f32_16x16x32_bf16 v[80:83], v[152:155], v[192:195], v[80:83]
	v_mfma_f32_16x16x32_bf16 v[72:75], v[160:163], v[192:195], v[72:75]
	v_mfma_f32_16x16x32_bf16 v[116:119], v[196:199], v[164:167], v[116:119]
	v_mfma_f32_16x16x32_bf16 v[108:111], v[204:207], v[164:167], v[108:111]
	v_mfma_f32_16x16x32_bf16 v[100:103], v[196:199], v[172:175], v[100:103]
	v_mfma_f32_16x16x32_bf16 v[96:99], v[204:207], v[172:175], v[96:99]
	v_mfma_f32_16x16x32_bf16 v[84:87], v[196:199], v[180:183], v[84:87]
	v_mfma_f32_16x16x32_bf16 v[76:79], v[204:207], v[180:183], v[76:79]
	v_mfma_f32_16x16x32_bf16 v[68:71], v[196:199], v[188:191], v[68:71]
	v_mfma_f32_16x16x32_bf16 v[64:67], v[204:207], v[188:191], v[64:67]
	v_mfma_f32_16x16x32_bf16 v[116:119], v[200:203], v[168:171], v[116:119]
	v_mfma_f32_16x16x32_bf16 v[108:111], v[208:211], v[168:171], v[108:111]
	v_mfma_f32_16x16x32_bf16 v[100:103], v[200:203], v[176:179], v[100:103]
	v_mfma_f32_16x16x32_bf16 v[96:99], v[208:211], v[176:179], v[96:99]
	v_mfma_f32_16x16x32_bf16 v[84:87], v[200:203], v[184:187], v[84:87]
	v_mfma_f32_16x16x32_bf16 v[76:79], v[208:211], v[184:187], v[76:79]
	v_mfma_f32_16x16x32_bf16 v[68:71], v[200:203], v[192:195], v[68:71]
	v_mfma_f32_16x16x32_bf16 v[64:67], v[208:211], v[192:195], v[64:67]
	s_setprio 0
	s_barrier
; #define PG8_STAGE(bufoff, gbase, voff) do { _Pragma("unroll") for (int _i = 0; _i < 2; ++_i) \
;         __builtin_amdgcn_global_load_lds((const unsigned*)((const char*)(gbase) + (voff)[_i]), (LAS unsigned*)(lds + (bufoff) + ldsw + _i * 8192), 16, 0, 0); } while (0)
; #define PG8_LDA(dst, b, h) do { _Pragma("unroll") for (int m = 0; m < 4; ++m) _Pragma("unroll") for (int k = 0; k < 2; ++k) dst[m][k] = *(const LAS bf16x8*)(lds + PG8_SA(b, h) + aoff + m * 2048 + k * 1024); } while (0)
; #define PG8_BAR __builtin_amdgcn_s_barrier()
; template <class Epi>
; __device__ __forceinline__ void gemm_phase(LAS unsigned char* lds, const Gemm g, const StaticOrder& S, const Epi& E) {
;     ...
;             PG8_WAIT_V(6); PG8_BAR; PG8_MMA(1, 1, At, B1); PG8_BAR;
;             PG8_LDB(B0, 1, 0); PG8_SCHED; PG8_LDA(At, 1, 0); PG8_STAGE(PG8_SA(0, 1), a2 + hstepA, voffA);
;             PG8_WAIT_L(8); PG8_BAR; PG8_WAIT_L(0); PG8_MMA(0, 0, At, B0); PG8_BAR; PG8_SCHED;
;             PG8_LDB(B1, 1, 1); PG8_STAGE(PG8_SB(1, 0), b3, voffB);
;             PG8_BAR; PG8_WAIT_L(0); PG8_MMA(0, 1, At, B1); PG8_BAR;
;             PG8_LDA(At, 1, 1); PG8_STAGE(PG8_SA(1, 0), a3, voffA);
;             PG8_BAR; PG8_WAIT_L(0); PG8_MMA(1, 0, At, B0); PG8_BAR; PG8_SCHED;
;             PG8_STAGE(PG8_SB(1, 1), b3 + hstepB, voffB);
;             PG8_WAIT_V(6); PG8_BAR; PG8_MMA(1, 1, At, B1); PG8_BAR;
;         }
;         E(acc, cur, wr, wc, fr, fq);
;     __device__ __forceinline__ void operator()(AccRef acc, const Unit& u, int wr, int wc, int fr, int fq) const {
;     ...
;         for (int ai = 0; ai < 2; ++ai)
; #pragma unroll
;             for (int mh = 0; mh < 2; ++mh) {
;                 f32x4 bs[2][2][2];
; #pragma unroll
;                 for (int m = 0; m < 2; ++m)
; #pragma unroll
;                     for (int bj = 0; bj < 2; ++bj)
; #pragma unroll
;                         for (int n = 0; n < 2; ++n) bs[m][bj][n] = *(const f32x4*)(base + (size_t)(row0 + ai * 128 + (2 * mh + m) * 16) * D + col0 + bj * 128 + n * 16);
; #pragma unroll
;                 for (int m = 0; m < 2; ++m)
; #pragma unroll
;                     for (int bj = 0; bj < 2; ++bj)
; #pragma unroll
;                         for (int n = 0; n < 2; ++n) *(f32x4*)(out + (size_t)(row0 + ai * 128 + (2 * mh + m) * 16) * D + col0 + bj * 128 + n * 16) = bs[m][bj][n] + sv[bj][n] * (acc[ai][bj][2 * mh + m][n] + bv[bj][n]);
	s_nop 1
	ds_read_b128 v[164:167], v150 offset:49152
	ds_read_b128 v[168:171], v150 offset:50176
	ds_read_b128 v[172:175], v150 offset:51200
	ds_read_b128 v[176:179], v150 offset:52224
	ds_read_b128 v[180:183], v150 offset:53248
	ds_read_b128 v[184:187], v150 offset:54272
	ds_read_b128 v[188:191], v150 offset:55296
	ds_read_b128 v[192:195], v150 offset:56320
	s_add_i32 s26, s69, s7
	v_lshl_add_u64 v[254:255], v[144:145], 0, s[16:17]
	s_mov_b32 m0, s26
	s_nop 0
	global_load_lds_dwordx4 v[254:255], off
	v_lshl_add_u64 v[254:255], v[212:213], 0, s[16:17]
	s_add_i32 m0, s26, 0x2000
	s_nop 0
	global_load_lds_dwordx4 v[254:255], off
	s_mov_b32 m0, s41
	v_lshl_add_u64 v[254:255], v[214:215], 0, s[16:17]
	global_load_lds_dwordx4 v[254:255], off
	v_lshl_add_u64 v[144:145], v[216:217], 0, s[16:17]
	s_mov_b32 m0, s42
	s_nop 0
	global_load_lds_dwordx4 v[144:145], off
	s_add_u32 s26, s30, 0xb0080
	s_addc_u32 s27, s31, 0
	s_add_i32 s30, s34, s7
	v_lshl_add_u64 v[254:255], s[26:27], 0, v[128:129]
	s_mov_b32 m0, s30
	s_nop 0
	global_load_lds_dwordx4 v[254:255], off
	v_lshl_add_u64 v[254:255], s[26:27], 0, v[130:131]
	s_add_i32 m0, s30, 0x2000
	s_nop 0
	global_load_lds_dwordx4 v[254:255], off
	s_waitcnt vmcnt(6)
	s_waitcnt lgkmcnt(0)
	s_barrier
	s_setprio 1
	v_mfma_f32_16x16x32_bf16 v[60:63], v[140:143], v[164:167], v[60:63]
	v_mfma_f32_16x16x32_bf16 v[56:59], v[156:159], v[164:167], v[56:59]
	v_mfma_f32_16x16x32_bf16 v[48:51], v[140:143], v[172:175], v[48:51]
	v_mfma_f32_16x16x32_bf16 v[40:43], v[156:159], v[172:175], v[40:43]
	v_mfma_f32_16x16x32_bf16 v[28:31], v[140:143], v[180:183], v[28:31]
	v_mfma_f32_16x16x32_bf16 v[24:27], v[156:159], v[180:183], v[24:27]
	v_mfma_f32_16x16x32_bf16 v[16:19], v[140:143], v[188:191], v[16:19]
	v_mfma_f32_16x16x32_bf16 v[8:11], v[156:159], v[188:191], v[8:11]
	v_mfma_f32_16x16x32_bf16 v[60:63], v[152:155], v[168:171], v[60:63]
	v_mfma_f32_16x16x32_bf16 v[56:59], v[160:163], v[168:171], v[56:59]
	v_mfma_f32_16x16x32_bf16 v[48:51], v[152:155], v[176:179], v[48:51]
	v_mfma_f32_16x16x32_bf16 v[40:43], v[160:163], v[176:179], v[40:43]
	v_mfma_f32_16x16x32_bf16 v[28:31], v[152:155], v[184:187], v[28:31]
	v_mfma_f32_16x16x32_bf16 v[24:27], v[160:163], v[184:187], v[24:27]
	v_mfma_f32_16x16x32_bf16 v[16:19], v[152:155], v[192:195], v[16:19]
	v_mfma_f32_16x16x32_bf16 v[8:11], v[160:163], v[192:195], v[8:11]
	v_mfma_f32_16x16x32_bf16 v[52:55], v[196:199], v[164:167], v[52:55]
	v_mfma_f32_16x16x32_bf16 v[44:47], v[204:207], v[164:167], v[44:47]
	v_mfma_f32_16x16x32_bf16 v[36:39], v[196:199], v[172:175], v[36:39]
	v_mfma_f32_16x16x32_bf16 v[32:35], v[204:207], v[172:175], v[32:35]
	v_mfma_f32_16x16x32_bf16 v[20:23], v[196:199], v[180:183], v[20:23]
	v_mfma_f32_16x16x32_bf16 v[12:15], v[204:207], v[180:183], v[12:15]
	v_mfma_f32_16x16x32_bf16 v[4:7], v[196:199], v[188:191], v[4:7]
	v_mfma_f32_16x16x32_bf16 v[0:3], v[204:207], v[188:191], v[0:3]
	v_mfma_f32_16x16x32_bf16 v[52:55], v[200:203], v[168:171], v[52:55]
	v_mfma_f32_16x16x32_bf16 v[44:47], v[208:211], v[168:171], v[44:47]
	v_mfma_f32_16x16x32_bf16 v[36:39], v[200:203], v[176:179], v[36:39]
	v_mfma_f32_16x16x32_bf16 v[32:35], v[208:211], v[176:179], v[32:35]
	v_mfma_f32_16x16x32_bf16 v[20:23], v[200:203], v[184:187], v[20:23]
	v_mfma_f32_16x16x32_bf16 v[12:15], v[208:211], v[184:187], v[12:15]
	v_mfma_f32_16x16x32_bf16 v[4:7], v[200:203], v[192:195], v[4:7]
	v_mfma_f32_16x16x32_bf16 v[0:3], v[208:211], v[192:195], v[0:3]
	s_setprio 0
	s_add_i32 s68, s68, 2
	s_add_u32 s49, s49, 0x100
	s_addc_u32 s63, s63, 0
	s_cmp_gt_u32 s68, 41
	s_mov_b64 s[26:27], s[28:29]
	s_barrier
	s_cbranch_scc0 .LBB0_411
	v_lshl_or_b32 v144, s47, 8, v148
	v_lshl_add_u32 v145, s48, 8, v146
	v_lshlrev_b32_e32 v144, 2, v144
	v_lshl_add_u32 v145, v145, 12, v144
	v_add_u32_e32 v216, 0x10000, v145
	v_add_u32_e32 v217, 0x20000, v145
	v_add_u32_e32 v218, 0x30000, v145
	v_add_u32_e32 v220, 0x80000, v145
	v_add_u32_e32 v221, 0x90000, v145
	v_add_u32_e32 v222, 0xa0000, v145
	v_add_u32_e32 v223, 0xb0000, v145
	v_and_b32_e32 v235, 8, v146
	v_cmp_ne_u32_e32 vcc, 0, v235
	v_mov_b32_e32 v232, 0xffff8040
	s_nop 0
	v_cndmask_b32_e32 v232, 0, v232, vcc
	v_mov_b32_e32 v233, 64
	v_mov_b32_e32 v235, 0x8000
	v_cndmask_b32_e32 v233, v235, v233, vcc
	v_add_u32_e32 v224, v145, v232
	v_add_u32_e32 v225, v216, v232
	v_add_u32_e32 v226, v217, v232
	v_add_u32_e32 v227, v218, v232
	v_add_u32_e32 v228, v220, v232
	v_add_u32_e32 v229, v221, v232
	v_add_u32_e32 v230, v222, v232
	v_add_u32_e32 v231, v223, v232
	s_and_b64 vcc, exec, s[8:9]
	s_mov_b32 s47, s45
	s_mov_b32 s48, s46
	s_mov_b64 s[28:29], s[12:13]
	s_mov_b64 s[26:27], s[10:11]
	global_load_dwordx4 v[140:143], v224, s[52:53]
	v_add_u32_e32 v144, v145, v233
	global_load_dwordx4 v[152:155], v144, s[52:53]
	global_load_dwordx4 v[156:159], v224, s[52:53] offset:512
	v_add_u32_e32 v144, v145, v233
	global_load_dwordx4 v[160:163], v144, s[52:53] offset:512
	global_load_dwordx4 v[164:167], v225, s[52:53]
	v_add_u32_e32 v144, v216, v233
	global_load_dwordx4 v[168:171], v144, s[52:53]
	global_load_dwordx4 v[172:175], v225, s[52:53] offset:512
	v_add_u32_e32 v144, v216, v233
	global_load_dwordx4 v[176:179], v144, s[52:53] offset:512
	global_load_dwordx4 v[180:183], v226, s[52:53]
	v_add_u32_e32 v144, v217, v233
	global_load_dwordx4 v[184:187], v144, s[52:53]
	global_load_dwordx4 v[188:191], v226, s[52:53] offset:512
	v_add_u32_e32 v144, v217, v233
	global_load_dwordx4 v[192:195], v144, s[52:53] offset:512
	global_load_dwordx4 v[196:199], v227, s[52:53]
	v_add_u32_e32 v144, v218, v233
	global_load_dwordx4 v[200:203], v144, s[52:53]
	global_load_dwordx4 v[204:207], v227, s[52:53] offset:512
	v_add_u32_e32 v144, v218, v233
	global_load_dwordx4 v[208:211], v144, s[52:53] offset:512
	v_pk_add_f32 v[124:125], v[124:125], 0 op_sel_hi:[1,0]
	v_pk_add_f32 v[126:127], v[126:127], 0 op_sel_hi:[1,0]
	v_pk_add_f32 v[120:121], v[120:121], 0 op_sel_hi:[1,0]
	v_pk_add_f32 v[122:123], v[122:123], 0 op_sel_hi:[1,0]
	v_pk_add_f32 v[116:117], v[116:117], 0 op_sel_hi:[1,0]
	v_pk_add_f32 v[118:119], v[118:119], 0 op_sel_hi:[1,0]
	v_pk_add_f32 v[108:109], v[108:109], 0 op_sel_hi:[1,0]
	v_pk_add_f32 v[110:111], v[110:111], 0 op_sel_hi:[1,0]
	v_pk_add_f32 v[112:113], v[112:113], 0 op_sel_hi:[1,0]
	v_pk_add_f32 v[114:115], v[114:115], 0 op_sel_hi:[1,0]
	v_pk_add_f32 v[104:105], v[104:105], 0 op_sel_hi:[1,0]
	v_pk_add_f32 v[106:107], v[106:107], 0 op_sel_hi:[1,0]
	v_pk_add_f32 v[100:101], v[100:101], 0 op_sel_hi:[1,0]
	v_pk_add_f32 v[102:103], v[102:103], 0 op_sel_hi:[1,0]
	v_pk_add_f32 v[96:97], v[96:97], 0 op_sel_hi:[1,0]
	v_pk_add_f32 v[98:99], v[98:99], 0 op_sel_hi:[1,0]
	v_pk_add_f32 v[92:93], v[92:93], 0 op_sel_hi:[1,0]
	v_pk_add_f32 v[94:95], v[94:95], 0 op_sel_hi:[1,0]
	v_pk_add_f32 v[88:89], v[88:89], 0 op_sel_hi:[1,0]
	v_pk_add_f32 v[90:91], v[90:91], 0 op_sel_hi:[1,0]
	v_pk_add_f32 v[84:85], v[84:85], 0 op_sel_hi:[1,0]
	v_pk_add_f32 v[86:87], v[86:87], 0 op_sel_hi:[1,0]
	v_pk_add_f32 v[76:77], v[76:77], 0 op_sel_hi:[1,0]
	v_pk_add_f32 v[78:79], v[78:79], 0 op_sel_hi:[1,0]
	v_pk_add_f32 v[80:81], v[80:81], 0 op_sel_hi:[1,0]
	v_pk_add_f32 v[82:83], v[82:83], 0 op_sel_hi:[1,0]
	v_pk_add_f32 v[72:73], v[72:73], 0 op_sel_hi:[1,0]
	v_pk_add_f32 v[74:75], v[74:75], 0 op_sel_hi:[1,0]
	v_pk_add_f32 v[68:69], v[68:69], 0 op_sel_hi:[1,0]
	v_pk_add_f32 v[70:71], v[70:71], 0 op_sel_hi:[1,0]
	v_pk_add_f32 v[64:65], v[64:65], 0 op_sel_hi:[1,0]
	v_pk_add_f32 v[66:67], v[66:67], 0 op_sel_hi:[1,0]
	v_pk_add_f32 v[60:61], v[60:61], 0 op_sel_hi:[1,0]
	v_pk_add_f32 v[62:63], v[62:63], 0 op_sel_hi:[1,0]
	v_pk_add_f32 v[56:57], v[56:57], 0 op_sel_hi:[1,0]
	v_pk_add_f32 v[58:59], v[58:59], 0 op_sel_hi:[1,0]
	v_pk_add_f32 v[52:53], v[52:53], 0 op_sel_hi:[1,0]
	v_pk_add_f32 v[54:55], v[54:55], 0 op_sel_hi:[1,0]
	v_pk_add_f32 v[44:45], v[44:45], 0 op_sel_hi:[1,0]
	v_pk_add_f32 v[46:47], v[46:47], 0 op_sel_hi:[1,0]
	v_pk_add_f32 v[48:49], v[48:49], 0 op_sel_hi:[1,0]
	v_pk_add_f32 v[50:51], v[50:51], 0 op_sel_hi:[1,0]
	v_pk_add_f32 v[40:41], v[40:41], 0 op_sel_hi:[1,0]
	v_pk_add_f32 v[42:43], v[42:43], 0 op_sel_hi:[1,0]
	v_pk_add_f32 v[36:37], v[36:37], 0 op_sel_hi:[1,0]
	v_pk_add_f32 v[38:39], v[38:39], 0 op_sel_hi:[1,0]
	v_pk_add_f32 v[32:33], v[32:33], 0 op_sel_hi:[1,0]
	v_pk_add_f32 v[34:35], v[34:35], 0 op_sel_hi:[1,0]
	v_pk_add_f32 v[28:29], v[28:29], 0 op_sel_hi:[1,0]
	v_pk_add_f32 v[30:31], v[30:31], 0 op_sel_hi:[1,0]
	v_pk_add_f32 v[24:25], v[24:25], 0 op_sel_hi:[1,0]
	v_pk_add_f32 v[26:27], v[26:27], 0 op_sel_hi:[1,0]
	v_pk_add_f32 v[20:21], v[20:21], 0 op_sel_hi:[1,0]
	v_pk_add_f32 v[22:23], v[22:23], 0 op_sel_hi:[1,0]
	v_pk_add_f32 v[12:13], v[12:13], 0 op_sel_hi:[1,0]
	v_pk_add_f32 v[14:15], v[14:15], 0 op_sel_hi:[1,0]
	v_pk_add_f32 v[16:17], v[16:17], 0 op_sel_hi:[1,0]
	v_pk_add_f32 v[18:19], v[18:19], 0 op_sel_hi:[1,0]
	v_pk_add_f32 v[8:9], v[8:9], 0 op_sel_hi:[1,0]
	v_pk_add_f32 v[10:11], v[10:11], 0 op_sel_hi:[1,0]
	v_pk_add_f32 v[4:5], v[4:5], 0 op_sel_hi:[1,0]
	v_pk_add_f32 v[6:7], v[6:7], 0 op_sel_hi:[1,0]
	v_pk_add_f32 v[0:1], v[0:1], 0 op_sel_hi:[1,0]
	v_pk_add_f32 v[2:3], v[2:3], 0 op_sel_hi:[1,0]
	s_waitcnt vmcnt(8)
	v_mov_b32_e32 v212, v124
	v_mov_b32_e32 v213, v125
	v_mov_b32_e32 v214, v126
	v_mov_b32_e32 v215, v127
	s_nop 0
	v_mov_b32_dpp v124, v120 row_shr:8 row_mask:0xf bank_mask:0xc
	v_mov_b32_dpp v125, v121 row_shr:8 row_mask:0xf bank_mask:0xc
	v_mov_b32_dpp v126, v122 row_shr:8 row_mask:0xf bank_mask:0xc
	v_mov_b32_dpp v127, v123 row_shr:8 row_mask:0xf bank_mask:0xc
	v_mov_b32_dpp v120, v212 row_shl:8 row_mask:0xf bank_mask:0x3
	v_mov_b32_dpp v121, v213 row_shl:8 row_mask:0xf bank_mask:0x3
	v_mov_b32_dpp v122, v214 row_shl:8 row_mask:0xf bank_mask:0x3
	v_mov_b32_dpp v123, v215 row_shl:8 row_mask:0xf bank_mask:0x3
	v_mov_b32_e32 v212, v116
	v_mov_b32_e32 v213, v117
	v_mov_b32_e32 v214, v118
	v_mov_b32_e32 v215, v119
	s_nop 0
	v_mov_b32_dpp v116, v108 row_shr:8 row_mask:0xf bank_mask:0xc
	v_mov_b32_dpp v117, v109 row_shr:8 row_mask:0xf bank_mask:0xc
	v_mov_b32_dpp v118, v110 row_shr:8 row_mask:0xf bank_mask:0xc
	v_mov_b32_dpp v119, v111 row_shr:8 row_mask:0xf bank_mask:0xc
	v_mov_b32_dpp v108, v212 row_shl:8 row_mask:0xf bank_mask:0x3
	v_mov_b32_dpp v109, v213 row_shl:8 row_mask:0xf bank_mask:0x3
	v_mov_b32_dpp v110, v214 row_shl:8 row_mask:0xf bank_mask:0x3
	v_mov_b32_dpp v111, v215 row_shl:8 row_mask:0xf bank_mask:0x3
	v_mov_b32_e32 v212, v112
	v_mov_b32_e32 v213, v113
	v_mov_b32_e32 v214, v114
	v_mov_b32_e32 v215, v115
	s_nop 0
	v_mov_b32_dpp v112, v104 row_shr:8 row_mask:0xf bank_mask:0xc
	v_mov_b32_dpp v113, v105 row_shr:8 row_mask:0xf bank_mask:0xc
	v_mov_b32_dpp v114, v106 row_shr:8 row_mask:0xf bank_mask:0xc
	v_mov_b32_dpp v115, v107 row_shr:8 row_mask:0xf bank_mask:0xc
	v_mov_b32_dpp v104, v212 row_shl:8 row_mask:0xf bank_mask:0x3
	v_mov_b32_dpp v105, v213 row_shl:8 row_mask:0xf bank_mask:0x3
	v_mov_b32_dpp v106, v214 row_shl:8 row_mask:0xf bank_mask:0x3
	v_mov_b32_dpp v107, v215 row_shl:8 row_mask:0xf bank_mask:0x3
	v_mov_b32_e32 v212, v100
	v_mov_b32_e32 v213, v101
	v_mov_b32_e32 v214, v102
	v_mov_b32_e32 v215, v103
	s_nop 0
	v_mov_b32_dpp v100, v96 row_shr:8 row_mask:0xf bank_mask:0xc
	v_mov_b32_dpp v101, v97 row_shr:8 row_mask:0xf bank_mask:0xc
	v_mov_b32_dpp v102, v98 row_shr:8 row_mask:0xf bank_mask:0xc
	v_mov_b32_dpp v103, v99 row_shr:8 row_mask:0xf bank_mask:0xc
	v_mov_b32_dpp v96, v212 row_shl:8 row_mask:0xf bank_mask:0x3
	v_mov_b32_dpp v97, v213 row_shl:8 row_mask:0xf bank_mask:0x3
	v_mov_b32_dpp v98, v214 row_shl:8 row_mask:0xf bank_mask:0x3
	v_mov_b32_dpp v99, v215 row_shl:8 row_mask:0xf bank_mask:0x3
	v_pk_add_f32 v[124:125], v[124:125], v[140:141]
	v_pk_add_f32 v[126:127], v[126:127], v[142:143]
	v_pk_add_f32 v[120:121], v[120:121], v[152:153]
	v_pk_add_f32 v[122:123], v[122:123], v[154:155]
	v_pk_add_f32 v[116:117], v[116:117], v[156:157]
	v_pk_add_f32 v[118:119], v[118:119], v[158:159]
	v_pk_add_f32 v[108:109], v[108:109], v[160:161]
	v_pk_add_f32 v[110:111], v[110:111], v[162:163]
	v_pk_add_f32 v[112:113], v[112:113], v[164:165]
	v_pk_add_f32 v[114:115], v[114:115], v[166:167]
	v_pk_add_f32 v[104:105], v[104:105], v[168:169]
	v_pk_add_f32 v[106:107], v[106:107], v[170:171]
	v_pk_add_f32 v[100:101], v[100:101], v[172:173]
	v_pk_add_f32 v[102:103], v[102:103], v[174:175]
	v_pk_add_f32 v[96:97], v[96:97], v[176:177]
	v_pk_add_f32 v[98:99], v[98:99], v[178:179]
	global_store_dwordx4 v224, v[124:127], s[52:53]
	v_add_u32_e32 v144, v145, v233
	global_store_dwordx4 v144, v[120:123], s[52:53]
	global_store_dwordx4 v224, v[116:119], s[52:53] offset:512
	v_add_u32_e32 v144, v145, v233
	global_store_dwordx4 v144, v[108:111], s[52:53] offset:512
	global_store_dwordx4 v225, v[112:115], s[52:53]
	v_add_u32_e32 v144, v216, v233
	global_store_dwordx4 v144, v[104:107], s[52:53]
	global_store_dwordx4 v225, v[100:103], s[52:53] offset:512
	v_add_u32_e32 v144, v216, v233
	global_store_dwordx4 v144, v[96:99], s[52:53] offset:512
	global_load_dwordx4 v[140:143], v228, s[52:53]
	v_add_u32_e32 v144, v220, v233
	global_load_dwordx4 v[152:155], v144, s[52:53]
	global_load_dwordx4 v[156:159], v228, s[52:53] offset:512
	v_add_u32_e32 v144, v220, v233
	global_load_dwordx4 v[160:163], v144, s[52:53] offset:512
	global_load_dwordx4 v[164:167], v229, s[52:53]
	v_add_u32_e32 v144, v221, v233
	global_load_dwordx4 v[168:171], v144, s[52:53]
	global_load_dwordx4 v[172:175], v229, s[52:53] offset:512
	v_add_u32_e32 v144, v221, v233
	global_load_dwordx4 v[176:179], v144, s[52:53] offset:512
	s_waitcnt vmcnt(16)
	v_mov_b32_e32 v212, v92
	v_mov_b32_e32 v213, v93
	v_mov_b32_e32 v214, v94
	v_mov_b32_e32 v215, v95
	s_nop 0
	v_mov_b32_dpp v92, v88 row_shr:8 row_mask:0xf bank_mask:0xc
	v_mov_b32_dpp v93, v89 row_shr:8 row_mask:0xf bank_mask:0xc
	v_mov_b32_dpp v94, v90 row_shr:8 row_mask:0xf bank_mask:0xc
	v_mov_b32_dpp v95, v91 row_shr:8 row_mask:0xf bank_mask:0xc
	v_mov_b32_dpp v88, v212 row_shl:8 row_mask:0xf bank_mask:0x3
	v_mov_b32_dpp v89, v213 row_shl:8 row_mask:0xf bank_mask:0x3
	v_mov_b32_dpp v90, v214 row_shl:8 row_mask:0xf bank_mask:0x3
	v_mov_b32_dpp v91, v215 row_shl:8 row_mask:0xf bank_mask:0x3
	v_mov_b32_e32 v212, v84
	v_mov_b32_e32 v213, v85
	v_mov_b32_e32 v214, v86
	v_mov_b32_e32 v215, v87
	s_nop 0
	v_mov_b32_dpp v84, v76 row_shr:8 row_mask:0xf bank_mask:0xc
	v_mov_b32_dpp v85, v77 row_shr:8 row_mask:0xf bank_mask:0xc
	v_mov_b32_dpp v86, v78 row_shr:8 row_mask:0xf bank_mask:0xc
	v_mov_b32_dpp v87, v79 row_shr:8 row_mask:0xf bank_mask:0xc
	v_mov_b32_dpp v76, v212 row_shl:8 row_mask:0xf bank_mask:0x3
	v_mov_b32_dpp v77, v213 row_shl:8 row_mask:0xf bank_mask:0x3
	v_mov_b32_dpp v78, v214 row_shl:8 row_mask:0xf bank_mask:0x3
	v_mov_b32_dpp v79, v215 row_shl:8 row_mask:0xf bank_mask:0x3
	v_mov_b32_e32 v212, v80
	v_mov_b32_e32 v213, v81
	v_mov_b32_e32 v214, v82
	v_mov_b32_e32 v215, v83
	s_nop 0
	v_mov_b32_dpp v80, v72 row_shr:8 row_mask:0xf bank_mask:0xc
	v_mov_b32_dpp v81, v73 row_shr:8 row_mask:0xf bank_mask:0xc
	v_mov_b32_dpp v82, v74 row_shr:8 row_mask:0xf bank_mask:0xc
	v_mov_b32_dpp v83, v75 row_shr:8 row_mask:0xf bank_mask:0xc
	v_mov_b32_dpp v72, v212 row_shl:8 row_mask:0xf bank_mask:0x3
	v_mov_b32_dpp v73, v213 row_shl:8 row_mask:0xf bank_mask:0x3
	v_mov_b32_dpp v74, v214 row_shl:8 row_mask:0xf bank_mask:0x3
	v_mov_b32_dpp v75, v215 row_shl:8 row_mask:0xf bank_mask:0x3
	v_mov_b32_e32 v212, v68
	v_mov_b32_e32 v213, v69
	v_mov_b32_e32 v214, v70
	v_mov_b32_e32 v215, v71
	s_nop 0
	v_mov_b32_dpp v68, v64 row_shr:8 row_mask:0xf bank_mask:0xc
	v_mov_b32_dpp v69, v65 row_shr:8 row_mask:0xf bank_mask:0xc
	v_mov_b32_dpp v70, v66 row_shr:8 row_mask:0xf bank_mask:0xc
	v_mov_b32_dpp v71, v67 row_shr:8 row_mask:0xf bank_mask:0xc
	v_mov_b32_dpp v64, v212 row_shl:8 row_mask:0xf bank_mask:0x3
	v_mov_b32_dpp v65, v213 row_shl:8 row_mask:0xf bank_mask:0x3
	v_mov_b32_dpp v66, v214 row_shl:8 row_mask:0xf bank_mask:0x3
	v_mov_b32_dpp v67, v215 row_shl:8 row_mask:0xf bank_mask:0x3
	v_pk_add_f32 v[92:93], v[92:93], v[180:181]
	v_pk_add_f32 v[94:95], v[94:95], v[182:183]
	v_pk_add_f32 v[88:89], v[88:89], v[184:185]
	v_pk_add_f32 v[90:91], v[90:91], v[186:187]
	v_pk_add_f32 v[84:85], v[84:85], v[188:189]
	v_pk_add_f32 v[86:87], v[86:87], v[190:191]
	v_pk_add_f32 v[76:77], v[76:77], v[192:193]
	v_pk_add_f32 v[78:79], v[78:79], v[194:195]
	v_pk_add_f32 v[80:81], v[80:81], v[196:197]
	v_pk_add_f32 v[82:83], v[82:83], v[198:199]
	v_pk_add_f32 v[72:73], v[72:73], v[200:201]
	v_pk_add_f32 v[74:75], v[74:75], v[202:203]
	v_pk_add_f32 v[68:69], v[68:69], v[204:205]
	v_pk_add_f32 v[70:71], v[70:71], v[206:207]
	v_pk_add_f32 v[64:65], v[64:65], v[208:209]
	v_pk_add_f32 v[66:67], v[66:67], v[210:211]
	global_store_dwordx4 v226, v[92:95], s[52:53]
	v_add_u32_e32 v144, v217, v233
	global_store_dwordx4 v144, v[88:91], s[52:53]
	global_store_dwordx4 v226, v[84:87], s[52:53] offset:512
	v_add_u32_e32 v144, v217, v233
	global_store_dwordx4 v144, v[76:79], s[52:53] offset:512
	global_store_dwordx4 v227, v[80:83], s[52:53]
	v_add_u32_e32 v144, v218, v233
	global_store_dwordx4 v144, v[72:75], s[52:53]
	global_store_dwordx4 v227, v[68:71], s[52:53] offset:512
	v_add_u32_e32 v144, v218, v233
	global_store_dwordx4 v144, v[64:67], s[52:53] offset:512
	global_load_dwordx4 v[180:183], v230, s[52:53]
	v_add_u32_e32 v144, v222, v233
	global_load_dwordx4 v[184:187], v144, s[52:53]
	global_load_dwordx4 v[188:191], v230, s[52:53] offset:512
	v_add_u32_e32 v144, v222, v233
	global_load_dwordx4 v[192:195], v144, s[52:53] offset:512
	global_load_dwordx4 v[196:199], v231, s[52:53]
	v_add_u32_e32 v144, v223, v233
	global_load_dwordx4 v[200:203], v144, s[52:53]
	global_load_dwordx4 v[204:207], v231, s[52:53] offset:512
	v_add_u32_e32 v144, v223, v233
	global_load_dwordx4 v[208:211], v144, s[52:53] offset:512
	s_waitcnt vmcnt(16)
	v_mov_b32_e32 v212, v60
	v_mov_b32_e32 v213, v61
	v_mov_b32_e32 v214, v62
	v_mov_b32_e32 v215, v63
	s_nop 0
	v_mov_b32_dpp v60, v56 row_shr:8 row_mask:0xf bank_mask:0xc
	v_mov_b32_dpp v61, v57 row_shr:8 row_mask:0xf bank_mask:0xc
	v_mov_b32_dpp v62, v58 row_shr:8 row_mask:0xf bank_mask:0xc
	v_mov_b32_dpp v63, v59 row_shr:8 row_mask:0xf bank_mask:0xc
	v_mov_b32_dpp v56, v212 row_shl:8 row_mask:0xf bank_mask:0x3
	v_mov_b32_dpp v57, v213 row_shl:8 row_mask:0xf bank_mask:0x3
	v_mov_b32_dpp v58, v214 row_shl:8 row_mask:0xf bank_mask:0x3
	v_mov_b32_dpp v59, v215 row_shl:8 row_mask:0xf bank_mask:0x3
	v_mov_b32_e32 v212, v52
	v_mov_b32_e32 v213, v53
	v_mov_b32_e32 v214, v54
	v_mov_b32_e32 v215, v55
	s_nop 0
	v_mov_b32_dpp v52, v44 row_shr:8 row_mask:0xf bank_mask:0xc
	v_mov_b32_dpp v53, v45 row_shr:8 row_mask:0xf bank_mask:0xc
	v_mov_b32_dpp v54, v46 row_shr:8 row_mask:0xf bank_mask:0xc
	v_mov_b32_dpp v55, v47 row_shr:8 row_mask:0xf bank_mask:0xc
	v_mov_b32_dpp v44, v212 row_shl:8 row_mask:0xf bank_mask:0x3
	v_mov_b32_dpp v45, v213 row_shl:8 row_mask:0xf bank_mask:0x3
	v_mov_b32_dpp v46, v214 row_shl:8 row_mask:0xf bank_mask:0x3
	v_mov_b32_dpp v47, v215 row_shl:8 row_mask:0xf bank_mask:0x3
	v_mov_b32_e32 v212, v48
	v_mov_b32_e32 v213, v49
	v_mov_b32_e32 v214, v50
	v_mov_b32_e32 v215, v51
	s_nop 0
	v_mov_b32_dpp v48, v40 row_shr:8 row_mask:0xf bank_mask:0xc
	v_mov_b32_dpp v49, v41 row_shr:8 row_mask:0xf bank_mask:0xc
	v_mov_b32_dpp v50, v42 row_shr:8 row_mask:0xf bank_mask:0xc
	v_mov_b32_dpp v51, v43 row_shr:8 row_mask:0xf bank_mask:0xc
	v_mov_b32_dpp v40, v212 row_shl:8 row_mask:0xf bank_mask:0x3
	v_mov_b32_dpp v41, v213 row_shl:8 row_mask:0xf bank_mask:0x3
	v_mov_b32_dpp v42, v214 row_shl:8 row_mask:0xf bank_mask:0x3
	v_mov_b32_dpp v43, v215 row_shl:8 row_mask:0xf bank_mask:0x3
	v_mov_b32_e32 v212, v36
	v_mov_b32_e32 v213, v37
	v_mov_b32_e32 v214, v38
	v_mov_b32_e32 v215, v39
	s_nop 0
	v_mov_b32_dpp v36, v32 row_shr:8 row_mask:0xf bank_mask:0xc
	v_mov_b32_dpp v37, v33 row_shr:8 row_mask:0xf bank_mask:0xc
	v_mov_b32_dpp v38, v34 row_shr:8 row_mask:0xf bank_mask:0xc
	v_mov_b32_dpp v39, v35 row_shr:8 row_mask:0xf bank_mask:0xc
	v_mov_b32_dpp v32, v212 row_shl:8 row_mask:0xf bank_mask:0x3
	v_mov_b32_dpp v33, v213 row_shl:8 row_mask:0xf bank_mask:0x3
	v_mov_b32_dpp v34, v214 row_shl:8 row_mask:0xf bank_mask:0x3
	v_mov_b32_dpp v35, v215 row_shl:8 row_mask:0xf bank_mask:0x3
	v_pk_add_f32 v[60:61], v[60:61], v[140:141]
	v_pk_add_f32 v[62:63], v[62:63], v[142:143]
	v_pk_add_f32 v[56:57], v[56:57], v[152:153]
	v_pk_add_f32 v[58:59], v[58:59], v[154:155]
	v_pk_add_f32 v[52:53], v[52:53], v[156:157]
	v_pk_add_f32 v[54:55], v[54:55], v[158:159]
	v_pk_add_f32 v[44:45], v[44:45], v[160:161]
	v_pk_add_f32 v[46:47], v[46:47], v[162:163]
	v_pk_add_f32 v[48:49], v[48:49], v[164:165]
	v_pk_add_f32 v[50:51], v[50:51], v[166:167]
	v_pk_add_f32 v[40:41], v[40:41], v[168:169]
	v_pk_add_f32 v[42:43], v[42:43], v[170:171]
	v_pk_add_f32 v[36:37], v[36:37], v[172:173]
	v_pk_add_f32 v[38:39], v[38:39], v[174:175]
	v_pk_add_f32 v[32:33], v[32:33], v[176:177]
	v_pk_add_f32 v[34:35], v[34:35], v[178:179]
	global_store_dwordx4 v228, v[60:63], s[52:53]
	v_add_u32_e32 v144, v220, v233
	global_store_dwordx4 v144, v[56:59], s[52:53]
	global_store_dwordx4 v228, v[52:55], s[52:53] offset:512
	v_add_u32_e32 v144, v220, v233
	global_store_dwordx4 v144, v[44:47], s[52:53] offset:512
	global_store_dwordx4 v229, v[48:51], s[52:53]
	v_add_u32_e32 v144, v221, v233
	global_store_dwordx4 v144, v[40:43], s[52:53]
	global_store_dwordx4 v229, v[36:39], s[52:53] offset:512
	v_add_u32_e32 v144, v221, v233
	global_store_dwordx4 v144, v[32:35], s[52:53] offset:512
	s_waitcnt vmcnt(8)
	v_mov_b32_e32 v212, v28
	v_mov_b32_e32 v213, v29
	v_mov_b32_e32 v214, v30
	v_mov_b32_e32 v215, v31
	s_nop 0
	v_mov_b32_dpp v28, v24 row_shr:8 row_mask:0xf bank_mask:0xc
	v_mov_b32_dpp v29, v25 row_shr:8 row_mask:0xf bank_mask:0xc
	v_mov_b32_dpp v30, v26 row_shr:8 row_mask:0xf bank_mask:0xc
	v_mov_b32_dpp v31, v27 row_shr:8 row_mask:0xf bank_mask:0xc
	v_mov_b32_dpp v24, v212 row_shl:8 row_mask:0xf bank_mask:0x3
	v_mov_b32_dpp v25, v213 row_shl:8 row_mask:0xf bank_mask:0x3
	v_mov_b32_dpp v26, v214 row_shl:8 row_mask:0xf bank_mask:0x3
	v_mov_b32_dpp v27, v215 row_shl:8 row_mask:0xf bank_mask:0x3
	v_mov_b32_e32 v212, v20
	v_mov_b32_e32 v213, v21
	v_mov_b32_e32 v214, v22
	v_mov_b32_e32 v215, v23
	s_nop 0
	v_mov_b32_dpp v20, v12 row_shr:8 row_mask:0xf bank_mask:0xc
	v_mov_b32_dpp v21, v13 row_shr:8 row_mask:0xf bank_mask:0xc
	v_mov_b32_dpp v22, v14 row_shr:8 row_mask:0xf bank_mask:0xc
	v_mov_b32_dpp v23, v15 row_shr:8 row_mask:0xf bank_mask:0xc
	v_mov_b32_dpp v12, v212 row_shl:8 row_mask:0xf bank_mask:0x3
	v_mov_b32_dpp v13, v213 row_shl:8 row_mask:0xf bank_mask:0x3
	v_mov_b32_dpp v14, v214 row_shl:8 row_mask:0xf bank_mask:0x3
	v_mov_b32_dpp v15, v215 row_shl:8 row_mask:0xf bank_mask:0x3
	v_mov_b32_e32 v212, v16
	v_mov_b32_e32 v213, v17
	v_mov_b32_e32 v214, v18
	v_mov_b32_e32 v215, v19
	s_nop 0
	v_mov_b32_dpp v16, v8 row_shr:8 row_mask:0xf bank_mask:0xc
	v_mov_b32_dpp v17, v9 row_shr:8 row_mask:0xf bank_mask:0xc
	v_mov_b32_dpp v18, v10 row_shr:8 row_mask:0xf bank_mask:0xc
	v_mov_b32_dpp v19, v11 row_shr:8 row_mask:0xf bank_mask:0xc
	v_mov_b32_dpp v8, v212 row_shl:8 row_mask:0xf bank_mask:0x3
	v_mov_b32_dpp v9, v213 row_shl:8 row_mask:0xf bank_mask:0x3
	v_mov_b32_dpp v10, v214 row_shl:8 row_mask:0xf bank_mask:0x3
	v_mov_b32_dpp v11, v215 row_shl:8 row_mask:0xf bank_mask:0x3
	v_mov_b32_e32 v212, v4
	v_mov_b32_e32 v213, v5
	v_mov_b32_e32 v214, v6
	v_mov_b32_e32 v215, v7
	s_nop 0
	v_mov_b32_dpp v4, v0 row_shr:8 row_mask:0xf bank_mask:0xc
	v_mov_b32_dpp v5, v1 row_shr:8 row_mask:0xf bank_mask:0xc
	v_mov_b32_dpp v6, v2 row_shr:8 row_mask:0xf bank_mask:0xc
	v_mov_b32_dpp v7, v3 row_shr:8 row_mask:0xf bank_mask:0xc
	v_mov_b32_dpp v0, v212 row_shl:8 row_mask:0xf bank_mask:0x3
	v_mov_b32_dpp v1, v213 row_shl:8 row_mask:0xf bank_mask:0x3
	v_mov_b32_dpp v2, v214 row_shl:8 row_mask:0xf bank_mask:0x3
	v_mov_b32_dpp v3, v215 row_shl:8 row_mask:0xf bank_mask:0x3
	v_pk_add_f32 v[28:29], v[28:29], v[180:181]
	v_pk_add_f32 v[30:31], v[30:31], v[182:183]
	v_pk_add_f32 v[24:25], v[24:25], v[184:185]
	v_pk_add_f32 v[26:27], v[26:27], v[186:187]
	v_pk_add_f32 v[20:21], v[20:21], v[188:189]
	v_pk_add_f32 v[22:23], v[22:23], v[190:191]
	v_pk_add_f32 v[12:13], v[12:13], v[192:193]
	v_pk_add_f32 v[14:15], v[14:15], v[194:195]
	v_pk_add_f32 v[16:17], v[16:17], v[196:197]
	v_pk_add_f32 v[18:19], v[18:19], v[198:199]
	v_pk_add_f32 v[8:9], v[8:9], v[200:201]
	v_pk_add_f32 v[10:11], v[10:11], v[202:203]
	v_pk_add_f32 v[4:5], v[4:5], v[204:205]
	v_pk_add_f32 v[6:7], v[6:7], v[206:207]
	v_pk_add_f32 v[0:1], v[0:1], v[208:209]
	v_pk_add_f32 v[2:3], v[2:3], v[210:211]
	global_store_dwordx4 v230, v[28:31], s[52:53]
	v_add_u32_e32 v144, v222, v233
	global_store_dwordx4 v144, v[24:27], s[52:53]
	global_store_dwordx4 v230, v[20:23], s[52:53] offset:512
	v_add_u32_e32 v144, v222, v233
	global_store_dwordx4 v144, v[12:15], s[52:53] offset:512
	global_store_dwordx4 v231, v[16:19], s[52:53]
	v_add_u32_e32 v144, v223, v233
	global_store_dwordx4 v144, v[8:11], s[52:53]
	global_store_dwordx4 v231, v[4:7], s[52:53] offset:512
	v_add_u32_e32 v144, v223, v233
	global_store_dwordx4 v144, v[0:3], s[52:53] offset:512
	s_cbranch_vccz .LBB0_400
	s_waitcnt vmcnt(0)
	s_cmpk_gt_u32 s4, 0xff
	s_cbranch_scc1 .LBB0_415
	s_barrier

.LBB0_860:
	ds_read_b128 v[140:143], v149
	ds_read_b128 v[152:155], v149 offset:1024
	ds_read_b128 v[156:159], v149 offset:2048
	ds_read_b128 v[160:163], v149 offset:3072
	s_add_u32 s30, s28, 0x100
	s_addc_u32 s31, s29, 0
	s_cmp_eq_u32 s68, 40
	s_cselect_b32 s37, s13, s31
	s_cselect_b32 s36, s12, s30
	s_cselect_b32 s35, s15, s63
	s_cselect_b32 s34, s14, s49
	v_lshl_add_u64 v[144:145], s[28:29], 0, v[132:133]
	s_add_i32 m0, s8, 0xc000
	ds_read_b128 v[164:167], v150
	ds_read_b128 v[168:171], v150 offset:1024
	ds_read_b128 v[172:175], v150 offset:2048
	ds_read_b128 v[176:179], v150 offset:3072
	ds_read_b128 v[180:183], v150 offset:4096
	ds_read_b128 v[184:187], v150 offset:5120
	ds_read_b128 v[188:191], v150 offset:6144
	ds_read_b128 v[192:195], v150 offset:7168
	global_load_lds_dwordx4 v[144:145], off
	v_lshl_add_u64 v[144:145], s[28:29], 0, v[134:135]
	s_add_i32 m0, s8, 0xe000
	s_nop 0
	global_load_lds_dwordx4 v[144:145], off
	ds_read_b128 v[196:199], v151
	ds_read_b128 v[200:203], v151 offset:1024
	ds_read_b128 v[204:207], v151 offset:2048
	ds_read_b128 v[208:211], v151 offset:3072
	s_waitcnt lgkmcnt(0)
	s_barrier
	s_setprio 1
	v_mfma_f32_16x16x32_bf16 v[124:127], v[140:143], v[164:167], v[124:127]
	v_mfma_f32_16x16x32_bf16 v[120:123], v[156:159], v[164:167], v[120:123]
	v_mfma_f32_16x16x32_bf16 v[112:115], v[140:143], v[172:175], v[112:115]
	v_mfma_f32_16x16x32_bf16 v[104:107], v[156:159], v[172:175], v[104:107]
	v_mfma_f32_16x16x32_bf16 v[92:95], v[140:143], v[180:183], v[92:95]
	v_mfma_f32_16x16x32_bf16 v[88:91], v[156:159], v[180:183], v[88:91]
	v_mfma_f32_16x16x32_bf16 v[80:83], v[140:143], v[188:191], v[80:83]
	v_mfma_f32_16x16x32_bf16 v[72:75], v[156:159], v[188:191], v[72:75]
	v_mfma_f32_16x16x32_bf16 v[124:127], v[152:155], v[168:171], v[124:127]
	v_mfma_f32_16x16x32_bf16 v[120:123], v[160:163], v[168:171], v[120:123]
	v_mfma_f32_16x16x32_bf16 v[112:115], v[152:155], v[176:179], v[112:115]
	v_mfma_f32_16x16x32_bf16 v[104:107], v[160:163], v[176:179], v[104:107]
	v_mfma_f32_16x16x32_bf16 v[92:95], v[152:155], v[184:187], v[92:95]
	v_mfma_f32_16x16x32_bf16 v[88:91], v[160:163], v[184:187], v[88:91]
	v_mfma_f32_16x16x32_bf16 v[80:83], v[152:155], v[192:195], v[80:83]
	v_mfma_f32_16x16x32_bf16 v[72:75], v[160:163], v[192:195], v[72:75]
	v_mfma_f32_16x16x32_bf16 v[116:119], v[196:199], v[164:167], v[116:119]
	v_mfma_f32_16x16x32_bf16 v[108:111], v[204:207], v[164:167], v[108:111]
	v_mfma_f32_16x16x32_bf16 v[100:103], v[196:199], v[172:175], v[100:103]
	v_mfma_f32_16x16x32_bf16 v[96:99], v[204:207], v[172:175], v[96:99]
	v_mfma_f32_16x16x32_bf16 v[84:87], v[196:199], v[180:183], v[84:87]
	v_mfma_f32_16x16x32_bf16 v[76:79], v[204:207], v[180:183], v[76:79]
	v_mfma_f32_16x16x32_bf16 v[68:71], v[196:199], v[188:191], v[68:71]
	v_mfma_f32_16x16x32_bf16 v[64:67], v[204:207], v[188:191], v[64:67]
	v_mfma_f32_16x16x32_bf16 v[116:119], v[200:203], v[168:171], v[116:119]
	v_mfma_f32_16x16x32_bf16 v[108:111], v[208:211], v[168:171], v[108:111]
	v_mfma_f32_16x16x32_bf16 v[100:103], v[200:203], v[176:179], v[100:103]
	v_mfma_f32_16x16x32_bf16 v[96:99], v[208:211], v[176:179], v[96:99]
	v_mfma_f32_16x16x32_bf16 v[84:87], v[200:203], v[184:187], v[84:87]
	v_mfma_f32_16x16x32_bf16 v[76:79], v[208:211], v[184:187], v[76:79]
	v_mfma_f32_16x16x32_bf16 v[68:71], v[200:203], v[192:195], v[68:71]
	v_mfma_f32_16x16x32_bf16 v[64:67], v[208:211], v[192:195], v[64:67]
	s_setprio 0
	s_barrier
	s_nop 1
	ds_read_b128 v[164:167], v150 offset:16384
	ds_read_b128 v[168:171], v150 offset:17408
	ds_read_b128 v[172:175], v150 offset:18432
	ds_read_b128 v[176:179], v150 offset:19456
	ds_read_b128 v[180:183], v150 offset:20480
	ds_read_b128 v[184:187], v150 offset:21504
	ds_read_b128 v[188:191], v150 offset:22528
	ds_read_b128 v[192:195], v150 offset:23552
	s_add_i32 s28, s43, s7
	v_lshl_add_u64 v[144:145], s[34:35], 0, v[128:129]
	s_mov_b32 m0, s28
	s_nop 0
	global_load_lds_dwordx4 v[144:145], off
	v_lshl_add_u64 v[212:213], s[34:35], 0, v[130:131]
	s_add_i32 m0, s28, 0x2000
	s_nop 0
	global_load_lds_dwordx4 v[212:213], off
	s_mov_b32 m0, s8
	v_lshl_add_u64 v[214:215], s[36:37], 0, v[128:129]
	global_load_lds_dwordx4 v[214:215], off
	v_lshl_add_u64 v[216:217], s[36:37], 0, v[130:131]
	s_mov_b32 m0, s9
	s_nop 0
	global_load_lds_dwordx4 v[216:217], off
	s_add_u32 s28, s34, 0xb0000
	s_addc_u32 s29, s35, 0
	s_add_i32 s69, s44, s7
	v_lshl_add_u64 v[254:255], s[28:29], 0, v[128:129]
	s_mov_b32 m0, s69
	s_nop 0
	global_load_lds_dwordx4 v[254:255], off
	v_lshl_add_u64 v[254:255], s[28:29], 0, v[130:131]
	s_add_i32 m0, s69, 0x2000
	s_nop 0
	global_load_lds_dwordx4 v[254:255], off
	s_waitcnt vmcnt(6)
	s_waitcnt lgkmcnt(0)
	s_barrier
	s_setprio 1
	v_mfma_f32_16x16x32_bf16 v[60:63], v[140:143], v[164:167], v[60:63]
	v_mfma_f32_16x16x32_bf16 v[56:59], v[156:159], v[164:167], v[56:59]
	v_mfma_f32_16x16x32_bf16 v[48:51], v[140:143], v[172:175], v[48:51]
	v_mfma_f32_16x16x32_bf16 v[40:43], v[156:159], v[172:175], v[40:43]
	v_mfma_f32_16x16x32_bf16 v[28:31], v[140:143], v[180:183], v[28:31]
	v_mfma_f32_16x16x32_bf16 v[24:27], v[156:159], v[180:183], v[24:27]
	v_mfma_f32_16x16x32_bf16 v[16:19], v[140:143], v[188:191], v[16:19]
	v_mfma_f32_16x16x32_bf16 v[8:11], v[156:159], v[188:191], v[8:11]
	v_mfma_f32_16x16x32_bf16 v[60:63], v[152:155], v[168:171], v[60:63]
	v_mfma_f32_16x16x32_bf16 v[56:59], v[160:163], v[168:171], v[56:59]
	v_mfma_f32_16x16x32_bf16 v[48:51], v[152:155], v[176:179], v[48:51]
	v_mfma_f32_16x16x32_bf16 v[40:43], v[160:163], v[176:179], v[40:43]
	v_mfma_f32_16x16x32_bf16 v[28:31], v[152:155], v[184:187], v[28:31]
	v_mfma_f32_16x16x32_bf16 v[24:27], v[160:163], v[184:187], v[24:27]
	v_mfma_f32_16x16x32_bf16 v[16:19], v[152:155], v[192:195], v[16:19]
	v_mfma_f32_16x16x32_bf16 v[8:11], v[160:163], v[192:195], v[8:11]
	v_mfma_f32_16x16x32_bf16 v[52:55], v[196:199], v[164:167], v[52:55]
	v_mfma_f32_16x16x32_bf16 v[44:47], v[204:207], v[164:167], v[44:47]
	v_mfma_f32_16x16x32_bf16 v[36:39], v[196:199], v[172:175], v[36:39]
	v_mfma_f32_16x16x32_bf16 v[32:35], v[204:207], v[172:175], v[32:35]
	v_mfma_f32_16x16x32_bf16 v[20:23], v[196:199], v[180:183], v[20:23]
	v_mfma_f32_16x16x32_bf16 v[12:15], v[204:207], v[180:183], v[12:15]
	v_mfma_f32_16x16x32_bf16 v[4:7], v[196:199], v[188:191], v[4:7]
	v_mfma_f32_16x16x32_bf16 v[0:3], v[204:207], v[188:191], v[0:3]
	v_mfma_f32_16x16x32_bf16 v[52:55], v[200:203], v[168:171], v[52:55]
	v_mfma_f32_16x16x32_bf16 v[44:47], v[208:211], v[168:171], v[44:47]
	v_mfma_f32_16x16x32_bf16 v[36:39], v[200:203], v[176:179], v[36:39]
	v_mfma_f32_16x16x32_bf16 v[32:35], v[208:211], v[176:179], v[32:35]
	v_mfma_f32_16x16x32_bf16 v[20:23], v[200:203], v[184:187], v[20:23]
	v_mfma_f32_16x16x32_bf16 v[12:15], v[208:211], v[184:187], v[12:15]
	v_mfma_f32_16x16x32_bf16 v[4:7], v[200:203], v[192:195], v[4:7]
	v_mfma_f32_16x16x32_bf16 v[0:3], v[208:211], v[192:195], v[0:3]
	s_setprio 0
	s_add_i32 s69, 0, 0x18000
	v_add_u32_e32 v160, s69, v147
	s_barrier
	ds_read_b128 v[140:143], v160
	ds_read_b128 v[152:155], v160 offset:1024
	ds_read_b128 v[156:159], v160 offset:2048
	ds_read_b128 v[160:163], v160 offset:3072
	s_add_u32 s28, s36, 0xb0000
	s_addc_u32 s29, s37, 0
	s_mov_b32 m0, s38
	v_lshl_add_u64 v[196:197], s[28:29], 0, v[128:129]
	ds_read_b128 v[164:167], v150 offset:32768
	ds_read_b128 v[168:171], v150 offset:33792
	ds_read_b128 v[172:175], v150 offset:34816
	ds_read_b128 v[176:179], v150 offset:35840
	ds_read_b128 v[180:183], v150 offset:36864
	ds_read_b128 v[184:187], v150 offset:37888
	ds_read_b128 v[188:191], v150 offset:38912
	ds_read_b128 v[192:195], v150 offset:39936
	global_load_lds_dwordx4 v[196:197], off
	v_lshl_add_u64 v[196:197], s[28:29], 0, v[130:131]
	s_mov_b32 m0, s39
	s_nop 0
	global_load_lds_dwordx4 v[196:197], off
	s_add_i32 s36, 0, 0x1c000
	v_add_u32_e32 v208, s36, v147
	ds_read_b128 v[196:199], v208
	ds_read_b128 v[200:203], v208 offset:1024
	ds_read_b128 v[204:207], v208 offset:2048
	ds_read_b128 v[208:211], v208 offset:3072
	s_waitcnt lgkmcnt(0)
	s_barrier
	s_setprio 1
	v_mfma_f32_16x16x32_bf16 v[124:127], v[140:143], v[164:167], v[124:127]
	v_mfma_f32_16x16x32_bf16 v[120:123], v[156:159], v[164:167], v[120:123]
	v_mfma_f32_16x16x32_bf16 v[112:115], v[140:143], v[172:175], v[112:115]
	v_mfma_f32_16x16x32_bf16 v[104:107], v[156:159], v[172:175], v[104:107]
	v_mfma_f32_16x16x32_bf16 v[92:95], v[140:143], v[180:183], v[92:95]
	v_mfma_f32_16x16x32_bf16 v[88:91], v[156:159], v[180:183], v[88:91]
	v_mfma_f32_16x16x32_bf16 v[80:83], v[140:143], v[188:191], v[80:83]
	v_mfma_f32_16x16x32_bf16 v[72:75], v[156:159], v[188:191], v[72:75]
	v_mfma_f32_16x16x32_bf16 v[124:127], v[152:155], v[168:171], v[124:127]
	v_mfma_f32_16x16x32_bf16 v[120:123], v[160:163], v[168:171], v[120:123]
	v_mfma_f32_16x16x32_bf16 v[112:115], v[152:155], v[176:179], v[112:115]
	v_mfma_f32_16x16x32_bf16 v[104:107], v[160:163], v[176:179], v[104:107]
	v_mfma_f32_16x16x32_bf16 v[92:95], v[152:155], v[184:187], v[92:95]
	v_mfma_f32_16x16x32_bf16 v[88:91], v[160:163], v[184:187], v[88:91]
	v_mfma_f32_16x16x32_bf16 v[80:83], v[152:155], v[192:195], v[80:83]
	v_mfma_f32_16x16x32_bf16 v[72:75], v[160:163], v[192:195], v[72:75]
	v_mfma_f32_16x16x32_bf16 v[116:119], v[196:199], v[164:167], v[116:119]
	v_mfma_f32_16x16x32_bf16 v[108:111], v[204:207], v[164:167], v[108:111]
	v_mfma_f32_16x16x32_bf16 v[100:103], v[196:199], v[172:175], v[100:103]
	v_mfma_f32_16x16x32_bf16 v[96:99], v[204:207], v[172:175], v[96:99]
	v_mfma_f32_16x16x32_bf16 v[84:87], v[196:199], v[180:183], v[84:87]
	v_mfma_f32_16x16x32_bf16 v[76:79], v[204:207], v[180:183], v[76:79]
	v_mfma_f32_16x16x32_bf16 v[68:71], v[196:199], v[188:191], v[68:71]
	v_mfma_f32_16x16x32_bf16 v[64:67], v[204:207], v[188:191], v[64:67]
	v_mfma_f32_16x16x32_bf16 v[116:119], v[200:203], v[168:171], v[116:119]
	v_mfma_f32_16x16x32_bf16 v[108:111], v[208:211], v[168:171], v[108:111]
	v_mfma_f32_16x16x32_bf16 v[100:103], v[200:203], v[176:179], v[100:103]
	v_mfma_f32_16x16x32_bf16 v[96:99], v[208:211], v[176:179], v[96:99]
	v_mfma_f32_16x16x32_bf16 v[84:87], v[200:203], v[184:187], v[84:87]
	v_mfma_f32_16x16x32_bf16 v[76:79], v[208:211], v[184:187], v[76:79]
	v_mfma_f32_16x16x32_bf16 v[68:71], v[200:203], v[192:195], v[68:71]
	v_mfma_f32_16x16x32_bf16 v[64:67], v[208:211], v[192:195], v[64:67]
	s_setprio 0
	s_barrier
	s_nop 1
	ds_read_b128 v[164:167], v150 offset:49152
	ds_read_b128 v[168:171], v150 offset:50176
	ds_read_b128 v[172:175], v150 offset:51200
	ds_read_b128 v[176:179], v150 offset:52224
	ds_read_b128 v[180:183], v150 offset:53248
	ds_read_b128 v[184:187], v150 offset:54272
	ds_read_b128 v[188:191], v150 offset:55296
	ds_read_b128 v[192:195], v150 offset:56320
	s_add_i32 s28, s69, s7
	v_lshl_add_u64 v[254:255], v[144:145], 0, s[20:21]
	s_mov_b32 m0, s28
	s_nop 0
	global_load_lds_dwordx4 v[254:255], off
	v_lshl_add_u64 v[254:255], v[212:213], 0, s[20:21]
	s_add_i32 m0, s28, 0x2000
	s_nop 0
	global_load_lds_dwordx4 v[254:255], off
	s_mov_b32 m0, s41
	v_lshl_add_u64 v[254:255], v[214:215], 0, s[20:21]
	global_load_lds_dwordx4 v[254:255], off
	v_lshl_add_u64 v[144:145], v[216:217], 0, s[20:21]
	s_mov_b32 m0, s42
	s_nop 0
	global_load_lds_dwordx4 v[144:145], off
	s_add_u32 s28, s34, 0xb0080
	s_addc_u32 s29, s35, 0
	s_add_i32 s34, s36, s7
	v_lshl_add_u64 v[254:255], s[28:29], 0, v[128:129]
	s_mov_b32 m0, s34
	s_nop 0
	global_load_lds_dwordx4 v[254:255], off
	v_lshl_add_u64 v[254:255], s[28:29], 0, v[130:131]
	s_add_i32 m0, s34, 0x2000
	s_nop 0
	global_load_lds_dwordx4 v[254:255], off
	s_waitcnt vmcnt(6)
	s_waitcnt lgkmcnt(0)
	s_barrier
	s_setprio 1
	v_mfma_f32_16x16x32_bf16 v[60:63], v[140:143], v[164:167], v[60:63]
	v_mfma_f32_16x16x32_bf16 v[56:59], v[156:159], v[164:167], v[56:59]
	v_mfma_f32_16x16x32_bf16 v[48:51], v[140:143], v[172:175], v[48:51]
	v_mfma_f32_16x16x32_bf16 v[40:43], v[156:159], v[172:175], v[40:43]
	v_mfma_f32_16x16x32_bf16 v[28:31], v[140:143], v[180:183], v[28:31]
	v_mfma_f32_16x16x32_bf16 v[24:27], v[156:159], v[180:183], v[24:27]
	v_mfma_f32_16x16x32_bf16 v[16:19], v[140:143], v[188:191], v[16:19]
	v_mfma_f32_16x16x32_bf16 v[8:11], v[156:159], v[188:191], v[8:11]
	v_mfma_f32_16x16x32_bf16 v[60:63], v[152:155], v[168:171], v[60:63]
	v_mfma_f32_16x16x32_bf16 v[56:59], v[160:163], v[168:171], v[56:59]
	v_mfma_f32_16x16x32_bf16 v[48:51], v[152:155], v[176:179], v[48:51]
	v_mfma_f32_16x16x32_bf16 v[40:43], v[160:163], v[176:179], v[40:43]
	v_mfma_f32_16x16x32_bf16 v[28:31], v[152:155], v[184:187], v[28:31]
	v_mfma_f32_16x16x32_bf16 v[24:27], v[160:163], v[184:187], v[24:27]
	v_mfma_f32_16x16x32_bf16 v[16:19], v[152:155], v[192:195], v[16:19]
	v_mfma_f32_16x16x32_bf16 v[8:11], v[160:163], v[192:195], v[8:11]
	v_mfma_f32_16x16x32_bf16 v[52:55], v[196:199], v[164:167], v[52:55]
	v_mfma_f32_16x16x32_bf16 v[44:47], v[204:207], v[164:167], v[44:47]
	v_mfma_f32_16x16x32_bf16 v[36:39], v[196:199], v[172:175], v[36:39]
	v_mfma_f32_16x16x32_bf16 v[32:35], v[204:207], v[172:175], v[32:35]
	v_mfma_f32_16x16x32_bf16 v[20:23], v[196:199], v[180:183], v[20:23]
	v_mfma_f32_16x16x32_bf16 v[12:15], v[204:207], v[180:183], v[12:15]
	v_mfma_f32_16x16x32_bf16 v[4:7], v[196:199], v[188:191], v[4:7]
	v_mfma_f32_16x16x32_bf16 v[0:3], v[204:207], v[188:191], v[0:3]
	v_mfma_f32_16x16x32_bf16 v[52:55], v[200:203], v[168:171], v[52:55]
	v_mfma_f32_16x16x32_bf16 v[44:47], v[208:211], v[168:171], v[44:47]
	v_mfma_f32_16x16x32_bf16 v[36:39], v[200:203], v[176:179], v[36:39]
	v_mfma_f32_16x16x32_bf16 v[32:35], v[208:211], v[176:179], v[32:35]
	v_mfma_f32_16x16x32_bf16 v[20:23], v[200:203], v[184:187], v[20:23]
	v_mfma_f32_16x16x32_bf16 v[12:15], v[208:211], v[184:187], v[12:15]
	v_mfma_f32_16x16x32_bf16 v[4:7], v[200:203], v[192:195], v[4:7]
	v_mfma_f32_16x16x32_bf16 v[0:3], v[208:211], v[192:195], v[0:3]
	s_setprio 0
	s_add_i32 s68, s68, 2
	s_add_u32 s49, s49, 0x100
	s_addc_u32 s63, s63, 0
	s_cmp_gt_u32 s68, 41
	s_mov_b64 s[28:29], s[30:31]
	s_barrier
	s_cbranch_scc0 .LBB0_860
	v_lshl_or_b32 v144, s47, 8, v148
	v_lshl_add_u32 v145, s48, 8, v146
	v_lshlrev_b32_e32 v144, 2, v144
	v_lshl_add_u32 v145, v145, 12, v144
	v_add_u32_e32 v216, 0x10000, v145
	v_add_u32_e32 v217, 0x20000, v145
	v_add_u32_e32 v218, 0x30000, v145
	v_add_u32_e32 v220, 0x80000, v145
	v_add_u32_e32 v221, 0x90000, v145
	v_add_u32_e32 v222, 0xa0000, v145
	v_add_u32_e32 v223, 0xb0000, v145
	v_and_b32_e32 v235, 8, v146
	v_cmp_ne_u32_e32 vcc, 0, v235
	v_mov_b32_e32 v232, 0xffff8040
	s_nop 0
	v_cndmask_b32_e32 v232, 0, v232, vcc
	v_mov_b32_e32 v233, 64
	v_mov_b32_e32 v235, 0x8000
	v_cndmask_b32_e32 v233, v235, v233, vcc
	v_add_u32_e32 v224, v145, v232
	v_add_u32_e32 v225, v216, v232
	v_add_u32_e32 v226, v217, v232
	v_add_u32_e32 v227, v218, v232
	v_add_u32_e32 v228, v220, v232
	v_add_u32_e32 v229, v221, v232
	v_add_u32_e32 v230, v222, v232
	v_add_u32_e32 v231, v223, v232
	s_and_b64 vcc, exec, s[10:11]
	s_mov_b32 s47, s45
	s_mov_b32 s48, s46
	s_mov_b64 s[30:31], s[14:15]
	s_mov_b64 s[28:29], s[12:13]
	global_load_dwordx4 v[140:143], v224, s[52:53]
	v_add_u32_e32 v144, v145, v233
	global_load_dwordx4 v[152:155], v144, s[52:53]
	global_load_dwordx4 v[156:159], v224, s[52:53] offset:512
	v_add_u32_e32 v144, v145, v233
	global_load_dwordx4 v[160:163], v144, s[52:53] offset:512
	global_load_dwordx4 v[164:167], v225, s[52:53]
	v_add_u32_e32 v144, v216, v233
	global_load_dwordx4 v[168:171], v144, s[52:53]
	global_load_dwordx4 v[172:175], v225, s[52:53] offset:512
	v_add_u32_e32 v144, v216, v233
	global_load_dwordx4 v[176:179], v144, s[52:53] offset:512
	global_load_dwordx4 v[180:183], v226, s[52:53]
	v_add_u32_e32 v144, v217, v233
	global_load_dwordx4 v[184:187], v144, s[52:53]
	global_load_dwordx4 v[188:191], v226, s[52:53] offset:512
	v_add_u32_e32 v144, v217, v233
	global_load_dwordx4 v[192:195], v144, s[52:53] offset:512
	global_load_dwordx4 v[196:199], v227, s[52:53]
	v_add_u32_e32 v144, v218, v233
	global_load_dwordx4 v[200:203], v144, s[52:53]
	global_load_dwordx4 v[204:207], v227, s[52:53] offset:512
	v_add_u32_e32 v144, v218, v233
	global_load_dwordx4 v[208:211], v144, s[52:53] offset:512
	v_pk_add_f32 v[124:125], v[124:125], 0 op_sel_hi:[1,0]
	v_pk_add_f32 v[126:127], v[126:127], 0 op_sel_hi:[1,0]
	v_pk_add_f32 v[120:121], v[120:121], 0 op_sel_hi:[1,0]
	v_pk_add_f32 v[122:123], v[122:123], 0 op_sel_hi:[1,0]
	v_pk_add_f32 v[116:117], v[116:117], 0 op_sel_hi:[1,0]
	v_pk_add_f32 v[118:119], v[118:119], 0 op_sel_hi:[1,0]
	v_pk_add_f32 v[108:109], v[108:109], 0 op_sel_hi:[1,0]
	v_pk_add_f32 v[110:111], v[110:111], 0 op_sel_hi:[1,0]
	v_pk_add_f32 v[112:113], v[112:113], 0 op_sel_hi:[1,0]
	v_pk_add_f32 v[114:115], v[114:115], 0 op_sel_hi:[1,0]
	v_pk_add_f32 v[104:105], v[104:105], 0 op_sel_hi:[1,0]
	v_pk_add_f32 v[106:107], v[106:107], 0 op_sel_hi:[1,0]
	v_pk_add_f32 v[100:101], v[100:101], 0 op_sel_hi:[1,0]
	v_pk_add_f32 v[102:103], v[102:103], 0 op_sel_hi:[1,0]
	v_pk_add_f32 v[96:97], v[96:97], 0 op_sel_hi:[1,0]
	v_pk_add_f32 v[98:99], v[98:99], 0 op_sel_hi:[1,0]
	v_pk_add_f32 v[92:93], v[92:93], 0 op_sel_hi:[1,0]
	v_pk_add_f32 v[94:95], v[94:95], 0 op_sel_hi:[1,0]
	v_pk_add_f32 v[88:89], v[88:89], 0 op_sel_hi:[1,0]
	v_pk_add_f32 v[90:91], v[90:91], 0 op_sel_hi:[1,0]
	v_pk_add_f32 v[84:85], v[84:85], 0 op_sel_hi:[1,0]
	v_pk_add_f32 v[86:87], v[86:87], 0 op_sel_hi:[1,0]
	v_pk_add_f32 v[76:77], v[76:77], 0 op_sel_hi:[1,0]
	v_pk_add_f32 v[78:79], v[78:79], 0 op_sel_hi:[1,0]
	v_pk_add_f32 v[80:81], v[80:81], 0 op_sel_hi:[1,0]
	v_pk_add_f32 v[82:83], v[82:83], 0 op_sel_hi:[1,0]
	v_pk_add_f32 v[72:73], v[72:73], 0 op_sel_hi:[1,0]
	v_pk_add_f32 v[74:75], v[74:75], 0 op_sel_hi:[1,0]
	v_pk_add_f32 v[68:69], v[68:69], 0 op_sel_hi:[1,0]
	v_pk_add_f32 v[70:71], v[70:71], 0 op_sel_hi:[1,0]
	v_pk_add_f32 v[64:65], v[64:65], 0 op_sel_hi:[1,0]
	v_pk_add_f32 v[66:67], v[66:67], 0 op_sel_hi:[1,0]
	v_pk_add_f32 v[60:61], v[60:61], 0 op_sel_hi:[1,0]
	v_pk_add_f32 v[62:63], v[62:63], 0 op_sel_hi:[1,0]
	v_pk_add_f32 v[56:57], v[56:57], 0 op_sel_hi:[1,0]
	v_pk_add_f32 v[58:59], v[58:59], 0 op_sel_hi:[1,0]
	v_pk_add_f32 v[52:53], v[52:53], 0 op_sel_hi:[1,0]
	v_pk_add_f32 v[54:55], v[54:55], 0 op_sel_hi:[1,0]
	v_pk_add_f32 v[44:45], v[44:45], 0 op_sel_hi:[1,0]
	v_pk_add_f32 v[46:47], v[46:47], 0 op_sel_hi:[1,0]
	v_pk_add_f32 v[48:49], v[48:49], 0 op_sel_hi:[1,0]
	v_pk_add_f32 v[50:51], v[50:51], 0 op_sel_hi:[1,0]
	v_pk_add_f32 v[40:41], v[40:41], 0 op_sel_hi:[1,0]
	v_pk_add_f32 v[42:43], v[42:43], 0 op_sel_hi:[1,0]
	v_pk_add_f32 v[36:37], v[36:37], 0 op_sel_hi:[1,0]
	v_pk_add_f32 v[38:39], v[38:39], 0 op_sel_hi:[1,0]
	v_pk_add_f32 v[32:33], v[32:33], 0 op_sel_hi:[1,0]
	v_pk_add_f32 v[34:35], v[34:35], 0 op_sel_hi:[1,0]
	v_pk_add_f32 v[28:29], v[28:29], 0 op_sel_hi:[1,0]
	v_pk_add_f32 v[30:31], v[30:31], 0 op_sel_hi:[1,0]
	v_pk_add_f32 v[24:25], v[24:25], 0 op_sel_hi:[1,0]
	v_pk_add_f32 v[26:27], v[26:27], 0 op_sel_hi:[1,0]
	v_pk_add_f32 v[20:21], v[20:21], 0 op_sel_hi:[1,0]
	v_pk_add_f32 v[22:23], v[22:23], 0 op_sel_hi:[1,0]
	v_pk_add_f32 v[12:13], v[12:13], 0 op_sel_hi:[1,0]
	v_pk_add_f32 v[14:15], v[14:15], 0 op_sel_hi:[1,0]
	v_pk_add_f32 v[16:17], v[16:17], 0 op_sel_hi:[1,0]
	v_pk_add_f32 v[18:19], v[18:19], 0 op_sel_hi:[1,0]
	v_pk_add_f32 v[8:9], v[8:9], 0 op_sel_hi:[1,0]
	v_pk_add_f32 v[10:11], v[10:11], 0 op_sel_hi:[1,0]
	v_pk_add_f32 v[4:5], v[4:5], 0 op_sel_hi:[1,0]
	v_pk_add_f32 v[6:7], v[6:7], 0 op_sel_hi:[1,0]
	v_pk_add_f32 v[0:1], v[0:1], 0 op_sel_hi:[1,0]
	v_pk_add_f32 v[2:3], v[2:3], 0 op_sel_hi:[1,0]
	s_waitcnt vmcnt(8)
	v_mov_b32_e32 v212, v124
	v_mov_b32_e32 v213, v125
	v_mov_b32_e32 v214, v126
	v_mov_b32_e32 v215, v127
	s_nop 0
	v_mov_b32_dpp v124, v120 row_shr:8 row_mask:0xf bank_mask:0xc
	v_mov_b32_dpp v125, v121 row_shr:8 row_mask:0xf bank_mask:0xc
	v_mov_b32_dpp v126, v122 row_shr:8 row_mask:0xf bank_mask:0xc
	v_mov_b32_dpp v127, v123 row_shr:8 row_mask:0xf bank_mask:0xc
	v_mov_b32_dpp v120, v212 row_shl:8 row_mask:0xf bank_mask:0x3
	v_mov_b32_dpp v121, v213 row_shl:8 row_mask:0xf bank_mask:0x3
	v_mov_b32_dpp v122, v214 row_shl:8 row_mask:0xf bank_mask:0x3
	v_mov_b32_dpp v123, v215 row_shl:8 row_mask:0xf bank_mask:0x3
	v_mov_b32_e32 v212, v116
	v_mov_b32_e32 v213, v117
	v_mov_b32_e32 v214, v118
	v_mov_b32_e32 v215, v119
	s_nop 0
	v_mov_b32_dpp v116, v108 row_shr:8 row_mask:0xf bank_mask:0xc
	v_mov_b32_dpp v117, v109 row_shr:8 row_mask:0xf bank_mask:0xc
	v_mov_b32_dpp v118, v110 row_shr:8 row_mask:0xf bank_mask:0xc
	v_mov_b32_dpp v119, v111 row_shr:8 row_mask:0xf bank_mask:0xc
	v_mov_b32_dpp v108, v212 row_shl:8 row_mask:0xf bank_mask:0x3
	v_mov_b32_dpp v109, v213 row_shl:8 row_mask:0xf bank_mask:0x3
	v_mov_b32_dpp v110, v214 row_shl:8 row_mask:0xf bank_mask:0x3
	v_mov_b32_dpp v111, v215 row_shl:8 row_mask:0xf bank_mask:0x3
	v_mov_b32_e32 v212, v112
	v_mov_b32_e32 v213, v113
	v_mov_b32_e32 v214, v114
	v_mov_b32_e32 v215, v115
	s_nop 0
	v_mov_b32_dpp v112, v104 row_shr:8 row_mask:0xf bank_mask:0xc
	v_mov_b32_dpp v113, v105 row_shr:8 row_mask:0xf bank_mask:0xc
	v_mov_b32_dpp v114, v106 row_shr:8 row_mask:0xf bank_mask:0xc
	v_mov_b32_dpp v115, v107 row_shr:8 row_mask:0xf bank_mask:0xc
	v_mov_b32_dpp v104, v212 row_shl:8 row_mask:0xf bank_mask:0x3
	v_mov_b32_dpp v105, v213 row_shl:8 row_mask:0xf bank_mask:0x3
	v_mov_b32_dpp v106, v214 row_shl:8 row_mask:0xf bank_mask:0x3
	v_mov_b32_dpp v107, v215 row_shl:8 row_mask:0xf bank_mask:0x3
	v_mov_b32_e32 v212, v100
	v_mov_b32_e32 v213, v101
	v_mov_b32_e32 v214, v102
	v_mov_b32_e32 v215, v103
	s_nop 0
	v_mov_b32_dpp v100, v96 row_shr:8 row_mask:0xf bank_mask:0xc
	v_mov_b32_dpp v101, v97 row_shr:8 row_mask:0xf bank_mask:0xc
	v_mov_b32_dpp v102, v98 row_shr:8 row_mask:0xf bank_mask:0xc
	v_mov_b32_dpp v103, v99 row_shr:8 row_mask:0xf bank_mask:0xc
	v_mov_b32_dpp v96, v212 row_shl:8 row_mask:0xf bank_mask:0x3
	v_mov_b32_dpp v97, v213 row_shl:8 row_mask:0xf bank_mask:0x3
	v_mov_b32_dpp v98, v214 row_shl:8 row_mask:0xf bank_mask:0x3
	v_mov_b32_dpp v99, v215 row_shl:8 row_mask:0xf bank_mask:0x3
	v_pk_add_f32 v[124:125], v[124:125], v[140:141]
	v_pk_add_f32 v[126:127], v[126:127], v[142:143]
	v_pk_add_f32 v[120:121], v[120:121], v[152:153]
	v_pk_add_f32 v[122:123], v[122:123], v[154:155]
	v_pk_add_f32 v[116:117], v[116:117], v[156:157]
	v_pk_add_f32 v[118:119], v[118:119], v[158:159]
	v_pk_add_f32 v[108:109], v[108:109], v[160:161]
	v_pk_add_f32 v[110:111], v[110:111], v[162:163]
	v_pk_add_f32 v[112:113], v[112:113], v[164:165]
	v_pk_add_f32 v[114:115], v[114:115], v[166:167]
	v_pk_add_f32 v[104:105], v[104:105], v[168:169]
	v_pk_add_f32 v[106:107], v[106:107], v[170:171]
	v_pk_add_f32 v[100:101], v[100:101], v[172:173]
	v_pk_add_f32 v[102:103], v[102:103], v[174:175]
	v_pk_add_f32 v[96:97], v[96:97], v[176:177]
	v_pk_add_f32 v[98:99], v[98:99], v[178:179]
	global_store_dwordx4 v224, v[124:127], s[52:53]
	v_add_u32_e32 v144, v145, v233
	global_store_dwordx4 v144, v[120:123], s[52:53]
	global_store_dwordx4 v224, v[116:119], s[52:53] offset:512
	v_add_u32_e32 v144, v145, v233
	global_store_dwordx4 v144, v[108:111], s[52:53] offset:512
	global_store_dwordx4 v225, v[112:115], s[52:53]
	v_add_u32_e32 v144, v216, v233
	global_store_dwordx4 v144, v[104:107], s[52:53]
	global_store_dwordx4 v225, v[100:103], s[52:53] offset:512
	v_add_u32_e32 v144, v216, v233
	global_store_dwordx4 v144, v[96:99], s[52:53] offset:512
	global_load_dwordx4 v[140:143], v228, s[52:53]
	v_add_u32_e32 v144, v220, v233
	global_load_dwordx4 v[152:155], v144, s[52:53]
	global_load_dwordx4 v[156:159], v228, s[52:53] offset:512
	v_add_u32_e32 v144, v220, v233
	global_load_dwordx4 v[160:163], v144, s[52:53] offset:512
	global_load_dwordx4 v[164:167], v229, s[52:53]
	v_add_u32_e32 v144, v221, v233
	global_load_dwordx4 v[168:171], v144, s[52:53]
	global_load_dwordx4 v[172:175], v229, s[52:53] offset:512
	v_add_u32_e32 v144, v221, v233
	global_load_dwordx4 v[176:179], v144, s[52:53] offset:512
	s_waitcnt vmcnt(16)
	v_mov_b32_e32 v212, v92
	v_mov_b32_e32 v213, v93
	v_mov_b32_e32 v214, v94
	v_mov_b32_e32 v215, v95
	s_nop 0
	v_mov_b32_dpp v92, v88 row_shr:8 row_mask:0xf bank_mask:0xc
	v_mov_b32_dpp v93, v89 row_shr:8 row_mask:0xf bank_mask:0xc
	v_mov_b32_dpp v94, v90 row_shr:8 row_mask:0xf bank_mask:0xc
	v_mov_b32_dpp v95, v91 row_shr:8 row_mask:0xf bank_mask:0xc
	v_mov_b32_dpp v88, v212 row_shl:8 row_mask:0xf bank_mask:0x3
	v_mov_b32_dpp v89, v213 row_shl:8 row_mask:0xf bank_mask:0x3
	v_mov_b32_dpp v90, v214 row_shl:8 row_mask:0xf bank_mask:0x3
	v_mov_b32_dpp v91, v215 row_shl:8 row_mask:0xf bank_mask:0x3
	v_mov_b32_e32 v212, v84
	v_mov_b32_e32 v213, v85
	v_mov_b32_e32 v214, v86
	v_mov_b32_e32 v215, v87
	s_nop 0
	v_mov_b32_dpp v84, v76 row_shr:8 row_mask:0xf bank_mask:0xc
	v_mov_b32_dpp v85, v77 row_shr:8 row_mask:0xf bank_mask:0xc
	v_mov_b32_dpp v86, v78 row_shr:8 row_mask:0xf bank_mask:0xc
	v_mov_b32_dpp v87, v79 row_shr:8 row_mask:0xf bank_mask:0xc
	v_mov_b32_dpp v76, v212 row_shl:8 row_mask:0xf bank_mask:0x3
	v_mov_b32_dpp v77, v213 row_shl:8 row_mask:0xf bank_mask:0x3
	v_mov_b32_dpp v78, v214 row_shl:8 row_mask:0xf bank_mask:0x3
	v_mov_b32_dpp v79, v215 row_shl:8 row_mask:0xf bank_mask:0x3
	v_mov_b32_e32 v212, v80
	v_mov_b32_e32 v213, v81
	v_mov_b32_e32 v214, v82
	v_mov_b32_e32 v215, v83
	s_nop 0
	v_mov_b32_dpp v80, v72 row_shr:8 row_mask:0xf bank_mask:0xc
	v_mov_b32_dpp v81, v73 row_shr:8 row_mask:0xf bank_mask:0xc
	v_mov_b32_dpp v82, v74 row_shr:8 row_mask:0xf bank_mask:0xc
	v_mov_b32_dpp v83, v75 row_shr:8 row_mask:0xf bank_mask:0xc
	v_mov_b32_dpp v72, v212 row_shl:8 row_mask:0xf bank_mask:0x3
	v_mov_b32_dpp v73, v213 row_shl:8 row_mask:0xf bank_mask:0x3
	v_mov_b32_dpp v74, v214 row_shl:8 row_mask:0xf bank_mask:0x3
	v_mov_b32_dpp v75, v215 row_shl:8 row_mask:0xf bank_mask:0x3
	v_mov_b32_e32 v212, v68
	v_mov_b32_e32 v213, v69
	v_mov_b32_e32 v214, v70
	v_mov_b32_e32 v215, v71
	s_nop 0
	v_mov_b32_dpp v68, v64 row_shr:8 row_mask:0xf bank_mask:0xc
	v_mov_b32_dpp v69, v65 row_shr:8 row_mask:0xf bank_mask:0xc
	v_mov_b32_dpp v70, v66 row_shr:8 row_mask:0xf bank_mask:0xc
	v_mov_b32_dpp v71, v67 row_shr:8 row_mask:0xf bank_mask:0xc
	v_mov_b32_dpp v64, v212 row_shl:8 row_mask:0xf bank_mask:0x3
	v_mov_b32_dpp v65, v213 row_shl:8 row_mask:0xf bank_mask:0x3
	v_mov_b32_dpp v66, v214 row_shl:8 row_mask:0xf bank_mask:0x3
	v_mov_b32_dpp v67, v215 row_shl:8 row_mask:0xf bank_mask:0x3
	v_pk_add_f32 v[92:93], v[92:93], v[180:181]
	v_pk_add_f32 v[94:95], v[94:95], v[182:183]
	v_pk_add_f32 v[88:89], v[88:89], v[184:185]
	v_pk_add_f32 v[90:91], v[90:91], v[186:187]
	v_pk_add_f32 v[84:85], v[84:85], v[188:189]
	v_pk_add_f32 v[86:87], v[86:87], v[190:191]
	v_pk_add_f32 v[76:77], v[76:77], v[192:193]
	v_pk_add_f32 v[78:79], v[78:79], v[194:195]
	v_pk_add_f32 v[80:81], v[80:81], v[196:197]
	v_pk_add_f32 v[82:83], v[82:83], v[198:199]
	v_pk_add_f32 v[72:73], v[72:73], v[200:201]
	v_pk_add_f32 v[74:75], v[74:75], v[202:203]
	v_pk_add_f32 v[68:69], v[68:69], v[204:205]
	v_pk_add_f32 v[70:71], v[70:71], v[206:207]
	v_pk_add_f32 v[64:65], v[64:65], v[208:209]
	v_pk_add_f32 v[66:67], v[66:67], v[210:211]
	global_store_dwordx4 v226, v[92:95], s[52:53]
	v_add_u32_e32 v144, v217, v233
	global_store_dwordx4 v144, v[88:91], s[52:53]
	global_store_dwordx4 v226, v[84:87], s[52:53] offset:512
	v_add_u32_e32 v144, v217, v233
	global_store_dwordx4 v144, v[76:79], s[52:53] offset:512
	global_store_dwordx4 v227, v[80:83], s[52:53]
	v_add_u32_e32 v144, v218, v233
	global_store_dwordx4 v144, v[72:75], s[52:53]
	global_store_dwordx4 v227, v[68:71], s[52:53] offset:512
	v_add_u32_e32 v144, v218, v233
	global_store_dwordx4 v144, v[64:67], s[52:53] offset:512
	global_load_dwordx4 v[180:183], v230, s[52:53]
	v_add_u32_e32 v144, v222, v233
	global_load_dwordx4 v[184:187], v144, s[52:53]
	global_load_dwordx4 v[188:191], v230, s[52:53] offset:512
	v_add_u32_e32 v144, v222, v233
	global_load_dwordx4 v[192:195], v144, s[52:53] offset:512
	global_load_dwordx4 v[196:199], v231, s[52:53]
	v_add_u32_e32 v144, v223, v233
	global_load_dwordx4 v[200:203], v144, s[52:53]
	global_load_dwordx4 v[204:207], v231, s[52:53] offset:512
	v_add_u32_e32 v144, v223, v233
	global_load_dwordx4 v[208:211], v144, s[52:53] offset:512
	s_waitcnt vmcnt(16)
	v_mov_b32_e32 v212, v60
	v_mov_b32_e32 v213, v61
	v_mov_b32_e32 v214, v62
	v_mov_b32_e32 v215, v63
	s_nop 0
	v_mov_b32_dpp v60, v56 row_shr:8 row_mask:0xf bank_mask:0xc
	v_mov_b32_dpp v61, v57 row_shr:8 row_mask:0xf bank_mask:0xc
	v_mov_b32_dpp v62, v58 row_shr:8 row_mask:0xf bank_mask:0xc
	v_mov_b32_dpp v63, v59 row_shr:8 row_mask:0xf bank_mask:0xc
	v_mov_b32_dpp v56, v212 row_shl:8 row_mask:0xf bank_mask:0x3
	v_mov_b32_dpp v57, v213 row_shl:8 row_mask:0xf bank_mask:0x3
	v_mov_b32_dpp v58, v214 row_shl:8 row_mask:0xf bank_mask:0x3
	v_mov_b32_dpp v59, v215 row_shl:8 row_mask:0xf bank_mask:0x3
	v_mov_b32_e32 v212, v52
	v_mov_b32_e32 v213, v53
	v_mov_b32_e32 v214, v54
	v_mov_b32_e32 v215, v55
	s_nop 0
	v_mov_b32_dpp v52, v44 row_shr:8 row_mask:0xf bank_mask:0xc
	v_mov_b32_dpp v53, v45 row_shr:8 row_mask:0xf bank_mask:0xc
	v_mov_b32_dpp v54, v46 row_shr:8 row_mask:0xf bank_mask:0xc
	v_mov_b32_dpp v55, v47 row_shr:8 row_mask:0xf bank_mask:0xc
	v_mov_b32_dpp v44, v212 row_shl:8 row_mask:0xf bank_mask:0x3
	v_mov_b32_dpp v45, v213 row_shl:8 row_mask:0xf bank_mask:0x3
	v_mov_b32_dpp v46, v214 row_shl:8 row_mask:0xf bank_mask:0x3
	v_mov_b32_dpp v47, v215 row_shl:8 row_mask:0xf bank_mask:0x3
	v_mov_b32_e32 v212, v48
	v_mov_b32_e32 v213, v49
	v_mov_b32_e32 v214, v50
	v_mov_b32_e32 v215, v51
	s_nop 0
	v_mov_b32_dpp v48, v40 row_shr:8 row_mask:0xf bank_mask:0xc
	v_mov_b32_dpp v49, v41 row_shr:8 row_mask:0xf bank_mask:0xc
	v_mov_b32_dpp v50, v42 row_shr:8 row_mask:0xf bank_mask:0xc
	v_mov_b32_dpp v51, v43 row_shr:8 row_mask:0xf bank_mask:0xc
	v_mov_b32_dpp v40, v212 row_shl:8 row_mask:0xf bank_mask:0x3
	v_mov_b32_dpp v41, v213 row_shl:8 row_mask:0xf bank_mask:0x3
	v_mov_b32_dpp v42, v214 row_shl:8 row_mask:0xf bank_mask:0x3
	v_mov_b32_dpp v43, v215 row_shl:8 row_mask:0xf bank_mask:0x3
	v_mov_b32_e32 v212, v36
	v_mov_b32_e32 v213, v37
	v_mov_b32_e32 v214, v38
	v_mov_b32_e32 v215, v39
	s_nop 0
	v_mov_b32_dpp v36, v32 row_shr:8 row_mask:0xf bank_mask:0xc
	v_mov_b32_dpp v37, v33 row_shr:8 row_mask:0xf bank_mask:0xc
	v_mov_b32_dpp v38, v34 row_shr:8 row_mask:0xf bank_mask:0xc
	v_mov_b32_dpp v39, v35 row_shr:8 row_mask:0xf bank_mask:0xc
	v_mov_b32_dpp v32, v212 row_shl:8 row_mask:0xf bank_mask:0x3
	v_mov_b32_dpp v33, v213 row_shl:8 row_mask:0xf bank_mask:0x3
	v_mov_b32_dpp v34, v214 row_shl:8 row_mask:0xf bank_mask:0x3
	v_mov_b32_dpp v35, v215 row_shl:8 row_mask:0xf bank_mask:0x3
	v_pk_add_f32 v[60:61], v[60:61], v[140:141]
	v_pk_add_f32 v[62:63], v[62:63], v[142:143]
	v_pk_add_f32 v[56:57], v[56:57], v[152:153]
	v_pk_add_f32 v[58:59], v[58:59], v[154:155]
	v_pk_add_f32 v[52:53], v[52:53], v[156:157]
	v_pk_add_f32 v[54:55], v[54:55], v[158:159]
	v_pk_add_f32 v[44:45], v[44:45], v[160:161]
	v_pk_add_f32 v[46:47], v[46:47], v[162:163]
	v_pk_add_f32 v[48:49], v[48:49], v[164:165]
	v_pk_add_f32 v[50:51], v[50:51], v[166:167]
	v_pk_add_f32 v[40:41], v[40:41], v[168:169]
	v_pk_add_f32 v[42:43], v[42:43], v[170:171]
	v_pk_add_f32 v[36:37], v[36:37], v[172:173]
	v_pk_add_f32 v[38:39], v[38:39], v[174:175]
	v_pk_add_f32 v[32:33], v[32:33], v[176:177]
	v_pk_add_f32 v[34:35], v[34:35], v[178:179]
	global_store_dwordx4 v228, v[60:63], s[52:53]
	v_add_u32_e32 v144, v220, v233
	global_store_dwordx4 v144, v[56:59], s[52:53]
	global_store_dwordx4 v228, v[52:55], s[52:53] offset:512
	v_add_u32_e32 v144, v220, v233
	global_store_dwordx4 v144, v[44:47], s[52:53] offset:512
	global_store_dwordx4 v229, v[48:51], s[52:53]
	v_add_u32_e32 v144, v221, v233
	global_store_dwordx4 v144, v[40:43], s[52:53]
	global_store_dwordx4 v229, v[36:39], s[52:53] offset:512
	v_add_u32_e32 v144, v221, v233
	global_store_dwordx4 v144, v[32:35], s[52:53] offset:512
	s_waitcnt vmcnt(8)
	v_mov_b32_e32 v212, v28
	v_mov_b32_e32 v213, v29
	v_mov_b32_e32 v214, v30
	v_mov_b32_e32 v215, v31
	s_nop 0
	v_mov_b32_dpp v28, v24 row_shr:8 row_mask:0xf bank_mask:0xc
	v_mov_b32_dpp v29, v25 row_shr:8 row_mask:0xf bank_mask:0xc
	v_mov_b32_dpp v30, v26 row_shr:8 row_mask:0xf bank_mask:0xc
	v_mov_b32_dpp v31, v27 row_shr:8 row_mask:0xf bank_mask:0xc
	v_mov_b32_dpp v24, v212 row_shl:8 row_mask:0xf bank_mask:0x3
	v_mov_b32_dpp v25, v213 row_shl:8 row_mask:0xf bank_mask:0x3
	v_mov_b32_dpp v26, v214 row_shl:8 row_mask:0xf bank_mask:0x3
	v_mov_b32_dpp v27, v215 row_shl:8 row_mask:0xf bank_mask:0x3
	v_mov_b32_e32 v212, v20
	v_mov_b32_e32 v213, v21
	v_mov_b32_e32 v214, v22
	v_mov_b32_e32 v215, v23
	s_nop 0
	v_mov_b32_dpp v20, v12 row_shr:8 row_mask:0xf bank_mask:0xc
	v_mov_b32_dpp v21, v13 row_shr:8 row_mask:0xf bank_mask:0xc
	v_mov_b32_dpp v22, v14 row_shr:8 row_mask:0xf bank_mask:0xc
	v_mov_b32_dpp v23, v15 row_shr:8 row_mask:0xf bank_mask:0xc
	v_mov_b32_dpp v12, v212 row_shl:8 row_mask:0xf bank_mask:0x3
	v_mov_b32_dpp v13, v213 row_shl:8 row_mask:0xf bank_mask:0x3
	v_mov_b32_dpp v14, v214 row_shl:8 row_mask:0xf bank_mask:0x3
	v_mov_b32_dpp v15, v215 row_shl:8 row_mask:0xf bank_mask:0x3
	v_mov_b32_e32 v212, v16
	v_mov_b32_e32 v213, v17
	v_mov_b32_e32 v214, v18
	v_mov_b32_e32 v215, v19
	s_nop 0
	v_mov_b32_dpp v16, v8 row_shr:8 row_mask:0xf bank_mask:0xc
	v_mov_b32_dpp v17, v9 row_shr:8 row_mask:0xf bank_mask:0xc
	v_mov_b32_dpp v18, v10 row_shr:8 row_mask:0xf bank_mask:0xc
	v_mov_b32_dpp v19, v11 row_shr:8 row_mask:0xf bank_mask:0xc
	v_mov_b32_dpp v8, v212 row_shl:8 row_mask:0xf bank_mask:0x3
	v_mov_b32_dpp v9, v213 row_shl:8 row_mask:0xf bank_mask:0x3
	v_mov_b32_dpp v10, v214 row_shl:8 row_mask:0xf bank_mask:0x3
	v_mov_b32_dpp v11, v215 row_shl:8 row_mask:0xf bank_mask:0x3
	v_mov_b32_e32 v212, v4
	v_mov_b32_e32 v213, v5
	v_mov_b32_e32 v214, v6
	v_mov_b32_e32 v215, v7
	s_nop 0
	v_mov_b32_dpp v4, v0 row_shr:8 row_mask:0xf bank_mask:0xc
	v_mov_b32_dpp v5, v1 row_shr:8 row_mask:0xf bank_mask:0xc
	v_mov_b32_dpp v6, v2 row_shr:8 row_mask:0xf bank_mask:0xc
	v_mov_b32_dpp v7, v3 row_shr:8 row_mask:0xf bank_mask:0xc
	v_mov_b32_dpp v0, v212 row_shl:8 row_mask:0xf bank_mask:0x3
	v_mov_b32_dpp v1, v213 row_shl:8 row_mask:0xf bank_mask:0x3
	v_mov_b32_dpp v2, v214 row_shl:8 row_mask:0xf bank_mask:0x3
	v_mov_b32_dpp v3, v215 row_shl:8 row_mask:0xf bank_mask:0x3
	v_pk_add_f32 v[28:29], v[28:29], v[180:181]
	v_pk_add_f32 v[30:31], v[30:31], v[182:183]
	v_pk_add_f32 v[24:25], v[24:25], v[184:185]
	v_pk_add_f32 v[26:27], v[26:27], v[186:187]
	v_pk_add_f32 v[20:21], v[20:21], v[188:189]
	v_pk_add_f32 v[22:23], v[22:23], v[190:191]
	v_pk_add_f32 v[12:13], v[12:13], v[192:193]
	v_pk_add_f32 v[14:15], v[14:15], v[194:195]
	v_pk_add_f32 v[16:17], v[16:17], v[196:197]
	v_pk_add_f32 v[18:19], v[18:19], v[198:199]
	v_pk_add_f32 v[8:9], v[8:9], v[200:201]
	v_pk_add_f32 v[10:11], v[10:11], v[202:203]
	v_pk_add_f32 v[4:5], v[4:5], v[204:205]
	v_pk_add_f32 v[6:7], v[6:7], v[206:207]
	v_pk_add_f32 v[0:1], v[0:1], v[208:209]
	v_pk_add_f32 v[2:3], v[2:3], v[210:211]
	global_store_dwordx4 v230, v[28:31], s[52:53]
	v_add_u32_e32 v144, v222, v233
	global_store_dwordx4 v144, v[24:27], s[52:53]
	global_store_dwordx4 v230, v[20:23], s[52:53] offset:512
	v_add_u32_e32 v144, v222, v233
	global_store_dwordx4 v144, v[12:15], s[52:53] offset:512
	global_store_dwordx4 v231, v[16:19], s[52:53]
	v_add_u32_e32 v144, v223, v233
	global_store_dwordx4 v144, v[8:11], s[52:53]
	global_store_dwordx4 v231, v[4:7], s[52:53] offset:512
	v_add_u32_e32 v144, v223, v233
	global_store_dwordx4 v144, v[0:3], s[52:53] offset:512
	s_cbranch_vccz .LBB0_849
	s_waitcnt vmcnt(0)
	s_cmpk_gt_u32 s4, 0xff
	s_cbranch_scc1 .LBB0_864
	s_barrier

.LBB0_1239:
	ds_read_b128 v[140:143], v149
	ds_read_b128 v[152:155], v149 offset:1024
	ds_read_b128 v[156:159], v149 offset:2048
	ds_read_b128 v[160:163], v149 offset:3072
	s_add_u32 s40, s38, 0xfffc0080
	s_addc_u32 s41, s39, -1
	s_cmp_eq_u32 s76, 12
	s_cselect_b32 s43, s29, s41
	s_cselect_b32 s42, s72, s40
	s_cselect_b32 s41, s27, s75
	s_cselect_b32 s40, s73, s74
	v_lshl_add_u64 v[144:145], s[38:39], 0, v[132:133]
	s_add_i32 m0, s8, 0xc000
	ds_read_b128 v[164:167], v150
	ds_read_b128 v[168:171], v150 offset:1024
	ds_read_b128 v[172:175], v150 offset:2048
	ds_read_b128 v[176:179], v150 offset:3072
	ds_read_b128 v[180:183], v150 offset:4096
	ds_read_b128 v[184:187], v150 offset:5120
	ds_read_b128 v[188:191], v150 offset:6144
	ds_read_b128 v[192:195], v150 offset:7168
	global_load_lds_dwordx4 v[144:145], off
	v_lshl_add_u64 v[144:145], s[38:39], 0, v[134:135]
	s_add_i32 m0, s8, 0xe000
	s_nop 0
	global_load_lds_dwordx4 v[144:145], off
	ds_read_b128 v[196:199], v151
	ds_read_b128 v[200:203], v151 offset:1024
	ds_read_b128 v[204:207], v151 offset:2048
	ds_read_b128 v[208:211], v151 offset:3072
	s_waitcnt lgkmcnt(0)
	s_barrier
	s_setprio 1
	v_mfma_f32_16x16x32_bf16 v[124:127], v[140:143], v[164:167], v[124:127]
	v_mfma_f32_16x16x32_bf16 v[120:123], v[156:159], v[164:167], v[120:123]
	v_mfma_f32_16x16x32_bf16 v[112:115], v[140:143], v[172:175], v[112:115]
	v_mfma_f32_16x16x32_bf16 v[104:107], v[156:159], v[172:175], v[104:107]
	v_mfma_f32_16x16x32_bf16 v[92:95], v[140:143], v[180:183], v[92:95]
	v_mfma_f32_16x16x32_bf16 v[88:91], v[156:159], v[180:183], v[88:91]
	v_mfma_f32_16x16x32_bf16 v[80:83], v[140:143], v[188:191], v[80:83]
	v_mfma_f32_16x16x32_bf16 v[72:75], v[156:159], v[188:191], v[72:75]
	v_mfma_f32_16x16x32_bf16 v[124:127], v[152:155], v[168:171], v[124:127]
	v_mfma_f32_16x16x32_bf16 v[120:123], v[160:163], v[168:171], v[120:123]
	v_mfma_f32_16x16x32_bf16 v[112:115], v[152:155], v[176:179], v[112:115]
	v_mfma_f32_16x16x32_bf16 v[104:107], v[160:163], v[176:179], v[104:107]
	v_mfma_f32_16x16x32_bf16 v[92:95], v[152:155], v[184:187], v[92:95]
	v_mfma_f32_16x16x32_bf16 v[88:91], v[160:163], v[184:187], v[88:91]
	v_mfma_f32_16x16x32_bf16 v[80:83], v[152:155], v[192:195], v[80:83]
	v_mfma_f32_16x16x32_bf16 v[72:75], v[160:163], v[192:195], v[72:75]
	v_mfma_f32_16x16x32_bf16 v[116:119], v[196:199], v[164:167], v[116:119]
	v_mfma_f32_16x16x32_bf16 v[108:111], v[204:207], v[164:167], v[108:111]
	v_mfma_f32_16x16x32_bf16 v[100:103], v[196:199], v[172:175], v[100:103]
	v_mfma_f32_16x16x32_bf16 v[96:99], v[204:207], v[172:175], v[96:99]
	v_mfma_f32_16x16x32_bf16 v[84:87], v[196:199], v[180:183], v[84:87]
	v_mfma_f32_16x16x32_bf16 v[76:79], v[204:207], v[180:183], v[76:79]
	v_mfma_f32_16x16x32_bf16 v[68:71], v[196:199], v[188:191], v[68:71]
	v_mfma_f32_16x16x32_bf16 v[64:67], v[204:207], v[188:191], v[64:67]
	v_mfma_f32_16x16x32_bf16 v[116:119], v[200:203], v[168:171], v[116:119]
	v_mfma_f32_16x16x32_bf16 v[108:111], v[208:211], v[168:171], v[108:111]
	v_mfma_f32_16x16x32_bf16 v[100:103], v[200:203], v[176:179], v[100:103]
	v_mfma_f32_16x16x32_bf16 v[96:99], v[208:211], v[176:179], v[96:99]
	v_mfma_f32_16x16x32_bf16 v[84:87], v[200:203], v[184:187], v[84:87]
	v_mfma_f32_16x16x32_bf16 v[76:79], v[208:211], v[184:187], v[76:79]
	v_mfma_f32_16x16x32_bf16 v[68:71], v[200:203], v[192:195], v[68:71]
	v_mfma_f32_16x16x32_bf16 v[64:67], v[208:211], v[192:195], v[64:67]
	s_setprio 0
	s_barrier
	s_nop 1
	ds_read_b128 v[164:167], v150 offset:16384
	ds_read_b128 v[168:171], v150 offset:17408
	ds_read_b128 v[172:175], v150 offset:18432
	ds_read_b128 v[176:179], v150 offset:19456
	ds_read_b128 v[180:183], v150 offset:20480
	ds_read_b128 v[184:187], v150 offset:21504
	ds_read_b128 v[188:191], v150 offset:22528
	ds_read_b128 v[192:195], v150 offset:23552
	s_add_i32 s77, s48, s7
	v_lshl_add_u64 v[144:145], s[40:41], 0, v[128:129]
	s_mov_b32 m0, s77
	s_nop 0
	global_load_lds_dwordx4 v[144:145], off
	v_lshl_add_u64 v[212:213], s[40:41], 0, v[130:131]
	s_add_i32 m0, s77, 0x2000
	s_nop 0
	global_load_lds_dwordx4 v[212:213], off
	s_mov_b32 m0, s8
	v_lshl_add_u64 v[214:215], s[42:43], 0, v[128:129]
	global_load_lds_dwordx4 v[214:215], off
	v_lshl_add_u64 v[216:217], s[42:43], 0, v[130:131]
	s_mov_b32 m0, s9
	s_nop 0
	global_load_lds_dwordx4 v[216:217], off
	s_add_u32 s78, s40, 0x40000
	s_addc_u32 s79, s41, 0
	s_add_i32 s77, s49, s7
	v_lshl_add_u64 v[254:255], s[78:79], 0, v[128:129]
	s_mov_b32 m0, s77
	s_nop 0
	global_load_lds_dwordx4 v[254:255], off
	v_lshl_add_u64 v[254:255], s[78:79], 0, v[130:131]
	s_add_i32 m0, s77, 0x2000
	s_nop 0
	global_load_lds_dwordx4 v[254:255], off
	s_waitcnt vmcnt(6)
	s_waitcnt lgkmcnt(0)
	s_barrier
	s_setprio 1
	v_mfma_f32_16x16x32_bf16 v[60:63], v[140:143], v[164:167], v[60:63]
	v_mfma_f32_16x16x32_bf16 v[56:59], v[156:159], v[164:167], v[56:59]
	v_mfma_f32_16x16x32_bf16 v[48:51], v[140:143], v[172:175], v[48:51]
	v_mfma_f32_16x16x32_bf16 v[40:43], v[156:159], v[172:175], v[40:43]
	v_mfma_f32_16x16x32_bf16 v[28:31], v[140:143], v[180:183], v[28:31]
	v_mfma_f32_16x16x32_bf16 v[24:27], v[156:159], v[180:183], v[24:27]
	v_mfma_f32_16x16x32_bf16 v[16:19], v[140:143], v[188:191], v[16:19]
	v_mfma_f32_16x16x32_bf16 v[8:11], v[156:159], v[188:191], v[8:11]
	v_mfma_f32_16x16x32_bf16 v[60:63], v[152:155], v[168:171], v[60:63]
	v_mfma_f32_16x16x32_bf16 v[56:59], v[160:163], v[168:171], v[56:59]
	v_mfma_f32_16x16x32_bf16 v[48:51], v[152:155], v[176:179], v[48:51]
	v_mfma_f32_16x16x32_bf16 v[40:43], v[160:163], v[176:179], v[40:43]
	v_mfma_f32_16x16x32_bf16 v[28:31], v[152:155], v[184:187], v[28:31]
	v_mfma_f32_16x16x32_bf16 v[24:27], v[160:163], v[184:187], v[24:27]
	v_mfma_f32_16x16x32_bf16 v[16:19], v[152:155], v[192:195], v[16:19]
	v_mfma_f32_16x16x32_bf16 v[8:11], v[160:163], v[192:195], v[8:11]
	v_mfma_f32_16x16x32_bf16 v[52:55], v[196:199], v[164:167], v[52:55]
	v_mfma_f32_16x16x32_bf16 v[44:47], v[204:207], v[164:167], v[44:47]
	v_mfma_f32_16x16x32_bf16 v[36:39], v[196:199], v[172:175], v[36:39]
	v_mfma_f32_16x16x32_bf16 v[32:35], v[204:207], v[172:175], v[32:35]
	v_mfma_f32_16x16x32_bf16 v[20:23], v[196:199], v[180:183], v[20:23]
	v_mfma_f32_16x16x32_bf16 v[12:15], v[204:207], v[180:183], v[12:15]
	v_mfma_f32_16x16x32_bf16 v[4:7], v[196:199], v[188:191], v[4:7]
	v_mfma_f32_16x16x32_bf16 v[0:3], v[204:207], v[188:191], v[0:3]
	v_mfma_f32_16x16x32_bf16 v[52:55], v[200:203], v[168:171], v[52:55]
	v_mfma_f32_16x16x32_bf16 v[44:47], v[208:211], v[168:171], v[44:47]
	v_mfma_f32_16x16x32_bf16 v[36:39], v[200:203], v[176:179], v[36:39]
	v_mfma_f32_16x16x32_bf16 v[32:35], v[208:211], v[176:179], v[32:35]
	v_mfma_f32_16x16x32_bf16 v[20:23], v[200:203], v[184:187], v[20:23]
	v_mfma_f32_16x16x32_bf16 v[12:15], v[208:211], v[184:187], v[12:15]
	v_mfma_f32_16x16x32_bf16 v[4:7], v[200:203], v[192:195], v[4:7]
	v_mfma_f32_16x16x32_bf16 v[0:3], v[208:211], v[192:195], v[0:3]
	s_setprio 0
	s_add_i32 s77, 0, 0x18000
	v_add_u32_e32 v160, s77, v147
	s_barrier
	ds_read_b128 v[140:143], v160
	ds_read_b128 v[152:155], v160 offset:1024
	ds_read_b128 v[156:159], v160 offset:2048
	ds_read_b128 v[160:163], v160 offset:3072
	s_add_u32 s42, s42, 0x40000
	s_addc_u32 s43, s43, 0
	s_mov_b32 m0, s37
	v_lshl_add_u64 v[196:197], s[42:43], 0, v[128:129]
	ds_read_b128 v[164:167], v150 offset:32768
	ds_read_b128 v[168:171], v150 offset:33792
	ds_read_b128 v[172:175], v150 offset:34816
	ds_read_b128 v[176:179], v150 offset:35840
	ds_read_b128 v[180:183], v150 offset:36864
	ds_read_b128 v[184:187], v150 offset:37888
	ds_read_b128 v[188:191], v150 offset:38912
	ds_read_b128 v[192:195], v150 offset:39936
	global_load_lds_dwordx4 v[196:197], off
	v_lshl_add_u64 v[196:197], s[42:43], 0, v[130:131]
	s_mov_b32 m0, s44
	s_nop 0
	global_load_lds_dwordx4 v[196:197], off
	s_add_i32 s42, 0, 0x1c000
	v_add_u32_e32 v208, s42, v147
	ds_read_b128 v[196:199], v208
	ds_read_b128 v[200:203], v208 offset:1024
	ds_read_b128 v[204:207], v208 offset:2048
	ds_read_b128 v[208:211], v208 offset:3072
	s_waitcnt lgkmcnt(0)
	s_barrier
	s_setprio 1
	v_mfma_f32_16x16x32_bf16 v[124:127], v[140:143], v[164:167], v[124:127]
	v_mfma_f32_16x16x32_bf16 v[120:123], v[156:159], v[164:167], v[120:123]
	v_mfma_f32_16x16x32_bf16 v[112:115], v[140:143], v[172:175], v[112:115]
	v_mfma_f32_16x16x32_bf16 v[104:107], v[156:159], v[172:175], v[104:107]
	v_mfma_f32_16x16x32_bf16 v[92:95], v[140:143], v[180:183], v[92:95]
	v_mfma_f32_16x16x32_bf16 v[88:91], v[156:159], v[180:183], v[88:91]
	v_mfma_f32_16x16x32_bf16 v[80:83], v[140:143], v[188:191], v[80:83]
	v_mfma_f32_16x16x32_bf16 v[72:75], v[156:159], v[188:191], v[72:75]
	v_mfma_f32_16x16x32_bf16 v[124:127], v[152:155], v[168:171], v[124:127]
	v_mfma_f32_16x16x32_bf16 v[120:123], v[160:163], v[168:171], v[120:123]
	v_mfma_f32_16x16x32_bf16 v[112:115], v[152:155], v[176:179], v[112:115]
	v_mfma_f32_16x16x32_bf16 v[104:107], v[160:163], v[176:179], v[104:107]
	v_mfma_f32_16x16x32_bf16 v[92:95], v[152:155], v[184:187], v[92:95]
	v_mfma_f32_16x16x32_bf16 v[88:91], v[160:163], v[184:187], v[88:91]
	v_mfma_f32_16x16x32_bf16 v[80:83], v[152:155], v[192:195], v[80:83]
	v_mfma_f32_16x16x32_bf16 v[72:75], v[160:163], v[192:195], v[72:75]
	v_mfma_f32_16x16x32_bf16 v[116:119], v[196:199], v[164:167], v[116:119]
	v_mfma_f32_16x16x32_bf16 v[108:111], v[204:207], v[164:167], v[108:111]
	v_mfma_f32_16x16x32_bf16 v[100:103], v[196:199], v[172:175], v[100:103]
	v_mfma_f32_16x16x32_bf16 v[96:99], v[204:207], v[172:175], v[96:99]
	v_mfma_f32_16x16x32_bf16 v[84:87], v[196:199], v[180:183], v[84:87]
	v_mfma_f32_16x16x32_bf16 v[76:79], v[204:207], v[180:183], v[76:79]
	v_mfma_f32_16x16x32_bf16 v[68:71], v[196:199], v[188:191], v[68:71]
	v_mfma_f32_16x16x32_bf16 v[64:67], v[204:207], v[188:191], v[64:67]
	v_mfma_f32_16x16x32_bf16 v[116:119], v[200:203], v[168:171], v[116:119]
	v_mfma_f32_16x16x32_bf16 v[108:111], v[208:211], v[168:171], v[108:111]
	v_mfma_f32_16x16x32_bf16 v[100:103], v[200:203], v[176:179], v[100:103]
	v_mfma_f32_16x16x32_bf16 v[96:99], v[208:211], v[176:179], v[96:99]
	v_mfma_f32_16x16x32_bf16 v[84:87], v[200:203], v[184:187], v[84:87]
	v_mfma_f32_16x16x32_bf16 v[76:79], v[208:211], v[184:187], v[76:79]
	v_mfma_f32_16x16x32_bf16 v[68:71], v[200:203], v[192:195], v[68:71]
	v_mfma_f32_16x16x32_bf16 v[64:67], v[208:211], v[192:195], v[64:67]
	s_setprio 0
	s_barrier
	s_nop 1
	ds_read_b128 v[164:167], v150 offset:49152
	ds_read_b128 v[168:171], v150 offset:50176
	ds_read_b128 v[172:175], v150 offset:51200
	ds_read_b128 v[176:179], v150 offset:52224
	ds_read_b128 v[180:183], v150 offset:53248
	ds_read_b128 v[184:187], v150 offset:54272
	ds_read_b128 v[188:191], v150 offset:55296
	ds_read_b128 v[192:195], v150 offset:56320
	s_add_i32 s43, s77, s7
	v_lshl_add_u64 v[254:255], v[144:145], 0, s[12:13]
	s_mov_b32 m0, s43
	s_nop 0
	global_load_lds_dwordx4 v[254:255], off
	v_lshl_add_u64 v[254:255], v[212:213], 0, s[12:13]
	s_add_i32 m0, s43, 0x2000
	s_nop 0
	global_load_lds_dwordx4 v[254:255], off
	s_mov_b32 m0, s46
	v_lshl_add_u64 v[254:255], v[214:215], 0, s[12:13]
	global_load_lds_dwordx4 v[254:255], off
	v_lshl_add_u64 v[144:145], v[216:217], 0, s[12:13]
	s_mov_b32 m0, s47
	s_nop 0
	global_load_lds_dwordx4 v[144:145], off
	s_add_u32 s40, s40, 0x40080
	s_addc_u32 s41, s41, 0
	s_add_i32 s42, s42, s7
	v_lshl_add_u64 v[254:255], s[40:41], 0, v[128:129]
	s_mov_b32 m0, s42
	s_nop 0
	global_load_lds_dwordx4 v[254:255], off
	v_lshl_add_u64 v[254:255], s[40:41], 0, v[130:131]
	s_add_i32 m0, s42, 0x2000
	s_nop 0
	global_load_lds_dwordx4 v[254:255], off
	s_waitcnt vmcnt(6)
	s_waitcnt lgkmcnt(0)
	s_barrier
	s_setprio 1
	v_mfma_f32_16x16x32_bf16 v[60:63], v[140:143], v[164:167], v[60:63]
	v_mfma_f32_16x16x32_bf16 v[56:59], v[156:159], v[164:167], v[56:59]
	v_mfma_f32_16x16x32_bf16 v[48:51], v[140:143], v[172:175], v[48:51]
	v_mfma_f32_16x16x32_bf16 v[40:43], v[156:159], v[172:175], v[40:43]
	v_mfma_f32_16x16x32_bf16 v[28:31], v[140:143], v[180:183], v[28:31]
	v_mfma_f32_16x16x32_bf16 v[24:27], v[156:159], v[180:183], v[24:27]
	v_mfma_f32_16x16x32_bf16 v[16:19], v[140:143], v[188:191], v[16:19]
	v_mfma_f32_16x16x32_bf16 v[8:11], v[156:159], v[188:191], v[8:11]
	v_mfma_f32_16x16x32_bf16 v[60:63], v[152:155], v[168:171], v[60:63]
	v_mfma_f32_16x16x32_bf16 v[56:59], v[160:163], v[168:171], v[56:59]
	v_mfma_f32_16x16x32_bf16 v[48:51], v[152:155], v[176:179], v[48:51]
	v_mfma_f32_16x16x32_bf16 v[40:43], v[160:163], v[176:179], v[40:43]
	v_mfma_f32_16x16x32_bf16 v[28:31], v[152:155], v[184:187], v[28:31]
	v_mfma_f32_16x16x32_bf16 v[24:27], v[160:163], v[184:187], v[24:27]
	v_mfma_f32_16x16x32_bf16 v[16:19], v[152:155], v[192:195], v[16:19]
	v_mfma_f32_16x16x32_bf16 v[8:11], v[160:163], v[192:195], v[8:11]
	v_mfma_f32_16x16x32_bf16 v[52:55], v[196:199], v[164:167], v[52:55]
	v_mfma_f32_16x16x32_bf16 v[44:47], v[204:207], v[164:167], v[44:47]
	v_mfma_f32_16x16x32_bf16 v[36:39], v[196:199], v[172:175], v[36:39]
	v_mfma_f32_16x16x32_bf16 v[32:35], v[204:207], v[172:175], v[32:35]
	v_mfma_f32_16x16x32_bf16 v[20:23], v[196:199], v[180:183], v[20:23]
	v_mfma_f32_16x16x32_bf16 v[12:15], v[204:207], v[180:183], v[12:15]
	v_mfma_f32_16x16x32_bf16 v[4:7], v[196:199], v[188:191], v[4:7]
	v_mfma_f32_16x16x32_bf16 v[0:3], v[204:207], v[188:191], v[0:3]
	v_mfma_f32_16x16x32_bf16 v[52:55], v[200:203], v[168:171], v[52:55]
	v_mfma_f32_16x16x32_bf16 v[44:47], v[208:211], v[168:171], v[44:47]
	v_mfma_f32_16x16x32_bf16 v[36:39], v[200:203], v[176:179], v[36:39]
	v_mfma_f32_16x16x32_bf16 v[32:35], v[208:211], v[176:179], v[32:35]
	v_mfma_f32_16x16x32_bf16 v[20:23], v[200:203], v[184:187], v[20:23]
	v_mfma_f32_16x16x32_bf16 v[12:15], v[208:211], v[184:187], v[12:15]
	v_mfma_f32_16x16x32_bf16 v[4:7], v[200:203], v[192:195], v[4:7]
	v_mfma_f32_16x16x32_bf16 v[0:3], v[208:211], v[192:195], v[0:3]
	s_setprio 0
	s_add_i32 s76, s76, 2
	s_add_u32 s38, s38, 0x100
	s_addc_u32 s39, s39, 0
	s_add_u32 s74, s74, 0x100
	s_addc_u32 s75, s75, 0
	s_cmp_gt_u32 s76, 13
	s_barrier
	s_cbranch_scc0 .LBB0_1239
	v_lshl_or_b32 v144, s63, 8, v148
	v_lshl_add_u32 v145, s36, 8, v146
	v_lshlrev_b32_e32 v144, 2, v144
	v_lshl_add_u32 v145, v145, 12, v144
	v_add_u32_e32 v216, 0x10000, v145
	v_add_u32_e32 v217, 0x20000, v145
	v_add_u32_e32 v218, 0x30000, v145
	v_add_u32_e32 v220, 0x80000, v145
	v_add_u32_e32 v221, 0x90000, v145
	v_add_u32_e32 v222, 0xa0000, v145
	v_add_u32_e32 v223, 0xb0000, v145
	v_and_b32_e32 v235, 8, v146
	v_cmp_ne_u32_e32 vcc, 0, v235
	v_mov_b32_e32 v232, 0xffff8040
	s_nop 0
	v_cndmask_b32_e32 v232, 0, v232, vcc
	v_mov_b32_e32 v233, 64
	v_mov_b32_e32 v235, 0x8000
	v_cndmask_b32_e32 v233, v235, v233, vcc
	v_add_u32_e32 v224, v145, v232
	v_add_u32_e32 v225, v216, v232
	v_add_u32_e32 v226, v217, v232
	v_add_u32_e32 v227, v218, v232
	v_add_u32_e32 v228, v220, v232
	v_add_u32_e32 v229, v221, v232
	v_add_u32_e32 v230, v222, v232
	v_add_u32_e32 v231, v223, v232
	s_and_b64 vcc, exec, s[10:11]
	s_mov_b32 s63, s26
	s_mov_b32 s36, s28
	s_mov_b64 s[40:41], s[34:35]
	s_mov_b64 s[38:39], s[30:31]
	global_load_dwordx4 v[140:143], v224, s[52:53]
	v_add_u32_e32 v144, v145, v233
	global_load_dwordx4 v[152:155], v144, s[52:53]
	global_load_dwordx4 v[156:159], v224, s[52:53] offset:512
	v_add_u32_e32 v144, v145, v233
	global_load_dwordx4 v[160:163], v144, s[52:53] offset:512
	global_load_dwordx4 v[164:167], v225, s[52:53]
	v_add_u32_e32 v144, v216, v233
	global_load_dwordx4 v[168:171], v144, s[52:53]
	global_load_dwordx4 v[172:175], v225, s[52:53] offset:512
	v_add_u32_e32 v144, v216, v233
	global_load_dwordx4 v[176:179], v144, s[52:53] offset:512
	global_load_dwordx4 v[180:183], v226, s[52:53]
	v_add_u32_e32 v144, v217, v233
	global_load_dwordx4 v[184:187], v144, s[52:53]
	global_load_dwordx4 v[188:191], v226, s[52:53] offset:512
	v_add_u32_e32 v144, v217, v233
	global_load_dwordx4 v[192:195], v144, s[52:53] offset:512
	global_load_dwordx4 v[196:199], v227, s[52:53]
	v_add_u32_e32 v144, v218, v233
	global_load_dwordx4 v[200:203], v144, s[52:53]
	global_load_dwordx4 v[204:207], v227, s[52:53] offset:512
	v_add_u32_e32 v144, v218, v233
	global_load_dwordx4 v[208:211], v144, s[52:53] offset:512
	v_pk_add_f32 v[124:125], v[124:125], 0 op_sel_hi:[1,0]
	v_pk_add_f32 v[126:127], v[126:127], 0 op_sel_hi:[1,0]
	v_pk_add_f32 v[120:121], v[120:121], 0 op_sel_hi:[1,0]
	v_pk_add_f32 v[122:123], v[122:123], 0 op_sel_hi:[1,0]
	v_pk_add_f32 v[116:117], v[116:117], 0 op_sel_hi:[1,0]
	v_pk_add_f32 v[118:119], v[118:119], 0 op_sel_hi:[1,0]
	v_pk_add_f32 v[108:109], v[108:109], 0 op_sel_hi:[1,0]
	v_pk_add_f32 v[110:111], v[110:111], 0 op_sel_hi:[1,0]
	v_pk_add_f32 v[112:113], v[112:113], 0 op_sel_hi:[1,0]
	v_pk_add_f32 v[114:115], v[114:115], 0 op_sel_hi:[1,0]
	v_pk_add_f32 v[104:105], v[104:105], 0 op_sel_hi:[1,0]
	v_pk_add_f32 v[106:107], v[106:107], 0 op_sel_hi:[1,0]
	v_pk_add_f32 v[100:101], v[100:101], 0 op_sel_hi:[1,0]
	v_pk_add_f32 v[102:103], v[102:103], 0 op_sel_hi:[1,0]
	v_pk_add_f32 v[96:97], v[96:97], 0 op_sel_hi:[1,0]
	v_pk_add_f32 v[98:99], v[98:99], 0 op_sel_hi:[1,0]
	v_pk_add_f32 v[92:93], v[92:93], 0 op_sel_hi:[1,0]
	v_pk_add_f32 v[94:95], v[94:95], 0 op_sel_hi:[1,0]
	v_pk_add_f32 v[88:89], v[88:89], 0 op_sel_hi:[1,0]
	v_pk_add_f32 v[90:91], v[90:91], 0 op_sel_hi:[1,0]
	v_pk_add_f32 v[84:85], v[84:85], 0 op_sel_hi:[1,0]
	v_pk_add_f32 v[86:87], v[86:87], 0 op_sel_hi:[1,0]
	v_pk_add_f32 v[76:77], v[76:77], 0 op_sel_hi:[1,0]
	v_pk_add_f32 v[78:79], v[78:79], 0 op_sel_hi:[1,0]
	v_pk_add_f32 v[80:81], v[80:81], 0 op_sel_hi:[1,0]
	v_pk_add_f32 v[82:83], v[82:83], 0 op_sel_hi:[1,0]
	v_pk_add_f32 v[72:73], v[72:73], 0 op_sel_hi:[1,0]
	v_pk_add_f32 v[74:75], v[74:75], 0 op_sel_hi:[1,0]
	v_pk_add_f32 v[68:69], v[68:69], 0 op_sel_hi:[1,0]
	v_pk_add_f32 v[70:71], v[70:71], 0 op_sel_hi:[1,0]
	v_pk_add_f32 v[64:65], v[64:65], 0 op_sel_hi:[1,0]
	v_pk_add_f32 v[66:67], v[66:67], 0 op_sel_hi:[1,0]
	v_pk_add_f32 v[60:61], v[60:61], 0 op_sel_hi:[1,0]
	v_pk_add_f32 v[62:63], v[62:63], 0 op_sel_hi:[1,0]
	v_pk_add_f32 v[56:57], v[56:57], 0 op_sel_hi:[1,0]
	v_pk_add_f32 v[58:59], v[58:59], 0 op_sel_hi:[1,0]
	v_pk_add_f32 v[52:53], v[52:53], 0 op_sel_hi:[1,0]
	v_pk_add_f32 v[54:55], v[54:55], 0 op_sel_hi:[1,0]
	v_pk_add_f32 v[44:45], v[44:45], 0 op_sel_hi:[1,0]
	v_pk_add_f32 v[46:47], v[46:47], 0 op_sel_hi:[1,0]
	v_pk_add_f32 v[48:49], v[48:49], 0 op_sel_hi:[1,0]
	v_pk_add_f32 v[50:51], v[50:51], 0 op_sel_hi:[1,0]
	v_pk_add_f32 v[40:41], v[40:41], 0 op_sel_hi:[1,0]
	v_pk_add_f32 v[42:43], v[42:43], 0 op_sel_hi:[1,0]
	v_pk_add_f32 v[36:37], v[36:37], 0 op_sel_hi:[1,0]
	v_pk_add_f32 v[38:39], v[38:39], 0 op_sel_hi:[1,0]
	v_pk_add_f32 v[32:33], v[32:33], 0 op_sel_hi:[1,0]
	v_pk_add_f32 v[34:35], v[34:35], 0 op_sel_hi:[1,0]
	v_pk_add_f32 v[28:29], v[28:29], 0 op_sel_hi:[1,0]
	v_pk_add_f32 v[30:31], v[30:31], 0 op_sel_hi:[1,0]
	v_pk_add_f32 v[24:25], v[24:25], 0 op_sel_hi:[1,0]
	v_pk_add_f32 v[26:27], v[26:27], 0 op_sel_hi:[1,0]
	v_pk_add_f32 v[20:21], v[20:21], 0 op_sel_hi:[1,0]
	v_pk_add_f32 v[22:23], v[22:23], 0 op_sel_hi:[1,0]
	v_pk_add_f32 v[12:13], v[12:13], 0 op_sel_hi:[1,0]
	v_pk_add_f32 v[14:15], v[14:15], 0 op_sel_hi:[1,0]
	v_pk_add_f32 v[16:17], v[16:17], 0 op_sel_hi:[1,0]
	v_pk_add_f32 v[18:19], v[18:19], 0 op_sel_hi:[1,0]
	v_pk_add_f32 v[8:9], v[8:9], 0 op_sel_hi:[1,0]
	v_pk_add_f32 v[10:11], v[10:11], 0 op_sel_hi:[1,0]
	v_pk_add_f32 v[4:5], v[4:5], 0 op_sel_hi:[1,0]
	v_pk_add_f32 v[6:7], v[6:7], 0 op_sel_hi:[1,0]
	v_pk_add_f32 v[0:1], v[0:1], 0 op_sel_hi:[1,0]
	v_pk_add_f32 v[2:3], v[2:3], 0 op_sel_hi:[1,0]
	s_waitcnt vmcnt(8)
	v_mov_b32_e32 v212, v124
	v_mov_b32_e32 v213, v125
	v_mov_b32_e32 v214, v126
	v_mov_b32_e32 v215, v127
	s_nop 0
	v_mov_b32_dpp v124, v120 row_shr:8 row_mask:0xf bank_mask:0xc
	v_mov_b32_dpp v125, v121 row_shr:8 row_mask:0xf bank_mask:0xc
	v_mov_b32_dpp v126, v122 row_shr:8 row_mask:0xf bank_mask:0xc
	v_mov_b32_dpp v127, v123 row_shr:8 row_mask:0xf bank_mask:0xc
	v_mov_b32_dpp v120, v212 row_shl:8 row_mask:0xf bank_mask:0x3
	v_mov_b32_dpp v121, v213 row_shl:8 row_mask:0xf bank_mask:0x3
	v_mov_b32_dpp v122, v214 row_shl:8 row_mask:0xf bank_mask:0x3
	v_mov_b32_dpp v123, v215 row_shl:8 row_mask:0xf bank_mask:0x3
	v_mov_b32_e32 v212, v116
	v_mov_b32_e32 v213, v117
	v_mov_b32_e32 v214, v118
	v_mov_b32_e32 v215, v119
	s_nop 0
	v_mov_b32_dpp v116, v108 row_shr:8 row_mask:0xf bank_mask:0xc
	v_mov_b32_dpp v117, v109 row_shr:8 row_mask:0xf bank_mask:0xc
	v_mov_b32_dpp v118, v110 row_shr:8 row_mask:0xf bank_mask:0xc
	v_mov_b32_dpp v119, v111 row_shr:8 row_mask:0xf bank_mask:0xc
	v_mov_b32_dpp v108, v212 row_shl:8 row_mask:0xf bank_mask:0x3
	v_mov_b32_dpp v109, v213 row_shl:8 row_mask:0xf bank_mask:0x3
	v_mov_b32_dpp v110, v214 row_shl:8 row_mask:0xf bank_mask:0x3
	v_mov_b32_dpp v111, v215 row_shl:8 row_mask:0xf bank_mask:0x3
	v_mov_b32_e32 v212, v112
	v_mov_b32_e32 v213, v113
	v_mov_b32_e32 v214, v114
	v_mov_b32_e32 v215, v115
	s_nop 0
	v_mov_b32_dpp v112, v104 row_shr:8 row_mask:0xf bank_mask:0xc
	v_mov_b32_dpp v113, v105 row_shr:8 row_mask:0xf bank_mask:0xc
	v_mov_b32_dpp v114, v106 row_shr:8 row_mask:0xf bank_mask:0xc
	v_mov_b32_dpp v115, v107 row_shr:8 row_mask:0xf bank_mask:0xc
	v_mov_b32_dpp v104, v212 row_shl:8 row_mask:0xf bank_mask:0x3
	v_mov_b32_dpp v105, v213 row_shl:8 row_mask:0xf bank_mask:0x3
	v_mov_b32_dpp v106, v214 row_shl:8 row_mask:0xf bank_mask:0x3
	v_mov_b32_dpp v107, v215 row_shl:8 row_mask:0xf bank_mask:0x3
	v_mov_b32_e32 v212, v100
	v_mov_b32_e32 v213, v101
	v_mov_b32_e32 v214, v102
	v_mov_b32_e32 v215, v103
	s_nop 0
	v_mov_b32_dpp v100, v96 row_shr:8 row_mask:0xf bank_mask:0xc
	v_mov_b32_dpp v101, v97 row_shr:8 row_mask:0xf bank_mask:0xc
	v_mov_b32_dpp v102, v98 row_shr:8 row_mask:0xf bank_mask:0xc
	v_mov_b32_dpp v103, v99 row_shr:8 row_mask:0xf bank_mask:0xc
	v_mov_b32_dpp v96, v212 row_shl:8 row_mask:0xf bank_mask:0x3
	v_mov_b32_dpp v97, v213 row_shl:8 row_mask:0xf bank_mask:0x3
	v_mov_b32_dpp v98, v214 row_shl:8 row_mask:0xf bank_mask:0x3
	v_mov_b32_dpp v99, v215 row_shl:8 row_mask:0xf bank_mask:0x3
	v_pk_add_f32 v[124:125], v[124:125], v[140:141]
	v_pk_add_f32 v[126:127], v[126:127], v[142:143]
	v_pk_add_f32 v[120:121], v[120:121], v[152:153]
	v_pk_add_f32 v[122:123], v[122:123], v[154:155]
	v_pk_add_f32 v[116:117], v[116:117], v[156:157]
	v_pk_add_f32 v[118:119], v[118:119], v[158:159]
	v_pk_add_f32 v[108:109], v[108:109], v[160:161]
	v_pk_add_f32 v[110:111], v[110:111], v[162:163]
	v_pk_add_f32 v[112:113], v[112:113], v[164:165]
	v_pk_add_f32 v[114:115], v[114:115], v[166:167]
	v_pk_add_f32 v[104:105], v[104:105], v[168:169]
	v_pk_add_f32 v[106:107], v[106:107], v[170:171]
	v_pk_add_f32 v[100:101], v[100:101], v[172:173]
	v_pk_add_f32 v[102:103], v[102:103], v[174:175]
	v_pk_add_f32 v[96:97], v[96:97], v[176:177]
	v_pk_add_f32 v[98:99], v[98:99], v[178:179]
	global_store_dwordx4 v224, v[124:127], s[52:53]
	v_add_u32_e32 v144, v145, v233
	global_store_dwordx4 v144, v[120:123], s[52:53]
	global_store_dwordx4 v224, v[116:119], s[52:53] offset:512
	v_add_u32_e32 v144, v145, v233
	global_store_dwordx4 v144, v[108:111], s[52:53] offset:512
	global_store_dwordx4 v225, v[112:115], s[52:53]
	v_add_u32_e32 v144, v216, v233
	global_store_dwordx4 v144, v[104:107], s[52:53]
	global_store_dwordx4 v225, v[100:103], s[52:53] offset:512
	v_add_u32_e32 v144, v216, v233
	global_store_dwordx4 v144, v[96:99], s[52:53] offset:512
	global_load_dwordx4 v[140:143], v228, s[52:53]
	v_add_u32_e32 v144, v220, v233
	global_load_dwordx4 v[152:155], v144, s[52:53]
	global_load_dwordx4 v[156:159], v228, s[52:53] offset:512
	v_add_u32_e32 v144, v220, v233
	global_load_dwordx4 v[160:163], v144, s[52:53] offset:512
	global_load_dwordx4 v[164:167], v229, s[52:53]
	v_add_u32_e32 v144, v221, v233
	global_load_dwordx4 v[168:171], v144, s[52:53]
	global_load_dwordx4 v[172:175], v229, s[52:53] offset:512
	v_add_u32_e32 v144, v221, v233
	global_load_dwordx4 v[176:179], v144, s[52:53] offset:512
	s_waitcnt vmcnt(16)
	v_mov_b32_e32 v212, v92
	v_mov_b32_e32 v213, v93
	v_mov_b32_e32 v214, v94
	v_mov_b32_e32 v215, v95
	s_nop 0
	v_mov_b32_dpp v92, v88 row_shr:8 row_mask:0xf bank_mask:0xc
	v_mov_b32_dpp v93, v89 row_shr:8 row_mask:0xf bank_mask:0xc
	v_mov_b32_dpp v94, v90 row_shr:8 row_mask:0xf bank_mask:0xc
	v_mov_b32_dpp v95, v91 row_shr:8 row_mask:0xf bank_mask:0xc
	v_mov_b32_dpp v88, v212 row_shl:8 row_mask:0xf bank_mask:0x3
	v_mov_b32_dpp v89, v213 row_shl:8 row_mask:0xf bank_mask:0x3
	v_mov_b32_dpp v90, v214 row_shl:8 row_mask:0xf bank_mask:0x3
	v_mov_b32_dpp v91, v215 row_shl:8 row_mask:0xf bank_mask:0x3
	v_mov_b32_e32 v212, v84
	v_mov_b32_e32 v213, v85
	v_mov_b32_e32 v214, v86
	v_mov_b32_e32 v215, v87
	s_nop 0
	v_mov_b32_dpp v84, v76 row_shr:8 row_mask:0xf bank_mask:0xc
	v_mov_b32_dpp v85, v77 row_shr:8 row_mask:0xf bank_mask:0xc
	v_mov_b32_dpp v86, v78 row_shr:8 row_mask:0xf bank_mask:0xc
	v_mov_b32_dpp v87, v79 row_shr:8 row_mask:0xf bank_mask:0xc
	v_mov_b32_dpp v76, v212 row_shl:8 row_mask:0xf bank_mask:0x3
	v_mov_b32_dpp v77, v213 row_shl:8 row_mask:0xf bank_mask:0x3
	v_mov_b32_dpp v78, v214 row_shl:8 row_mask:0xf bank_mask:0x3
	v_mov_b32_dpp v79, v215 row_shl:8 row_mask:0xf bank_mask:0x3
	v_mov_b32_e32 v212, v80
	v_mov_b32_e32 v213, v81
	v_mov_b32_e32 v214, v82
	v_mov_b32_e32 v215, v83
	s_nop 0
	v_mov_b32_dpp v80, v72 row_shr:8 row_mask:0xf bank_mask:0xc
	v_mov_b32_dpp v81, v73 row_shr:8 row_mask:0xf bank_mask:0xc
	v_mov_b32_dpp v82, v74 row_shr:8 row_mask:0xf bank_mask:0xc
	v_mov_b32_dpp v83, v75 row_shr:8 row_mask:0xf bank_mask:0xc
	v_mov_b32_dpp v72, v212 row_shl:8 row_mask:0xf bank_mask:0x3
	v_mov_b32_dpp v73, v213 row_shl:8 row_mask:0xf bank_mask:0x3
	v_mov_b32_dpp v74, v214 row_shl:8 row_mask:0xf bank_mask:0x3
	v_mov_b32_dpp v75, v215 row_shl:8 row_mask:0xf bank_mask:0x3
	v_mov_b32_e32 v212, v68
	v_mov_b32_e32 v213, v69
	v_mov_b32_e32 v214, v70
	v_mov_b32_e32 v215, v71
	s_nop 0
	v_mov_b32_dpp v68, v64 row_shr:8 row_mask:0xf bank_mask:0xc
	v_mov_b32_dpp v69, v65 row_shr:8 row_mask:0xf bank_mask:0xc
	v_mov_b32_dpp v70, v66 row_shr:8 row_mask:0xf bank_mask:0xc
	v_mov_b32_dpp v71, v67 row_shr:8 row_mask:0xf bank_mask:0xc
	v_mov_b32_dpp v64, v212 row_shl:8 row_mask:0xf bank_mask:0x3
	v_mov_b32_dpp v65, v213 row_shl:8 row_mask:0xf bank_mask:0x3
	v_mov_b32_dpp v66, v214 row_shl:8 row_mask:0xf bank_mask:0x3
	v_mov_b32_dpp v67, v215 row_shl:8 row_mask:0xf bank_mask:0x3
	v_pk_add_f32 v[92:93], v[92:93], v[180:181]
	v_pk_add_f32 v[94:95], v[94:95], v[182:183]
	v_pk_add_f32 v[88:89], v[88:89], v[184:185]
	v_pk_add_f32 v[90:91], v[90:91], v[186:187]
	v_pk_add_f32 v[84:85], v[84:85], v[188:189]
	v_pk_add_f32 v[86:87], v[86:87], v[190:191]
	v_pk_add_f32 v[76:77], v[76:77], v[192:193]
	v_pk_add_f32 v[78:79], v[78:79], v[194:195]
	v_pk_add_f32 v[80:81], v[80:81], v[196:197]
	v_pk_add_f32 v[82:83], v[82:83], v[198:199]
	v_pk_add_f32 v[72:73], v[72:73], v[200:201]
	v_pk_add_f32 v[74:75], v[74:75], v[202:203]
	v_pk_add_f32 v[68:69], v[68:69], v[204:205]
	v_pk_add_f32 v[70:71], v[70:71], v[206:207]
	v_pk_add_f32 v[64:65], v[64:65], v[208:209]
	v_pk_add_f32 v[66:67], v[66:67], v[210:211]
	global_store_dwordx4 v226, v[92:95], s[52:53]
	v_add_u32_e32 v144, v217, v233
	global_store_dwordx4 v144, v[88:91], s[52:53]
	global_store_dwordx4 v226, v[84:87], s[52:53] offset:512
	v_add_u32_e32 v144, v217, v233
	global_store_dwordx4 v144, v[76:79], s[52:53] offset:512
	global_store_dwordx4 v227, v[80:83], s[52:53]
	v_add_u32_e32 v144, v218, v233
	global_store_dwordx4 v144, v[72:75], s[52:53]
	global_store_dwordx4 v227, v[68:71], s[52:53] offset:512
	v_add_u32_e32 v144, v218, v233
	global_store_dwordx4 v144, v[64:67], s[52:53] offset:512
	global_load_dwordx4 v[180:183], v230, s[52:53]
	v_add_u32_e32 v144, v222, v233
	global_load_dwordx4 v[184:187], v144, s[52:53]
	global_load_dwordx4 v[188:191], v230, s[52:53] offset:512
	v_add_u32_e32 v144, v222, v233
	global_load_dwordx4 v[192:195], v144, s[52:53] offset:512
	global_load_dwordx4 v[196:199], v231, s[52:53]
	v_add_u32_e32 v144, v223, v233
	global_load_dwordx4 v[200:203], v144, s[52:53]
	global_load_dwordx4 v[204:207], v231, s[52:53] offset:512
	v_add_u32_e32 v144, v223, v233
	global_load_dwordx4 v[208:211], v144, s[52:53] offset:512
	s_waitcnt vmcnt(16)
	v_mov_b32_e32 v212, v60
	v_mov_b32_e32 v213, v61
	v_mov_b32_e32 v214, v62
	v_mov_b32_e32 v215, v63
	s_nop 0
	v_mov_b32_dpp v60, v56 row_shr:8 row_mask:0xf bank_mask:0xc
	v_mov_b32_dpp v61, v57 row_shr:8 row_mask:0xf bank_mask:0xc
	v_mov_b32_dpp v62, v58 row_shr:8 row_mask:0xf bank_mask:0xc
	v_mov_b32_dpp v63, v59 row_shr:8 row_mask:0xf bank_mask:0xc
	v_mov_b32_dpp v56, v212 row_shl:8 row_mask:0xf bank_mask:0x3
	v_mov_b32_dpp v57, v213 row_shl:8 row_mask:0xf bank_mask:0x3
	v_mov_b32_dpp v58, v214 row_shl:8 row_mask:0xf bank_mask:0x3
	v_mov_b32_dpp v59, v215 row_shl:8 row_mask:0xf bank_mask:0x3
	v_mov_b32_e32 v212, v52
	v_mov_b32_e32 v213, v53
	v_mov_b32_e32 v214, v54
	v_mov_b32_e32 v215, v55
	s_nop 0
	v_mov_b32_dpp v52, v44 row_shr:8 row_mask:0xf bank_mask:0xc
	v_mov_b32_dpp v53, v45 row_shr:8 row_mask:0xf bank_mask:0xc
	v_mov_b32_dpp v54, v46 row_shr:8 row_mask:0xf bank_mask:0xc
	v_mov_b32_dpp v55, v47 row_shr:8 row_mask:0xf bank_mask:0xc
	v_mov_b32_dpp v44, v212 row_shl:8 row_mask:0xf bank_mask:0x3
	v_mov_b32_dpp v45, v213 row_shl:8 row_mask:0xf bank_mask:0x3
	v_mov_b32_dpp v46, v214 row_shl:8 row_mask:0xf bank_mask:0x3
	v_mov_b32_dpp v47, v215 row_shl:8 row_mask:0xf bank_mask:0x3
	v_mov_b32_e32 v212, v48
	v_mov_b32_e32 v213, v49
	v_mov_b32_e32 v214, v50
	v_mov_b32_e32 v215, v51
	s_nop 0
	v_mov_b32_dpp v48, v40 row_shr:8 row_mask:0xf bank_mask:0xc
	v_mov_b32_dpp v49, v41 row_shr:8 row_mask:0xf bank_mask:0xc
	v_mov_b32_dpp v50, v42 row_shr:8 row_mask:0xf bank_mask:0xc
	v_mov_b32_dpp v51, v43 row_shr:8 row_mask:0xf bank_mask:0xc
	v_mov_b32_dpp v40, v212 row_shl:8 row_mask:0xf bank_mask:0x3
	v_mov_b32_dpp v41, v213 row_shl:8 row_mask:0xf bank_mask:0x3
	v_mov_b32_dpp v42, v214 row_shl:8 row_mask:0xf bank_mask:0x3
	v_mov_b32_dpp v43, v215 row_shl:8 row_mask:0xf bank_mask:0x3
	v_mov_b32_e32 v212, v36
	v_mov_b32_e32 v213, v37
	v_mov_b32_e32 v214, v38
	v_mov_b32_e32 v215, v39
	s_nop 0
	v_mov_b32_dpp v36, v32 row_shr:8 row_mask:0xf bank_mask:0xc
	v_mov_b32_dpp v37, v33 row_shr:8 row_mask:0xf bank_mask:0xc
	v_mov_b32_dpp v38, v34 row_shr:8 row_mask:0xf bank_mask:0xc
	v_mov_b32_dpp v39, v35 row_shr:8 row_mask:0xf bank_mask:0xc
	v_mov_b32_dpp v32, v212 row_shl:8 row_mask:0xf bank_mask:0x3
	v_mov_b32_dpp v33, v213 row_shl:8 row_mask:0xf bank_mask:0x3
	v_mov_b32_dpp v34, v214 row_shl:8 row_mask:0xf bank_mask:0x3
	v_mov_b32_dpp v35, v215 row_shl:8 row_mask:0xf bank_mask:0x3
	v_pk_add_f32 v[60:61], v[60:61], v[140:141]
	v_pk_add_f32 v[62:63], v[62:63], v[142:143]
	v_pk_add_f32 v[56:57], v[56:57], v[152:153]
	v_pk_add_f32 v[58:59], v[58:59], v[154:155]
	v_pk_add_f32 v[52:53], v[52:53], v[156:157]
	v_pk_add_f32 v[54:55], v[54:55], v[158:159]
	v_pk_add_f32 v[44:45], v[44:45], v[160:161]
	v_pk_add_f32 v[46:47], v[46:47], v[162:163]
	v_pk_add_f32 v[48:49], v[48:49], v[164:165]
	v_pk_add_f32 v[50:51], v[50:51], v[166:167]
	v_pk_add_f32 v[40:41], v[40:41], v[168:169]
	v_pk_add_f32 v[42:43], v[42:43], v[170:171]
	v_pk_add_f32 v[36:37], v[36:37], v[172:173]
	v_pk_add_f32 v[38:39], v[38:39], v[174:175]
	v_pk_add_f32 v[32:33], v[32:33], v[176:177]
	v_pk_add_f32 v[34:35], v[34:35], v[178:179]
	global_store_dwordx4 v228, v[60:63], s[52:53]
	v_add_u32_e32 v144, v220, v233
	global_store_dwordx4 v144, v[56:59], s[52:53]
	global_store_dwordx4 v228, v[52:55], s[52:53] offset:512
	v_add_u32_e32 v144, v220, v233
	global_store_dwordx4 v144, v[44:47], s[52:53] offset:512
	global_store_dwordx4 v229, v[48:51], s[52:53]
	v_add_u32_e32 v144, v221, v233
	global_store_dwordx4 v144, v[40:43], s[52:53]
	global_store_dwordx4 v229, v[36:39], s[52:53] offset:512
	v_add_u32_e32 v144, v221, v233
	global_store_dwordx4 v144, v[32:35], s[52:53] offset:512
	s_waitcnt vmcnt(8)
	v_mov_b32_e32 v212, v28
	v_mov_b32_e32 v213, v29
	v_mov_b32_e32 v214, v30
	v_mov_b32_e32 v215, v31
	s_nop 0
	v_mov_b32_dpp v28, v24 row_shr:8 row_mask:0xf bank_mask:0xc
	v_mov_b32_dpp v29, v25 row_shr:8 row_mask:0xf bank_mask:0xc
	v_mov_b32_dpp v30, v26 row_shr:8 row_mask:0xf bank_mask:0xc
	v_mov_b32_dpp v31, v27 row_shr:8 row_mask:0xf bank_mask:0xc
	v_mov_b32_dpp v24, v212 row_shl:8 row_mask:0xf bank_mask:0x3
	v_mov_b32_dpp v25, v213 row_shl:8 row_mask:0xf bank_mask:0x3
	v_mov_b32_dpp v26, v214 row_shl:8 row_mask:0xf bank_mask:0x3
	v_mov_b32_dpp v27, v215 row_shl:8 row_mask:0xf bank_mask:0x3
	v_mov_b32_e32 v212, v20
	v_mov_b32_e32 v213, v21
	v_mov_b32_e32 v214, v22
	v_mov_b32_e32 v215, v23
	s_nop 0
	v_mov_b32_dpp v20, v12 row_shr:8 row_mask:0xf bank_mask:0xc
	v_mov_b32_dpp v21, v13 row_shr:8 row_mask:0xf bank_mask:0xc
	v_mov_b32_dpp v22, v14 row_shr:8 row_mask:0xf bank_mask:0xc
	v_mov_b32_dpp v23, v15 row_shr:8 row_mask:0xf bank_mask:0xc
	v_mov_b32_dpp v12, v212 row_shl:8 row_mask:0xf bank_mask:0x3
	v_mov_b32_dpp v13, v213 row_shl:8 row_mask:0xf bank_mask:0x3
	v_mov_b32_dpp v14, v214 row_shl:8 row_mask:0xf bank_mask:0x3
	v_mov_b32_dpp v15, v215 row_shl:8 row_mask:0xf bank_mask:0x3
	v_mov_b32_e32 v212, v16
	v_mov_b32_e32 v213, v17
	v_mov_b32_e32 v214, v18
	v_mov_b32_e32 v215, v19
	s_nop 0
	v_mov_b32_dpp v16, v8 row_shr:8 row_mask:0xf bank_mask:0xc
	v_mov_b32_dpp v17, v9 row_shr:8 row_mask:0xf bank_mask:0xc
	v_mov_b32_dpp v18, v10 row_shr:8 row_mask:0xf bank_mask:0xc
	v_mov_b32_dpp v19, v11 row_shr:8 row_mask:0xf bank_mask:0xc
	v_mov_b32_dpp v8, v212 row_shl:8 row_mask:0xf bank_mask:0x3
	v_mov_b32_dpp v9, v213 row_shl:8 row_mask:0xf bank_mask:0x3
	v_mov_b32_dpp v10, v214 row_shl:8 row_mask:0xf bank_mask:0x3
	v_mov_b32_dpp v11, v215 row_shl:8 row_mask:0xf bank_mask:0x3
	v_mov_b32_e32 v212, v4
	v_mov_b32_e32 v213, v5
	v_mov_b32_e32 v214, v6
	v_mov_b32_e32 v215, v7
	s_nop 0
	v_mov_b32_dpp v4, v0 row_shr:8 row_mask:0xf bank_mask:0xc
	v_mov_b32_dpp v5, v1 row_shr:8 row_mask:0xf bank_mask:0xc
	v_mov_b32_dpp v6, v2 row_shr:8 row_mask:0xf bank_mask:0xc
	v_mov_b32_dpp v7, v3 row_shr:8 row_mask:0xf bank_mask:0xc
	v_mov_b32_dpp v0, v212 row_shl:8 row_mask:0xf bank_mask:0x3
	v_mov_b32_dpp v1, v213 row_shl:8 row_mask:0xf bank_mask:0x3
	v_mov_b32_dpp v2, v214 row_shl:8 row_mask:0xf bank_mask:0x3
	v_mov_b32_dpp v3, v215 row_shl:8 row_mask:0xf bank_mask:0x3
	v_pk_add_f32 v[28:29], v[28:29], v[180:181]
	v_pk_add_f32 v[30:31], v[30:31], v[182:183]
	v_pk_add_f32 v[24:25], v[24:25], v[184:185]
	v_pk_add_f32 v[26:27], v[26:27], v[186:187]
	v_pk_add_f32 v[20:21], v[20:21], v[188:189]
	v_pk_add_f32 v[22:23], v[22:23], v[190:191]
	v_pk_add_f32 v[12:13], v[12:13], v[192:193]
	v_pk_add_f32 v[14:15], v[14:15], v[194:195]
	v_pk_add_f32 v[16:17], v[16:17], v[196:197]
	v_pk_add_f32 v[18:19], v[18:19], v[198:199]
	v_pk_add_f32 v[8:9], v[8:9], v[200:201]
	v_pk_add_f32 v[10:11], v[10:11], v[202:203]
	v_pk_add_f32 v[4:5], v[4:5], v[204:205]
	v_pk_add_f32 v[6:7], v[6:7], v[206:207]
	v_pk_add_f32 v[0:1], v[0:1], v[208:209]
	v_pk_add_f32 v[2:3], v[2:3], v[210:211]
	global_store_dwordx4 v230, v[28:31], s[52:53]
	v_add_u32_e32 v144, v222, v233
	global_store_dwordx4 v144, v[24:27], s[52:53]
	global_store_dwordx4 v230, v[20:23], s[52:53] offset:512
	v_add_u32_e32 v144, v222, v233
	global_store_dwordx4 v144, v[12:15], s[52:53] offset:512
	global_store_dwordx4 v231, v[16:19], s[52:53]
	v_add_u32_e32 v144, v223, v233
	global_store_dwordx4 v144, v[8:11], s[52:53]
	global_store_dwordx4 v231, v[4:7], s[52:53] offset:512
	v_add_u32_e32 v144, v223, v233
	global_store_dwordx4 v144, v[0:3], s[52:53] offset:512
	s_cbranch_vccz .LBB0_1232
	s_waitcnt vmcnt(0)
	s_cmpk_gt_u32 s4, 0xff
	s_cbranch_scc1 .LBB0_1243
	s_barrier

.LBB0_1461:
	ds_read_b128 v[140:143], v149
	ds_read_b128 v[152:155], v149 offset:1024
	ds_read_b128 v[156:159], v149 offset:2048
	ds_read_b128 v[160:163], v149 offset:3072
	s_add_u32 s34, s30, 0x100
	s_addc_u32 s35, s31, 0
	s_cmp_eq_u32 s74, 40
	s_cselect_b32 s39, s13, s35
	s_cselect_b32 s38, s12, s34
	s_cselect_b32 s37, s15, s73
	s_cselect_b32 s36, s14, s72
	v_lshl_add_u64 v[144:145], s[30:31], 0, v[132:133]
	s_add_i32 m0, s8, 0xc000
	ds_read_b128 v[164:167], v150
	ds_read_b128 v[168:171], v150 offset:1024
	ds_read_b128 v[172:175], v150 offset:2048
	ds_read_b128 v[176:179], v150 offset:3072
	ds_read_b128 v[180:183], v150 offset:4096
	ds_read_b128 v[184:187], v150 offset:5120
	ds_read_b128 v[188:191], v150 offset:6144
	ds_read_b128 v[192:195], v150 offset:7168
	global_load_lds_dwordx4 v[144:145], off
	v_lshl_add_u64 v[144:145], s[30:31], 0, v[134:135]
	s_add_i32 m0, s8, 0xe000
	s_nop 0
	global_load_lds_dwordx4 v[144:145], off
	ds_read_b128 v[196:199], v151
	ds_read_b128 v[200:203], v151 offset:1024
	ds_read_b128 v[204:207], v151 offset:2048
	ds_read_b128 v[208:211], v151 offset:3072
	s_waitcnt lgkmcnt(0)
	s_barrier
	s_setprio 1
	v_mfma_f32_16x16x32_bf16 v[124:127], v[140:143], v[164:167], v[124:127]
	v_mfma_f32_16x16x32_bf16 v[120:123], v[156:159], v[164:167], v[120:123]
	v_mfma_f32_16x16x32_bf16 v[112:115], v[140:143], v[172:175], v[112:115]
	v_mfma_f32_16x16x32_bf16 v[104:107], v[156:159], v[172:175], v[104:107]
	v_mfma_f32_16x16x32_bf16 v[92:95], v[140:143], v[180:183], v[92:95]
	v_mfma_f32_16x16x32_bf16 v[88:91], v[156:159], v[180:183], v[88:91]
	v_mfma_f32_16x16x32_bf16 v[80:83], v[140:143], v[188:191], v[80:83]
	v_mfma_f32_16x16x32_bf16 v[72:75], v[156:159], v[188:191], v[72:75]
	v_mfma_f32_16x16x32_bf16 v[124:127], v[152:155], v[168:171], v[124:127]
	v_mfma_f32_16x16x32_bf16 v[120:123], v[160:163], v[168:171], v[120:123]
	v_mfma_f32_16x16x32_bf16 v[112:115], v[152:155], v[176:179], v[112:115]
	v_mfma_f32_16x16x32_bf16 v[104:107], v[160:163], v[176:179], v[104:107]
	v_mfma_f32_16x16x32_bf16 v[92:95], v[152:155], v[184:187], v[92:95]
	v_mfma_f32_16x16x32_bf16 v[88:91], v[160:163], v[184:187], v[88:91]
	v_mfma_f32_16x16x32_bf16 v[80:83], v[152:155], v[192:195], v[80:83]
	v_mfma_f32_16x16x32_bf16 v[72:75], v[160:163], v[192:195], v[72:75]
	v_mfma_f32_16x16x32_bf16 v[116:119], v[196:199], v[164:167], v[116:119]
	v_mfma_f32_16x16x32_bf16 v[108:111], v[204:207], v[164:167], v[108:111]
	v_mfma_f32_16x16x32_bf16 v[100:103], v[196:199], v[172:175], v[100:103]
	v_mfma_f32_16x16x32_bf16 v[96:99], v[204:207], v[172:175], v[96:99]
	v_mfma_f32_16x16x32_bf16 v[84:87], v[196:199], v[180:183], v[84:87]
	v_mfma_f32_16x16x32_bf16 v[76:79], v[204:207], v[180:183], v[76:79]
	v_mfma_f32_16x16x32_bf16 v[68:71], v[196:199], v[188:191], v[68:71]
	v_mfma_f32_16x16x32_bf16 v[64:67], v[204:207], v[188:191], v[64:67]
	v_mfma_f32_16x16x32_bf16 v[116:119], v[200:203], v[168:171], v[116:119]
	v_mfma_f32_16x16x32_bf16 v[108:111], v[208:211], v[168:171], v[108:111]
	v_mfma_f32_16x16x32_bf16 v[100:103], v[200:203], v[176:179], v[100:103]
	v_mfma_f32_16x16x32_bf16 v[96:99], v[208:211], v[176:179], v[96:99]
	v_mfma_f32_16x16x32_bf16 v[84:87], v[200:203], v[184:187], v[84:87]
	v_mfma_f32_16x16x32_bf16 v[76:79], v[208:211], v[184:187], v[76:79]
	v_mfma_f32_16x16x32_bf16 v[68:71], v[200:203], v[192:195], v[68:71]
	v_mfma_f32_16x16x32_bf16 v[64:67], v[208:211], v[192:195], v[64:67]
	s_setprio 0
	s_barrier
	s_nop 1
	ds_read_b128 v[164:167], v150 offset:16384
	ds_read_b128 v[168:171], v150 offset:17408
	ds_read_b128 v[172:175], v150 offset:18432
	ds_read_b128 v[176:179], v150 offset:19456
	ds_read_b128 v[180:183], v150 offset:20480
	ds_read_b128 v[184:187], v150 offset:21504
	ds_read_b128 v[188:191], v150 offset:22528
	ds_read_b128 v[192:195], v150 offset:23552
	s_add_i32 s30, s45, s7
	v_lshl_add_u64 v[144:145], s[36:37], 0, v[128:129]
	s_mov_b32 m0, s30
	s_nop 0
	global_load_lds_dwordx4 v[144:145], off
	v_lshl_add_u64 v[212:213], s[36:37], 0, v[130:131]
	s_add_i32 m0, s30, 0x2000
	s_nop 0
	global_load_lds_dwordx4 v[212:213], off
	s_mov_b32 m0, s8
	v_lshl_add_u64 v[214:215], s[38:39], 0, v[128:129]
	global_load_lds_dwordx4 v[214:215], off
	v_lshl_add_u64 v[216:217], s[38:39], 0, v[130:131]
	s_mov_b32 m0, s9
	s_nop 0
	global_load_lds_dwordx4 v[216:217], off
	s_add_u32 s30, s36, 0xb0000
	s_addc_u32 s31, s37, 0
	s_add_i32 s75, s46, s7
	v_lshl_add_u64 v[254:255], s[30:31], 0, v[128:129]
	s_mov_b32 m0, s75
	s_nop 0
	global_load_lds_dwordx4 v[254:255], off
	v_lshl_add_u64 v[254:255], s[30:31], 0, v[130:131]
	s_add_i32 m0, s75, 0x2000
	s_nop 0
	global_load_lds_dwordx4 v[254:255], off
	s_waitcnt vmcnt(6)
	s_waitcnt lgkmcnt(0)
	s_barrier
	s_setprio 1
	v_mfma_f32_16x16x32_bf16 v[60:63], v[140:143], v[164:167], v[60:63]
	v_mfma_f32_16x16x32_bf16 v[56:59], v[156:159], v[164:167], v[56:59]
	v_mfma_f32_16x16x32_bf16 v[48:51], v[140:143], v[172:175], v[48:51]
	v_mfma_f32_16x16x32_bf16 v[40:43], v[156:159], v[172:175], v[40:43]
	v_mfma_f32_16x16x32_bf16 v[28:31], v[140:143], v[180:183], v[28:31]
	v_mfma_f32_16x16x32_bf16 v[24:27], v[156:159], v[180:183], v[24:27]
	v_mfma_f32_16x16x32_bf16 v[16:19], v[140:143], v[188:191], v[16:19]
	v_mfma_f32_16x16x32_bf16 v[8:11], v[156:159], v[188:191], v[8:11]
	v_mfma_f32_16x16x32_bf16 v[60:63], v[152:155], v[168:171], v[60:63]
	v_mfma_f32_16x16x32_bf16 v[56:59], v[160:163], v[168:171], v[56:59]
	v_mfma_f32_16x16x32_bf16 v[48:51], v[152:155], v[176:179], v[48:51]
	v_mfma_f32_16x16x32_bf16 v[40:43], v[160:163], v[176:179], v[40:43]
	v_mfma_f32_16x16x32_bf16 v[28:31], v[152:155], v[184:187], v[28:31]
	v_mfma_f32_16x16x32_bf16 v[24:27], v[160:163], v[184:187], v[24:27]
	v_mfma_f32_16x16x32_bf16 v[16:19], v[152:155], v[192:195], v[16:19]
	v_mfma_f32_16x16x32_bf16 v[8:11], v[160:163], v[192:195], v[8:11]
	v_mfma_f32_16x16x32_bf16 v[52:55], v[196:199], v[164:167], v[52:55]
	v_mfma_f32_16x16x32_bf16 v[44:47], v[204:207], v[164:167], v[44:47]
	v_mfma_f32_16x16x32_bf16 v[36:39], v[196:199], v[172:175], v[36:39]
	v_mfma_f32_16x16x32_bf16 v[32:35], v[204:207], v[172:175], v[32:35]
	v_mfma_f32_16x16x32_bf16 v[20:23], v[196:199], v[180:183], v[20:23]
	v_mfma_f32_16x16x32_bf16 v[12:15], v[204:207], v[180:183], v[12:15]
	v_mfma_f32_16x16x32_bf16 v[4:7], v[196:199], v[188:191], v[4:7]
	v_mfma_f32_16x16x32_bf16 v[0:3], v[204:207], v[188:191], v[0:3]
	v_mfma_f32_16x16x32_bf16 v[52:55], v[200:203], v[168:171], v[52:55]
	v_mfma_f32_16x16x32_bf16 v[44:47], v[208:211], v[168:171], v[44:47]
	v_mfma_f32_16x16x32_bf16 v[36:39], v[200:203], v[176:179], v[36:39]
	v_mfma_f32_16x16x32_bf16 v[32:35], v[208:211], v[176:179], v[32:35]
	v_mfma_f32_16x16x32_bf16 v[20:23], v[200:203], v[184:187], v[20:23]
	v_mfma_f32_16x16x32_bf16 v[12:15], v[208:211], v[184:187], v[12:15]
	v_mfma_f32_16x16x32_bf16 v[4:7], v[200:203], v[192:195], v[4:7]
	v_mfma_f32_16x16x32_bf16 v[0:3], v[208:211], v[192:195], v[0:3]
	s_setprio 0
	s_add_i32 s75, 0, 0x18000
	v_add_u32_e32 v160, s75, v147
	s_barrier
	ds_read_b128 v[140:143], v160
	ds_read_b128 v[152:155], v160 offset:1024
	ds_read_b128 v[156:159], v160 offset:2048
	ds_read_b128 v[160:163], v160 offset:3072
	s_add_u32 s30, s38, 0xb0000
	s_addc_u32 s31, s39, 0
	s_mov_b32 m0, s40
	v_lshl_add_u64 v[196:197], s[30:31], 0, v[128:129]
	ds_read_b128 v[164:167], v150 offset:32768
	ds_read_b128 v[168:171], v150 offset:33792
	ds_read_b128 v[172:175], v150 offset:34816
	ds_read_b128 v[176:179], v150 offset:35840
	ds_read_b128 v[180:183], v150 offset:36864
	ds_read_b128 v[184:187], v150 offset:37888
	ds_read_b128 v[188:191], v150 offset:38912
	ds_read_b128 v[192:195], v150 offset:39936
	global_load_lds_dwordx4 v[196:197], off
	v_lshl_add_u64 v[196:197], s[30:31], 0, v[130:131]
	s_mov_b32 m0, s41
	s_nop 0
	global_load_lds_dwordx4 v[196:197], off
	s_add_i32 s38, 0, 0x1c000
	v_add_u32_e32 v208, s38, v147
	ds_read_b128 v[196:199], v208
	ds_read_b128 v[200:203], v208 offset:1024
	ds_read_b128 v[204:207], v208 offset:2048
	ds_read_b128 v[208:211], v208 offset:3072
	s_waitcnt lgkmcnt(0)
	s_barrier
	s_setprio 1
	v_mfma_f32_16x16x32_bf16 v[124:127], v[140:143], v[164:167], v[124:127]
	v_mfma_f32_16x16x32_bf16 v[120:123], v[156:159], v[164:167], v[120:123]
	v_mfma_f32_16x16x32_bf16 v[112:115], v[140:143], v[172:175], v[112:115]
	v_mfma_f32_16x16x32_bf16 v[104:107], v[156:159], v[172:175], v[104:107]
	v_mfma_f32_16x16x32_bf16 v[92:95], v[140:143], v[180:183], v[92:95]
	v_mfma_f32_16x16x32_bf16 v[88:91], v[156:159], v[180:183], v[88:91]
	v_mfma_f32_16x16x32_bf16 v[80:83], v[140:143], v[188:191], v[80:83]
	v_mfma_f32_16x16x32_bf16 v[72:75], v[156:159], v[188:191], v[72:75]
	v_mfma_f32_16x16x32_bf16 v[124:127], v[152:155], v[168:171], v[124:127]
	v_mfma_f32_16x16x32_bf16 v[120:123], v[160:163], v[168:171], v[120:123]
	v_mfma_f32_16x16x32_bf16 v[112:115], v[152:155], v[176:179], v[112:115]
	v_mfma_f32_16x16x32_bf16 v[104:107], v[160:163], v[176:179], v[104:107]
	v_mfma_f32_16x16x32_bf16 v[92:95], v[152:155], v[184:187], v[92:95]
	v_mfma_f32_16x16x32_bf16 v[88:91], v[160:163], v[184:187], v[88:91]
	v_mfma_f32_16x16x32_bf16 v[80:83], v[152:155], v[192:195], v[80:83]
	v_mfma_f32_16x16x32_bf16 v[72:75], v[160:163], v[192:195], v[72:75]
	v_mfma_f32_16x16x32_bf16 v[116:119], v[196:199], v[164:167], v[116:119]
	v_mfma_f32_16x16x32_bf16 v[108:111], v[204:207], v[164:167], v[108:111]
	v_mfma_f32_16x16x32_bf16 v[100:103], v[196:199], v[172:175], v[100:103]
	v_mfma_f32_16x16x32_bf16 v[96:99], v[204:207], v[172:175], v[96:99]
	v_mfma_f32_16x16x32_bf16 v[84:87], v[196:199], v[180:183], v[84:87]
	v_mfma_f32_16x16x32_bf16 v[76:79], v[204:207], v[180:183], v[76:79]
	v_mfma_f32_16x16x32_bf16 v[68:71], v[196:199], v[188:191], v[68:71]
	v_mfma_f32_16x16x32_bf16 v[64:67], v[204:207], v[188:191], v[64:67]
	v_mfma_f32_16x16x32_bf16 v[116:119], v[200:203], v[168:171], v[116:119]
	v_mfma_f32_16x16x32_bf16 v[108:111], v[208:211], v[168:171], v[108:111]
	v_mfma_f32_16x16x32_bf16 v[100:103], v[200:203], v[176:179], v[100:103]
	v_mfma_f32_16x16x32_bf16 v[96:99], v[208:211], v[176:179], v[96:99]
	v_mfma_f32_16x16x32_bf16 v[84:87], v[200:203], v[184:187], v[84:87]
	v_mfma_f32_16x16x32_bf16 v[76:79], v[208:211], v[184:187], v[76:79]
	v_mfma_f32_16x16x32_bf16 v[68:71], v[200:203], v[192:195], v[68:71]
	v_mfma_f32_16x16x32_bf16 v[64:67], v[208:211], v[192:195], v[64:67]
	s_setprio 0
	s_barrier
	s_nop 1
	ds_read_b128 v[164:167], v150 offset:49152
	ds_read_b128 v[168:171], v150 offset:50176
	ds_read_b128 v[172:175], v150 offset:51200
	ds_read_b128 v[176:179], v150 offset:52224
	ds_read_b128 v[180:183], v150 offset:53248
	ds_read_b128 v[184:187], v150 offset:54272
	ds_read_b128 v[188:191], v150 offset:55296
	ds_read_b128 v[192:195], v150 offset:56320
	s_add_i32 s30, s75, s7
	v_lshl_add_u64 v[254:255], v[144:145], 0, s[22:23]
	s_mov_b32 m0, s30
	s_nop 0
	global_load_lds_dwordx4 v[254:255], off
	v_lshl_add_u64 v[254:255], v[212:213], 0, s[22:23]
	s_add_i32 m0, s30, 0x2000
	s_nop 0
	global_load_lds_dwordx4 v[254:255], off
	s_mov_b32 m0, s43
	v_lshl_add_u64 v[254:255], v[214:215], 0, s[22:23]
	global_load_lds_dwordx4 v[254:255], off
	v_lshl_add_u64 v[144:145], v[216:217], 0, s[22:23]
	s_mov_b32 m0, s44
	s_nop 0
	global_load_lds_dwordx4 v[144:145], off
	s_add_u32 s30, s36, 0xb0080
	s_addc_u32 s31, s37, 0
	s_add_i32 s36, s38, s7
	v_lshl_add_u64 v[254:255], s[30:31], 0, v[128:129]
	s_mov_b32 m0, s36
	s_nop 0
	global_load_lds_dwordx4 v[254:255], off
	v_lshl_add_u64 v[254:255], s[30:31], 0, v[130:131]
	s_add_i32 m0, s36, 0x2000
	s_nop 0
	global_load_lds_dwordx4 v[254:255], off
	s_waitcnt vmcnt(6)
	s_waitcnt lgkmcnt(0)
	s_barrier
	s_setprio 1
	v_mfma_f32_16x16x32_bf16 v[60:63], v[140:143], v[164:167], v[60:63]
	v_mfma_f32_16x16x32_bf16 v[56:59], v[156:159], v[164:167], v[56:59]
	v_mfma_f32_16x16x32_bf16 v[48:51], v[140:143], v[172:175], v[48:51]
	v_mfma_f32_16x16x32_bf16 v[40:43], v[156:159], v[172:175], v[40:43]
	v_mfma_f32_16x16x32_bf16 v[28:31], v[140:143], v[180:183], v[28:31]
	v_mfma_f32_16x16x32_bf16 v[24:27], v[156:159], v[180:183], v[24:27]
	v_mfma_f32_16x16x32_bf16 v[16:19], v[140:143], v[188:191], v[16:19]
	v_mfma_f32_16x16x32_bf16 v[8:11], v[156:159], v[188:191], v[8:11]
	v_mfma_f32_16x16x32_bf16 v[60:63], v[152:155], v[168:171], v[60:63]
	v_mfma_f32_16x16x32_bf16 v[56:59], v[160:163], v[168:171], v[56:59]
	v_mfma_f32_16x16x32_bf16 v[48:51], v[152:155], v[176:179], v[48:51]
	v_mfma_f32_16x16x32_bf16 v[40:43], v[160:163], v[176:179], v[40:43]
	v_mfma_f32_16x16x32_bf16 v[28:31], v[152:155], v[184:187], v[28:31]
	v_mfma_f32_16x16x32_bf16 v[24:27], v[160:163], v[184:187], v[24:27]
	v_mfma_f32_16x16x32_bf16 v[16:19], v[152:155], v[192:195], v[16:19]
	v_mfma_f32_16x16x32_bf16 v[8:11], v[160:163], v[192:195], v[8:11]
	v_mfma_f32_16x16x32_bf16 v[52:55], v[196:199], v[164:167], v[52:55]
	v_mfma_f32_16x16x32_bf16 v[44:47], v[204:207], v[164:167], v[44:47]
	v_mfma_f32_16x16x32_bf16 v[36:39], v[196:199], v[172:175], v[36:39]
	v_mfma_f32_16x16x32_bf16 v[32:35], v[204:207], v[172:175], v[32:35]
	v_mfma_f32_16x16x32_bf16 v[20:23], v[196:199], v[180:183], v[20:23]
	v_mfma_f32_16x16x32_bf16 v[12:15], v[204:207], v[180:183], v[12:15]
	v_mfma_f32_16x16x32_bf16 v[4:7], v[196:199], v[188:191], v[4:7]
	v_mfma_f32_16x16x32_bf16 v[0:3], v[204:207], v[188:191], v[0:3]
	v_mfma_f32_16x16x32_bf16 v[52:55], v[200:203], v[168:171], v[52:55]
	v_mfma_f32_16x16x32_bf16 v[44:47], v[208:211], v[168:171], v[44:47]
	v_mfma_f32_16x16x32_bf16 v[36:39], v[200:203], v[176:179], v[36:39]
	v_mfma_f32_16x16x32_bf16 v[32:35], v[208:211], v[176:179], v[32:35]
	v_mfma_f32_16x16x32_bf16 v[20:23], v[200:203], v[184:187], v[20:23]
	v_mfma_f32_16x16x32_bf16 v[12:15], v[208:211], v[184:187], v[12:15]
	v_mfma_f32_16x16x32_bf16 v[4:7], v[200:203], v[192:195], v[4:7]
	v_mfma_f32_16x16x32_bf16 v[0:3], v[208:211], v[192:195], v[0:3]
	s_setprio 0
	s_add_i32 s74, s74, 2
	s_add_u32 s72, s72, 0x100
	s_addc_u32 s73, s73, 0
	s_cmp_gt_u32 s74, 41
	s_mov_b64 s[30:31], s[34:35]
	s_barrier
	s_cbranch_scc0 .LBB0_1461
	v_lshl_or_b32 v144, s49, 8, v148
	v_lshl_add_u32 v145, s63, 8, v146
	v_lshlrev_b32_e32 v144, 2, v144
	v_lshl_add_u32 v145, v145, 12, v144
	v_add_u32_e32 v216, 0x10000, v145
	v_add_u32_e32 v217, 0x20000, v145
	v_add_u32_e32 v218, 0x30000, v145
	v_add_u32_e32 v220, 0x80000, v145
	v_add_u32_e32 v221, 0x90000, v145
	v_add_u32_e32 v222, 0xa0000, v145
	v_add_u32_e32 v223, 0xb0000, v145
	v_and_b32_e32 v235, 8, v146
	v_cmp_ne_u32_e32 vcc, 0, v235
	v_mov_b32_e32 v232, 0xffff8040
	s_nop 0
	v_cndmask_b32_e32 v232, 0, v232, vcc
	v_mov_b32_e32 v233, 64
	v_mov_b32_e32 v235, 0x8000
	v_cndmask_b32_e32 v233, v235, v233, vcc
	v_add_u32_e32 v224, v145, v232
	v_add_u32_e32 v225, v216, v232
	v_add_u32_e32 v226, v217, v232
	v_add_u32_e32 v227, v218, v232
	v_add_u32_e32 v228, v220, v232
	v_add_u32_e32 v229, v221, v232
	v_add_u32_e32 v230, v222, v232
	v_add_u32_e32 v231, v223, v232
	s_and_b64 vcc, exec, s[10:11]
	s_mov_b32 s49, s47
	s_mov_b32 s63, s48
	s_mov_b64 s[34:35], s[14:15]
	s_mov_b64 s[30:31], s[12:13]
	global_load_dwordx4 v[140:143], v224, s[52:53]
	v_add_u32_e32 v144, v145, v233
	global_load_dwordx4 v[152:155], v144, s[52:53]
	global_load_dwordx4 v[156:159], v224, s[52:53] offset:512
	v_add_u32_e32 v144, v145, v233
	global_load_dwordx4 v[160:163], v144, s[52:53] offset:512
	global_load_dwordx4 v[164:167], v225, s[52:53]
	v_add_u32_e32 v144, v216, v233
	global_load_dwordx4 v[168:171], v144, s[52:53]
	global_load_dwordx4 v[172:175], v225, s[52:53] offset:512
	v_add_u32_e32 v144, v216, v233
	global_load_dwordx4 v[176:179], v144, s[52:53] offset:512
	global_load_dwordx4 v[180:183], v226, s[52:53]
	v_add_u32_e32 v144, v217, v233
	global_load_dwordx4 v[184:187], v144, s[52:53]
	global_load_dwordx4 v[188:191], v226, s[52:53] offset:512
	v_add_u32_e32 v144, v217, v233
	global_load_dwordx4 v[192:195], v144, s[52:53] offset:512
	global_load_dwordx4 v[196:199], v227, s[52:53]
	v_add_u32_e32 v144, v218, v233
	global_load_dwordx4 v[200:203], v144, s[52:53]
	global_load_dwordx4 v[204:207], v227, s[52:53] offset:512
;     __device__ __forceinline__ void operator()(AccRef acc, const Unit& u, int wr, int wc, int fr, int fq) const {
;     ...
;                         for (int n = 0; n < 2; ++n) bs[m][bj][n] = *(const f32x4*)(base + (size_t)(row0 + ai * 128 + (2 * mh + m) * 16) * D + col0 + bj * 128 + n * 16);
; #pragma unroll
;                 for (int m = 0; m < 2; ++m)
; #pragma unroll
;                     for (int bj = 0; bj < 2; ++bj)
; #pragma unroll
;                         for (int n = 0; n < 2; ++n) *(f32x4*)(out + (size_t)(row0 + ai * 128 + (2 * mh + m) * 16) * D + col0 + bj * 128 + n * 16) = bs[m][bj][n] + sv[bj][n] * (acc[ai][bj][2 * mh + m][n] + bv[bj][n]);
	v_add_u32_e32 v144, v218, v233
	global_load_dwordx4 v[208:211], v144, s[52:53] offset:512
	v_pk_add_f32 v[124:125], v[124:125], 0 op_sel_hi:[1,0]
	v_pk_add_f32 v[126:127], v[126:127], 0 op_sel_hi:[1,0]
	v_pk_add_f32 v[120:121], v[120:121], 0 op_sel_hi:[1,0]
	v_pk_add_f32 v[122:123], v[122:123], 0 op_sel_hi:[1,0]
	v_pk_add_f32 v[116:117], v[116:117], 0 op_sel_hi:[1,0]
	v_pk_add_f32 v[118:119], v[118:119], 0 op_sel_hi:[1,0]
	v_pk_add_f32 v[108:109], v[108:109], 0 op_sel_hi:[1,0]
	v_pk_add_f32 v[110:111], v[110:111], 0 op_sel_hi:[1,0]
	v_pk_add_f32 v[112:113], v[112:113], 0 op_sel_hi:[1,0]
	v_pk_add_f32 v[114:115], v[114:115], 0 op_sel_hi:[1,0]
	v_pk_add_f32 v[104:105], v[104:105], 0 op_sel_hi:[1,0]
	v_pk_add_f32 v[106:107], v[106:107], 0 op_sel_hi:[1,0]
	v_pk_add_f32 v[100:101], v[100:101], 0 op_sel_hi:[1,0]
	v_pk_add_f32 v[102:103], v[102:103], 0 op_sel_hi:[1,0]
	v_pk_add_f32 v[96:97], v[96:97], 0 op_sel_hi:[1,0]
	v_pk_add_f32 v[98:99], v[98:99], 0 op_sel_hi:[1,0]
	v_pk_add_f32 v[92:93], v[92:93], 0 op_sel_hi:[1,0]
	v_pk_add_f32 v[94:95], v[94:95], 0 op_sel_hi:[1,0]
	v_pk_add_f32 v[88:89], v[88:89], 0 op_sel_hi:[1,0]
	v_pk_add_f32 v[90:91], v[90:91], 0 op_sel_hi:[1,0]
	v_pk_add_f32 v[84:85], v[84:85], 0 op_sel_hi:[1,0]
	v_pk_add_f32 v[86:87], v[86:87], 0 op_sel_hi:[1,0]
	v_pk_add_f32 v[76:77], v[76:77], 0 op_sel_hi:[1,0]
	v_pk_add_f32 v[78:79], v[78:79], 0 op_sel_hi:[1,0]
	v_pk_add_f32 v[80:81], v[80:81], 0 op_sel_hi:[1,0]
	v_pk_add_f32 v[82:83], v[82:83], 0 op_sel_hi:[1,0]
	v_pk_add_f32 v[72:73], v[72:73], 0 op_sel_hi:[1,0]
	v_pk_add_f32 v[74:75], v[74:75], 0 op_sel_hi:[1,0]
	v_pk_add_f32 v[68:69], v[68:69], 0 op_sel_hi:[1,0]
	v_pk_add_f32 v[70:71], v[70:71], 0 op_sel_hi:[1,0]
	v_pk_add_f32 v[64:65], v[64:65], 0 op_sel_hi:[1,0]
	v_pk_add_f32 v[66:67], v[66:67], 0 op_sel_hi:[1,0]
	v_pk_add_f32 v[60:61], v[60:61], 0 op_sel_hi:[1,0]
	v_pk_add_f32 v[62:63], v[62:63], 0 op_sel_hi:[1,0]
	v_pk_add_f32 v[56:57], v[56:57], 0 op_sel_hi:[1,0]
	v_pk_add_f32 v[58:59], v[58:59], 0 op_sel_hi:[1,0]
	v_pk_add_f32 v[52:53], v[52:53], 0 op_sel_hi:[1,0]
	v_pk_add_f32 v[54:55], v[54:55], 0 op_sel_hi:[1,0]
	v_pk_add_f32 v[44:45], v[44:45], 0 op_sel_hi:[1,0]
	v_pk_add_f32 v[46:47], v[46:47], 0 op_sel_hi:[1,0]
	v_pk_add_f32 v[48:49], v[48:49], 0 op_sel_hi:[1,0]
	v_pk_add_f32 v[50:51], v[50:51], 0 op_sel_hi:[1,0]
	v_pk_add_f32 v[40:41], v[40:41], 0 op_sel_hi:[1,0]
	v_pk_add_f32 v[42:43], v[42:43], 0 op_sel_hi:[1,0]
	v_pk_add_f32 v[36:37], v[36:37], 0 op_sel_hi:[1,0]
	v_pk_add_f32 v[38:39], v[38:39], 0 op_sel_hi:[1,0]
	v_pk_add_f32 v[32:33], v[32:33], 0 op_sel_hi:[1,0]
	v_pk_add_f32 v[34:35], v[34:35], 0 op_sel_hi:[1,0]
	v_pk_add_f32 v[28:29], v[28:29], 0 op_sel_hi:[1,0]
	v_pk_add_f32 v[30:31], v[30:31], 0 op_sel_hi:[1,0]
	v_pk_add_f32 v[24:25], v[24:25], 0 op_sel_hi:[1,0]
	v_pk_add_f32 v[26:27], v[26:27], 0 op_sel_hi:[1,0]
	v_pk_add_f32 v[20:21], v[20:21], 0 op_sel_hi:[1,0]
	v_pk_add_f32 v[22:23], v[22:23], 0 op_sel_hi:[1,0]
	v_pk_add_f32 v[12:13], v[12:13], 0 op_sel_hi:[1,0]
	v_pk_add_f32 v[14:15], v[14:15], 0 op_sel_hi:[1,0]
	v_pk_add_f32 v[16:17], v[16:17], 0 op_sel_hi:[1,0]
	v_pk_add_f32 v[18:19], v[18:19], 0 op_sel_hi:[1,0]
	v_pk_add_f32 v[8:9], v[8:9], 0 op_sel_hi:[1,0]
	v_pk_add_f32 v[10:11], v[10:11], 0 op_sel_hi:[1,0]
	v_pk_add_f32 v[4:5], v[4:5], 0 op_sel_hi:[1,0]
	v_pk_add_f32 v[6:7], v[6:7], 0 op_sel_hi:[1,0]
	v_pk_add_f32 v[0:1], v[0:1], 0 op_sel_hi:[1,0]
	v_pk_add_f32 v[2:3], v[2:3], 0 op_sel_hi:[1,0]
	s_waitcnt vmcnt(8)
	v_mov_b32_e32 v212, v124
	v_mov_b32_e32 v213, v125
	v_mov_b32_e32 v214, v126
	v_mov_b32_e32 v215, v127
	s_nop 0
	v_mov_b32_dpp v124, v120 row_shr:8 row_mask:0xf bank_mask:0xc
	v_mov_b32_dpp v125, v121 row_shr:8 row_mask:0xf bank_mask:0xc
	v_mov_b32_dpp v126, v122 row_shr:8 row_mask:0xf bank_mask:0xc
	v_mov_b32_dpp v127, v123 row_shr:8 row_mask:0xf bank_mask:0xc
	v_mov_b32_dpp v120, v212 row_shl:8 row_mask:0xf bank_mask:0x3
	v_mov_b32_dpp v121, v213 row_shl:8 row_mask:0xf bank_mask:0x3
	v_mov_b32_dpp v122, v214 row_shl:8 row_mask:0xf bank_mask:0x3
	v_mov_b32_dpp v123, v215 row_shl:8 row_mask:0xf bank_mask:0x3
	v_mov_b32_e32 v212, v116
	v_mov_b32_e32 v213, v117
	v_mov_b32_e32 v214, v118
	v_mov_b32_e32 v215, v119
	s_nop 0
	v_mov_b32_dpp v116, v108 row_shr:8 row_mask:0xf bank_mask:0xc
	v_mov_b32_dpp v117, v109 row_shr:8 row_mask:0xf bank_mask:0xc
	v_mov_b32_dpp v118, v110 row_shr:8 row_mask:0xf bank_mask:0xc
	v_mov_b32_dpp v119, v111 row_shr:8 row_mask:0xf bank_mask:0xc
	v_mov_b32_dpp v108, v212 row_shl:8 row_mask:0xf bank_mask:0x3
	v_mov_b32_dpp v109, v213 row_shl:8 row_mask:0xf bank_mask:0x3
	v_mov_b32_dpp v110, v214 row_shl:8 row_mask:0xf bank_mask:0x3
	v_mov_b32_dpp v111, v215 row_shl:8 row_mask:0xf bank_mask:0x3
	v_mov_b32_e32 v212, v112
	v_mov_b32_e32 v213, v113
	v_mov_b32_e32 v214, v114
	v_mov_b32_e32 v215, v115
	s_nop 0
	v_mov_b32_dpp v112, v104 row_shr:8 row_mask:0xf bank_mask:0xc
	v_mov_b32_dpp v113, v105 row_shr:8 row_mask:0xf bank_mask:0xc
	v_mov_b32_dpp v114, v106 row_shr:8 row_mask:0xf bank_mask:0xc
	v_mov_b32_dpp v115, v107 row_shr:8 row_mask:0xf bank_mask:0xc
	v_mov_b32_dpp v104, v212 row_shl:8 row_mask:0xf bank_mask:0x3
	v_mov_b32_dpp v105, v213 row_shl:8 row_mask:0xf bank_mask:0x3
	v_mov_b32_dpp v106, v214 row_shl:8 row_mask:0xf bank_mask:0x3
	v_mov_b32_dpp v107, v215 row_shl:8 row_mask:0xf bank_mask:0x3
	v_mov_b32_e32 v212, v100
	v_mov_b32_e32 v213, v101
	v_mov_b32_e32 v214, v102
	v_mov_b32_e32 v215, v103
	s_nop 0
	v_mov_b32_dpp v100, v96 row_shr:8 row_mask:0xf bank_mask:0xc
	v_mov_b32_dpp v101, v97 row_shr:8 row_mask:0xf bank_mask:0xc
	v_mov_b32_dpp v102, v98 row_shr:8 row_mask:0xf bank_mask:0xc
;     __device__ __forceinline__ void operator()(AccRef acc, const Unit& u, int wr, int wc, int fr, int fq) const {
;     ...
;                         for (int n = 0; n < 2; ++n) bs[m][bj][n] = *(const f32x4*)(base + (size_t)(row0 + ai * 128 + (2 * mh + m) * 16) * D + col0 + bj * 128 + n * 16);
; #pragma unroll
;                 for (int m = 0; m < 2; ++m)
; #pragma unroll
;                     for (int bj = 0; bj < 2; ++bj)
; #pragma unroll
;                         for (int n = 0; n < 2; ++n) *(f32x4*)(out + (size_t)(row0 + ai * 128 + (2 * mh + m) * 16) * D + col0 + bj * 128 + n * 16) = bs[m][bj][n] + sv[bj][n] * (acc[ai][bj][2 * mh + m][n] + bv[bj][n]);
;                 asm volatile("" ::: "memory"); }
	v_mov_b32_dpp v103, v99 row_shr:8 row_mask:0xf bank_mask:0xc
	v_mov_b32_dpp v96, v212 row_shl:8 row_mask:0xf bank_mask:0x3
	v_mov_b32_dpp v97, v213 row_shl:8 row_mask:0xf bank_mask:0x3
	v_mov_b32_dpp v98, v214 row_shl:8 row_mask:0xf bank_mask:0x3
	v_mov_b32_dpp v99, v215 row_shl:8 row_mask:0xf bank_mask:0x3
	v_pk_add_f32 v[124:125], v[124:125], v[140:141]
	v_pk_add_f32 v[126:127], v[126:127], v[142:143]
	v_pk_add_f32 v[120:121], v[120:121], v[152:153]
	v_pk_add_f32 v[122:123], v[122:123], v[154:155]
	v_pk_add_f32 v[116:117], v[116:117], v[156:157]
	v_pk_add_f32 v[118:119], v[118:119], v[158:159]
	v_pk_add_f32 v[108:109], v[108:109], v[160:161]
	v_pk_add_f32 v[110:111], v[110:111], v[162:163]
	v_pk_add_f32 v[112:113], v[112:113], v[164:165]
	v_pk_add_f32 v[114:115], v[114:115], v[166:167]
	v_pk_add_f32 v[104:105], v[104:105], v[168:169]
	v_pk_add_f32 v[106:107], v[106:107], v[170:171]
	v_pk_add_f32 v[100:101], v[100:101], v[172:173]
	v_pk_add_f32 v[102:103], v[102:103], v[174:175]
	v_pk_add_f32 v[96:97], v[96:97], v[176:177]
	v_pk_add_f32 v[98:99], v[98:99], v[178:179]
	global_store_dwordx4 v224, v[124:127], s[52:53]
	v_add_u32_e32 v144, v145, v233
	global_store_dwordx4 v144, v[120:123], s[52:53]
	global_store_dwordx4 v224, v[116:119], s[52:53] offset:512
	v_add_u32_e32 v144, v145, v233
	global_store_dwordx4 v144, v[108:111], s[52:53] offset:512
	global_store_dwordx4 v225, v[112:115], s[52:53]
	v_add_u32_e32 v144, v216, v233
	global_store_dwordx4 v144, v[104:107], s[52:53]
	global_store_dwordx4 v225, v[100:103], s[52:53] offset:512
	v_add_u32_e32 v144, v216, v233
	global_store_dwordx4 v144, v[96:99], s[52:53] offset:512
	global_load_dwordx4 v[140:143], v228, s[52:53]
	v_add_u32_e32 v144, v220, v233
	global_load_dwordx4 v[152:155], v144, s[52:53]
	global_load_dwordx4 v[156:159], v228, s[52:53] offset:512
	v_add_u32_e32 v144, v220, v233
	global_load_dwordx4 v[160:163], v144, s[52:53] offset:512
	global_load_dwordx4 v[164:167], v229, s[52:53]
	v_add_u32_e32 v144, v221, v233
	global_load_dwordx4 v[168:171], v144, s[52:53]
	global_load_dwordx4 v[172:175], v229, s[52:53] offset:512
	v_add_u32_e32 v144, v221, v233
	global_load_dwordx4 v[176:179], v144, s[52:53] offset:512
	s_waitcnt vmcnt(16)
	v_mov_b32_e32 v212, v92
	v_mov_b32_e32 v213, v93
	v_mov_b32_e32 v214, v94
	v_mov_b32_e32 v215, v95
	s_nop 0
	v_mov_b32_dpp v92, v88 row_shr:8 row_mask:0xf bank_mask:0xc
	v_mov_b32_dpp v93, v89 row_shr:8 row_mask:0xf bank_mask:0xc
	v_mov_b32_dpp v94, v90 row_shr:8 row_mask:0xf bank_mask:0xc
	v_mov_b32_dpp v95, v91 row_shr:8 row_mask:0xf bank_mask:0xc
	v_mov_b32_dpp v88, v212 row_shl:8 row_mask:0xf bank_mask:0x3
	v_mov_b32_dpp v89, v213 row_shl:8 row_mask:0xf bank_mask:0x3
	v_mov_b32_dpp v90, v214 row_shl:8 row_mask:0xf bank_mask:0x3
	v_mov_b32_dpp v91, v215 row_shl:8 row_mask:0xf bank_mask:0x3
	v_mov_b32_e32 v212, v84
	v_mov_b32_e32 v213, v85
	v_mov_b32_e32 v214, v86
	v_mov_b32_e32 v215, v87
	s_nop 0
	v_mov_b32_dpp v84, v76 row_shr:8 row_mask:0xf bank_mask:0xc
	v_mov_b32_dpp v85, v77 row_shr:8 row_mask:0xf bank_mask:0xc
	v_mov_b32_dpp v86, v78 row_shr:8 row_mask:0xf bank_mask:0xc
	v_mov_b32_dpp v87, v79 row_shr:8 row_mask:0xf bank_mask:0xc
	v_mov_b32_dpp v76, v212 row_shl:8 row_mask:0xf bank_mask:0x3
	v_mov_b32_dpp v77, v213 row_shl:8 row_mask:0xf bank_mask:0x3
	v_mov_b32_dpp v78, v214 row_shl:8 row_mask:0xf bank_mask:0x3
	v_mov_b32_dpp v79, v215 row_shl:8 row_mask:0xf bank_mask:0x3
	v_mov_b32_e32 v212, v80
	v_mov_b32_e32 v213, v81
	v_mov_b32_e32 v214, v82
	v_mov_b32_e32 v215, v83
	s_nop 0
	v_mov_b32_dpp v80, v72 row_shr:8 row_mask:0xf bank_mask:0xc
	v_mov_b32_dpp v81, v73 row_shr:8 row_mask:0xf bank_mask:0xc
	v_mov_b32_dpp v82, v74 row_shr:8 row_mask:0xf bank_mask:0xc
	v_mov_b32_dpp v83, v75 row_shr:8 row_mask:0xf bank_mask:0xc
	v_mov_b32_dpp v72, v212 row_shl:8 row_mask:0xf bank_mask:0x3
	v_mov_b32_dpp v73, v213 row_shl:8 row_mask:0xf bank_mask:0x3
	v_mov_b32_dpp v74, v214 row_shl:8 row_mask:0xf bank_mask:0x3
	v_mov_b32_dpp v75, v215 row_shl:8 row_mask:0xf bank_mask:0x3
	v_mov_b32_e32 v212, v68
	v_mov_b32_e32 v213, v69
	v_mov_b32_e32 v214, v70
	v_mov_b32_e32 v215, v71
	s_nop 0
	v_mov_b32_dpp v68, v64 row_shr:8 row_mask:0xf bank_mask:0xc
	v_mov_b32_dpp v69, v65 row_shr:8 row_mask:0xf bank_mask:0xc
	v_mov_b32_dpp v70, v66 row_shr:8 row_mask:0xf bank_mask:0xc
	v_mov_b32_dpp v71, v67 row_shr:8 row_mask:0xf bank_mask:0xc
	v_mov_b32_dpp v64, v212 row_shl:8 row_mask:0xf bank_mask:0x3
	v_mov_b32_dpp v65, v213 row_shl:8 row_mask:0xf bank_mask:0x3
	v_mov_b32_dpp v66, v214 row_shl:8 row_mask:0xf bank_mask:0x3
	v_mov_b32_dpp v67, v215 row_shl:8 row_mask:0xf bank_mask:0x3
	v_pk_add_f32 v[92:93], v[92:93], v[180:181]
	v_pk_add_f32 v[94:95], v[94:95], v[182:183]
	v_pk_add_f32 v[88:89], v[88:89], v[184:185]
	v_pk_add_f32 v[90:91], v[90:91], v[186:187]
	v_pk_add_f32 v[84:85], v[84:85], v[188:189]
	v_pk_add_f32 v[86:87], v[86:87], v[190:191]
	v_pk_add_f32 v[76:77], v[76:77], v[192:193]
	v_pk_add_f32 v[78:79], v[78:79], v[194:195]
	v_pk_add_f32 v[80:81], v[80:81], v[196:197]
	v_pk_add_f32 v[82:83], v[82:83], v[198:199]
	v_pk_add_f32 v[72:73], v[72:73], v[200:201]
	v_pk_add_f32 v[74:75], v[74:75], v[202:203]
	v_pk_add_f32 v[68:69], v[68:69], v[204:205]
	v_pk_add_f32 v[70:71], v[70:71], v[206:207]
	v_pk_add_f32 v[64:65], v[64:65], v[208:209]
	v_pk_add_f32 v[66:67], v[66:67], v[210:211]
	global_store_dwordx4 v226, v[92:95], s[52:53]
	v_add_u32_e32 v144, v217, v233
	global_store_dwordx4 v144, v[88:91], s[52:53]
	global_store_dwordx4 v226, v[84:87], s[52:53] offset:512
	v_add_u32_e32 v144, v217, v233
	global_store_dwordx4 v144, v[76:79], s[52:53] offset:512
	global_store_dwordx4 v227, v[80:83], s[52:53]
	v_add_u32_e32 v144, v218, v233
	global_store_dwordx4 v144, v[72:75], s[52:53]
	global_store_dwordx4 v227, v[68:71], s[52:53] offset:512
	v_add_u32_e32 v144, v218, v233
	global_store_dwordx4 v144, v[64:67], s[52:53] offset:512
	global_load_dwordx4 v[180:183], v230, s[52:53]
	v_add_u32_e32 v144, v222, v233
	global_load_dwordx4 v[184:187], v144, s[52:53]
	global_load_dwordx4 v[188:191], v230, s[52:53] offset:512
	v_add_u32_e32 v144, v222, v233
	global_load_dwordx4 v[192:195], v144, s[52:53] offset:512
	global_load_dwordx4 v[196:199], v231, s[52:53]
	v_add_u32_e32 v144, v223, v233
	global_load_dwordx4 v[200:203], v144, s[52:53]
	global_load_dwordx4 v[204:207], v231, s[52:53] offset:512
	v_add_u32_e32 v144, v223, v233
	global_load_dwordx4 v[208:211], v144, s[52:53] offset:512
	s_waitcnt vmcnt(16)
;     __device__ __forceinline__ void operator()(AccRef acc, const Unit& u, int wr, int wc, int fr, int fq) const {
;     ...
;                         for (int n = 0; n < 2; ++n) bs[m][bj][n] = *(const f32x4*)(base + (size_t)(row0 + ai * 128 + (2 * mh + m) * 16) * D + col0 + bj * 128 + n * 16);
; #pragma unroll
;                 for (int m = 0; m < 2; ++m)
; #pragma unroll
;                     for (int bj = 0; bj < 2; ++bj)
; #pragma unroll
;                         for (int n = 0; n < 2; ++n) *(f32x4*)(out + (size_t)(row0 + ai * 128 + (2 * mh + m) * 16) * D + col0 + bj * 128 + n * 16) = bs[m][bj][n] + sv[bj][n] * (acc[ai][bj][2 * mh + m][n] + bv[bj][n]);
;                 asm volatile("" ::: "memory"); }
	v_mov_b32_e32 v212, v60
	v_mov_b32_e32 v213, v61
	v_mov_b32_e32 v214, v62
	v_mov_b32_e32 v215, v63
	s_nop 0
	v_mov_b32_dpp v60, v56 row_shr:8 row_mask:0xf bank_mask:0xc
	v_mov_b32_dpp v61, v57 row_shr:8 row_mask:0xf bank_mask:0xc
	v_mov_b32_dpp v62, v58 row_shr:8 row_mask:0xf bank_mask:0xc
	v_mov_b32_dpp v63, v59 row_shr:8 row_mask:0xf bank_mask:0xc
	v_mov_b32_dpp v56, v212 row_shl:8 row_mask:0xf bank_mask:0x3
	v_mov_b32_dpp v57, v213 row_shl:8 row_mask:0xf bank_mask:0x3
	v_mov_b32_dpp v58, v214 row_shl:8 row_mask:0xf bank_mask:0x3
	v_mov_b32_dpp v59, v215 row_shl:8 row_mask:0xf bank_mask:0x3
	v_mov_b32_e32 v212, v52
	v_mov_b32_e32 v213, v53
	v_mov_b32_e32 v214, v54
	v_mov_b32_e32 v215, v55
	s_nop 0
	v_mov_b32_dpp v52, v44 row_shr:8 row_mask:0xf bank_mask:0xc
	v_mov_b32_dpp v53, v45 row_shr:8 row_mask:0xf bank_mask:0xc
	v_mov_b32_dpp v54, v46 row_shr:8 row_mask:0xf bank_mask:0xc
	v_mov_b32_dpp v55, v47 row_shr:8 row_mask:0xf bank_mask:0xc
	v_mov_b32_dpp v44, v212 row_shl:8 row_mask:0xf bank_mask:0x3
	v_mov_b32_dpp v45, v213 row_shl:8 row_mask:0xf bank_mask:0x3
	v_mov_b32_dpp v46, v214 row_shl:8 row_mask:0xf bank_mask:0x3
	v_mov_b32_dpp v47, v215 row_shl:8 row_mask:0xf bank_mask:0x3
	v_mov_b32_e32 v212, v48
	v_mov_b32_e32 v213, v49
	v_mov_b32_e32 v214, v50
	v_mov_b32_e32 v215, v51
	s_nop 0
	v_mov_b32_dpp v48, v40 row_shr:8 row_mask:0xf bank_mask:0xc
	v_mov_b32_dpp v49, v41 row_shr:8 row_mask:0xf bank_mask:0xc
	v_mov_b32_dpp v50, v42 row_shr:8 row_mask:0xf bank_mask:0xc
	v_mov_b32_dpp v51, v43 row_shr:8 row_mask:0xf bank_mask:0xc
	v_mov_b32_dpp v40, v212 row_shl:8 row_mask:0xf bank_mask:0x3
	v_mov_b32_dpp v41, v213 row_shl:8 row_mask:0xf bank_mask:0x3
	v_mov_b32_dpp v42, v214 row_shl:8 row_mask:0xf bank_mask:0x3
	v_mov_b32_dpp v43, v215 row_shl:8 row_mask:0xf bank_mask:0x3
	v_mov_b32_e32 v212, v36
	v_mov_b32_e32 v213, v37
	v_mov_b32_e32 v214, v38
	v_mov_b32_e32 v215, v39
	s_nop 0
	v_mov_b32_dpp v36, v32 row_shr:8 row_mask:0xf bank_mask:0xc
	v_mov_b32_dpp v37, v33 row_shr:8 row_mask:0xf bank_mask:0xc
	v_mov_b32_dpp v38, v34 row_shr:8 row_mask:0xf bank_mask:0xc
	v_mov_b32_dpp v39, v35 row_shr:8 row_mask:0xf bank_mask:0xc
	v_mov_b32_dpp v32, v212 row_shl:8 row_mask:0xf bank_mask:0x3
	v_mov_b32_dpp v33, v213 row_shl:8 row_mask:0xf bank_mask:0x3
	v_mov_b32_dpp v34, v214 row_shl:8 row_mask:0xf bank_mask:0x3
	v_mov_b32_dpp v35, v215 row_shl:8 row_mask:0xf bank_mask:0x3
	v_pk_add_f32 v[60:61], v[60:61], v[140:141]
	v_pk_add_f32 v[62:63], v[62:63], v[142:143]
	v_pk_add_f32 v[56:57], v[56:57], v[152:153]
	v_pk_add_f32 v[58:59], v[58:59], v[154:155]
	v_pk_add_f32 v[52:53], v[52:53], v[156:157]
	v_pk_add_f32 v[54:55], v[54:55], v[158:159]
	v_pk_add_f32 v[44:45], v[44:45], v[160:161]
	v_pk_add_f32 v[46:47], v[46:47], v[162:163]
	v_pk_add_f32 v[48:49], v[48:49], v[164:165]
	v_pk_add_f32 v[50:51], v[50:51], v[166:167]
	v_pk_add_f32 v[40:41], v[40:41], v[168:169]
	v_pk_add_f32 v[42:43], v[42:43], v[170:171]
	v_pk_add_f32 v[36:37], v[36:37], v[172:173]
	v_pk_add_f32 v[38:39], v[38:39], v[174:175]
	v_pk_add_f32 v[32:33], v[32:33], v[176:177]
	v_pk_add_f32 v[34:35], v[34:35], v[178:179]
	global_store_dwordx4 v228, v[60:63], s[52:53]
	v_add_u32_e32 v144, v220, v233
	global_store_dwordx4 v144, v[56:59], s[52:53]
	global_store_dwordx4 v228, v[52:55], s[52:53] offset:512
	v_add_u32_e32 v144, v220, v233
	global_store_dwordx4 v144, v[44:47], s[52:53] offset:512
	global_store_dwordx4 v229, v[48:51], s[52:53]
	v_add_u32_e32 v144, v221, v233
	global_store_dwordx4 v144, v[40:43], s[52:53]
	global_store_dwordx4 v229, v[36:39], s[52:53] offset:512
	v_add_u32_e32 v144, v221, v233
	global_store_dwordx4 v144, v[32:35], s[52:53] offset:512
	s_waitcnt vmcnt(8)
; #define PG8_WAIT_V(n) asm volatile("s_waitcnt vmcnt(" #n ")" ::: "memory")
; #define PG8_BAR __builtin_amdgcn_s_barrier()
; template <class Epi>
; __device__ __forceinline__ void gemm_phase(LAS unsigned char* lds, const Gemm g, const StaticOrder& S, const Epi& E) {
;     ...
;     PG8_WAIT_V(0);
;     if (wr == 0) PG8_BAR;
;     PG8_BAR;
;     __device__ __forceinline__ void operator()(AccRef acc, const Unit& u, int wr, int wc, int fr, int fq) const {
;     ...
;                         for (int n = 0; n < 2; ++n) bs[m][bj][n] = *(const f32x4*)(base + (size_t)(row0 + ai * 128 + (2 * mh + m) * 16) * D + col0 + bj * 128 + n * 16);
; #pragma unroll
;                 for (int m = 0; m < 2; ++m)
; #pragma unroll
;                     for (int bj = 0; bj < 2; ++bj)
; #pragma unroll
;                         for (int n = 0; n < 2; ++n) *(f32x4*)(out + (size_t)(row0 + ai * 128 + (2 * mh + m) * 16) * D + col0 + bj * 128 + n * 16) = bs[m][bj][n] + sv[bj][n] * (acc[ai][bj][2 * mh + m][n] + bv[bj][n]);
;                 asm volatile("" ::: "memory"); }
	v_mov_b32_e32 v212, v28
	v_mov_b32_e32 v213, v29
	v_mov_b32_e32 v214, v30
	v_mov_b32_e32 v215, v31
	s_nop 0
	v_mov_b32_dpp v28, v24 row_shr:8 row_mask:0xf bank_mask:0xc
	v_mov_b32_dpp v29, v25 row_shr:8 row_mask:0xf bank_mask:0xc
	v_mov_b32_dpp v30, v26 row_shr:8 row_mask:0xf bank_mask:0xc
	v_mov_b32_dpp v31, v27 row_shr:8 row_mask:0xf bank_mask:0xc
	v_mov_b32_dpp v24, v212 row_shl:8 row_mask:0xf bank_mask:0x3
	v_mov_b32_dpp v25, v213 row_shl:8 row_mask:0xf bank_mask:0x3
	v_mov_b32_dpp v26, v214 row_shl:8 row_mask:0xf bank_mask:0x3
	v_mov_b32_dpp v27, v215 row_shl:8 row_mask:0xf bank_mask:0x3
	v_mov_b32_e32 v212, v20
	v_mov_b32_e32 v213, v21
	v_mov_b32_e32 v214, v22
	v_mov_b32_e32 v215, v23
	s_nop 0
	v_mov_b32_dpp v20, v12 row_shr:8 row_mask:0xf bank_mask:0xc
	v_mov_b32_dpp v21, v13 row_shr:8 row_mask:0xf bank_mask:0xc
	v_mov_b32_dpp v22, v14 row_shr:8 row_mask:0xf bank_mask:0xc
	v_mov_b32_dpp v23, v15 row_shr:8 row_mask:0xf bank_mask:0xc
	v_mov_b32_dpp v12, v212 row_shl:8 row_mask:0xf bank_mask:0x3
	v_mov_b32_dpp v13, v213 row_shl:8 row_mask:0xf bank_mask:0x3
	v_mov_b32_dpp v14, v214 row_shl:8 row_mask:0xf bank_mask:0x3
	v_mov_b32_dpp v15, v215 row_shl:8 row_mask:0xf bank_mask:0x3
	v_mov_b32_e32 v212, v16
	v_mov_b32_e32 v213, v17
	v_mov_b32_e32 v214, v18
	v_mov_b32_e32 v215, v19
	s_nop 0
	v_mov_b32_dpp v16, v8 row_shr:8 row_mask:0xf bank_mask:0xc
	v_mov_b32_dpp v17, v9 row_shr:8 row_mask:0xf bank_mask:0xc
	v_mov_b32_dpp v18, v10 row_shr:8 row_mask:0xf bank_mask:0xc
	v_mov_b32_dpp v19, v11 row_shr:8 row_mask:0xf bank_mask:0xc
	v_mov_b32_dpp v8, v212 row_shl:8 row_mask:0xf bank_mask:0x3
	v_mov_b32_dpp v9, v213 row_shl:8 row_mask:0xf bank_mask:0x3
	v_mov_b32_dpp v10, v214 row_shl:8 row_mask:0xf bank_mask:0x3
	v_mov_b32_dpp v11, v215 row_shl:8 row_mask:0xf bank_mask:0x3
	v_mov_b32_e32 v212, v4
	v_mov_b32_e32 v213, v5
	v_mov_b32_e32 v214, v6
	v_mov_b32_e32 v215, v7
	s_nop 0
	v_mov_b32_dpp v4, v0 row_shr:8 row_mask:0xf bank_mask:0xc
	v_mov_b32_dpp v5, v1 row_shr:8 row_mask:0xf bank_mask:0xc
	v_mov_b32_dpp v6, v2 row_shr:8 row_mask:0xf bank_mask:0xc
	v_mov_b32_dpp v7, v3 row_shr:8 row_mask:0xf bank_mask:0xc
	v_mov_b32_dpp v0, v212 row_shl:8 row_mask:0xf bank_mask:0x3
	v_mov_b32_dpp v1, v213 row_shl:8 row_mask:0xf bank_mask:0x3
	v_mov_b32_dpp v2, v214 row_shl:8 row_mask:0xf bank_mask:0x3
	v_mov_b32_dpp v3, v215 row_shl:8 row_mask:0xf bank_mask:0x3
	v_pk_add_f32 v[28:29], v[28:29], v[180:181]
	v_pk_add_f32 v[30:31], v[30:31], v[182:183]
	v_pk_add_f32 v[24:25], v[24:25], v[184:185]
	v_pk_add_f32 v[26:27], v[26:27], v[186:187]
	v_pk_add_f32 v[20:21], v[20:21], v[188:189]
	v_pk_add_f32 v[22:23], v[22:23], v[190:191]
	v_pk_add_f32 v[12:13], v[12:13], v[192:193]
	v_pk_add_f32 v[14:15], v[14:15], v[194:195]
	v_pk_add_f32 v[16:17], v[16:17], v[196:197]
	v_pk_add_f32 v[18:19], v[18:19], v[198:199]
	v_pk_add_f32 v[8:9], v[8:9], v[200:201]
	v_pk_add_f32 v[10:11], v[10:11], v[202:203]
	v_pk_add_f32 v[4:5], v[4:5], v[204:205]
	v_pk_add_f32 v[6:7], v[6:7], v[206:207]
	v_pk_add_f32 v[0:1], v[0:1], v[208:209]
	v_pk_add_f32 v[2:3], v[2:3], v[210:211]
	global_store_dwordx4 v230, v[28:31], s[52:53]
	v_add_u32_e32 v144, v222, v233
	global_store_dwordx4 v144, v[24:27], s[52:53]
	global_store_dwordx4 v230, v[20:23], s[52:53] offset:512
	v_add_u32_e32 v144, v222, v233
	global_store_dwordx4 v144, v[12:15], s[52:53] offset:512
	global_store_dwordx4 v231, v[16:19], s[52:53]
	v_add_u32_e32 v144, v223, v233
	global_store_dwordx4 v144, v[8:11], s[52:53]
	global_store_dwordx4 v231, v[4:7], s[52:53] offset:512
	v_add_u32_e32 v144, v223, v233
	global_store_dwordx4 v144, v[0:3], s[52:53] offset:512
	s_cbranch_vccz .LBB0_1450
	s_waitcnt vmcnt(0)
	s_cmpk_gt_u32 s4, 0xff
	s_cbranch_scc1 .LBB0_1465
	s_barrier

; #define PG8_STAGE(bufoff, gbase, voff) do { _Pragma("unroll") for (int _i = 0; _i < 2; ++_i) \
;         __builtin_amdgcn_global_load_lds((const unsigned*)((const char*)(gbase) + (voff)[_i]), (LAS unsigned*)(lds + (bufoff) + ldsw + _i * 8192), 16, 0, 0); } while (0)
; #define PG8_LDA(dst, b, h) do { _Pragma("unroll") for (int m = 0; m < 4; ++m) _Pragma("unroll") for (int k = 0; k < 2; ++k) dst[m][k] = *(const LAS bf16x8*)(lds + PG8_SA(b, h) + aoff + m * 2048 + k * 1024); } while (0)
; #define PG8_LDB(dst, b, h) do { _Pragma("unroll") for (int n = 0; n < 2; ++n) _Pragma("unroll") for (int k = 0; k < 2; ++k) dst[n][k] = *(const LAS bf16x8*)(lds + PG8_SB(b, h) + boff + n * 2048 + k * 1024); } while (0)
; #define PG8_MMA(ai, bj, At, Bt) do { __builtin_amdgcn_s_setprio(1); _Pragma("unroll") for (int m = 0; m < 4; ++m) _Pragma("unroll") for (int n = 0; n < 2; ++n) _Pragma("unroll") for (int k = 0; k < 2; ++k) \
;         acc[ai][bj][m][n] = __builtin_amdgcn_mfma_f32_16x16x32_bf16(Bt[n][k], At[m][k], acc[ai][bj][m][n], 0, 0, 0); __builtin_amdgcn_s_setprio(0); } while (0)
; #define PG8_WAIT_V(n) asm volatile("s_waitcnt vmcnt(" #n ")" ::: "memory")
; #define PG8_WAIT_L(n) asm volatile("s_waitcnt lgkmcnt(" #n ")" ::: "memory")
; template <class Epi>
; __device__ __forceinline__ void gemm_phase(LAS unsigned char* lds, const Gemm g, const StaticOrder& S, const Epi& E) {
;     ...
;         for (int t = 0; t < nt; t += 2) {
;             const bool last = (t == nt - 2);
;             const char* a1 = cA + (size_t)(t + 1) * kstep;
;             const char* a2 = last ? nA : cA + (size_t)(t + 2) * kstep; const char* b2 = last ? nB : cB + (size_t)(t + 2) * kstep;
;             const char* a3 = a2 + kstep; const char* b3 = b2 + kstep;
;             PG8_LDB(B0, 0, 0); PG8_SCHED; PG8_LDA(At, 0, 0); PG8_STAGE(PG8_SA(1, 1), a1 + hstepA, voffA);
;             PG8_WAIT_L(8); PG8_BAR; PG8_WAIT_L(0); PG8_MMA(0, 0, At, B0); PG8_BAR; PG8_SCHED;
;             PG8_LDB(B1, 0, 1); PG8_STAGE(PG8_SB(0, 0), b2, voffB);
;             PG8_BAR; PG8_WAIT_L(0); PG8_MMA(0, 1, At, B1); PG8_BAR;
;             PG8_LDA(At, 0, 1); PG8_STAGE(PG8_SA(0, 0), a2, voffA);
;             PG8_BAR; PG8_WAIT_L(0); PG8_MMA(1, 0, At, B0); PG8_BAR; PG8_SCHED;
;             PG8_STAGE(PG8_SB(0, 1), b2 + hstepB, voffB);
;             PG8_WAIT_V(6); PG8_BAR; PG8_MMA(1, 1, At, B1); PG8_BAR;
.LBB0_1820:
	ds_read_b128 v[140:143], v149
	ds_read_b128 v[152:155], v149 offset:1024
	ds_read_b128 v[156:159], v149 offset:2048
	ds_read_b128 v[160:163], v149 offset:3072
	s_add_u32 s36, s34, 0xfffc0080
	s_addc_u32 s37, s35, -1
	s_cmp_eq_u32 s70, 12
	s_cselect_b32 s39, s25, s37
	s_cselect_b32 s38, s47, s36
	s_cselect_b32 s37, s23, s63
	s_cselect_b32 s36, s48, s49
	v_lshl_add_u64 v[144:145], s[34:35], 0, v[132:133]
	s_add_i32 m0, s8, 0xc000
	ds_read_b128 v[164:167], v150
	ds_read_b128 v[168:171], v150 offset:1024
	ds_read_b128 v[172:175], v150 offset:2048
	ds_read_b128 v[176:179], v150 offset:3072
	ds_read_b128 v[180:183], v150 offset:4096
	ds_read_b128 v[184:187], v150 offset:5120
	ds_read_b128 v[188:191], v150 offset:6144
	ds_read_b128 v[192:195], v150 offset:7168
	global_load_lds_dwordx4 v[144:145], off
	v_lshl_add_u64 v[144:145], s[34:35], 0, v[134:135]
	s_add_i32 m0, s8, 0xe000
	s_nop 0
	global_load_lds_dwordx4 v[144:145], off
	ds_read_b128 v[196:199], v151
	ds_read_b128 v[200:203], v151 offset:1024
	ds_read_b128 v[204:207], v151 offset:2048
	ds_read_b128 v[208:211], v151 offset:3072
	s_waitcnt lgkmcnt(0)
	s_barrier
	s_setprio 1
	v_mfma_f32_16x16x32_bf16 v[124:127], v[140:143], v[164:167], v[124:127]
	v_mfma_f32_16x16x32_bf16 v[120:123], v[156:159], v[164:167], v[120:123]
	v_mfma_f32_16x16x32_bf16 v[112:115], v[140:143], v[172:175], v[112:115]
	v_mfma_f32_16x16x32_bf16 v[104:107], v[156:159], v[172:175], v[104:107]
	v_mfma_f32_16x16x32_bf16 v[92:95], v[140:143], v[180:183], v[92:95]
	v_mfma_f32_16x16x32_bf16 v[88:91], v[156:159], v[180:183], v[88:91]
	v_mfma_f32_16x16x32_bf16 v[80:83], v[140:143], v[188:191], v[80:83]
	v_mfma_f32_16x16x32_bf16 v[72:75], v[156:159], v[188:191], v[72:75]
	v_mfma_f32_16x16x32_bf16 v[124:127], v[152:155], v[168:171], v[124:127]
	v_mfma_f32_16x16x32_bf16 v[120:123], v[160:163], v[168:171], v[120:123]
	v_mfma_f32_16x16x32_bf16 v[112:115], v[152:155], v[176:179], v[112:115]
	v_mfma_f32_16x16x32_bf16 v[104:107], v[160:163], v[176:179], v[104:107]
	v_mfma_f32_16x16x32_bf16 v[92:95], v[152:155], v[184:187], v[92:95]
	v_mfma_f32_16x16x32_bf16 v[88:91], v[160:163], v[184:187], v[88:91]
	v_mfma_f32_16x16x32_bf16 v[80:83], v[152:155], v[192:195], v[80:83]
	v_mfma_f32_16x16x32_bf16 v[72:75], v[160:163], v[192:195], v[72:75]
	v_mfma_f32_16x16x32_bf16 v[116:119], v[196:199], v[164:167], v[116:119]
	v_mfma_f32_16x16x32_bf16 v[108:111], v[204:207], v[164:167], v[108:111]
	v_mfma_f32_16x16x32_bf16 v[100:103], v[196:199], v[172:175], v[100:103]
	v_mfma_f32_16x16x32_bf16 v[96:99], v[204:207], v[172:175], v[96:99]
	v_mfma_f32_16x16x32_bf16 v[84:87], v[196:199], v[180:183], v[84:87]
	v_mfma_f32_16x16x32_bf16 v[76:79], v[204:207], v[180:183], v[76:79]
	v_mfma_f32_16x16x32_bf16 v[68:71], v[196:199], v[188:191], v[68:71]
	v_mfma_f32_16x16x32_bf16 v[64:67], v[204:207], v[188:191], v[64:67]
	v_mfma_f32_16x16x32_bf16 v[116:119], v[200:203], v[168:171], v[116:119]
	v_mfma_f32_16x16x32_bf16 v[108:111], v[208:211], v[168:171], v[108:111]
	v_mfma_f32_16x16x32_bf16 v[100:103], v[200:203], v[176:179], v[100:103]
	v_mfma_f32_16x16x32_bf16 v[96:99], v[208:211], v[176:179], v[96:99]
	v_mfma_f32_16x16x32_bf16 v[84:87], v[200:203], v[184:187], v[84:87]
	v_mfma_f32_16x16x32_bf16 v[76:79], v[208:211], v[184:187], v[76:79]
	v_mfma_f32_16x16x32_bf16 v[68:71], v[200:203], v[192:195], v[68:71]
	v_mfma_f32_16x16x32_bf16 v[64:67], v[208:211], v[192:195], v[64:67]
	s_setprio 0
	s_barrier
	s_nop 1
	ds_read_b128 v[164:167], v150 offset:16384
	ds_read_b128 v[168:171], v150 offset:17408
	ds_read_b128 v[172:175], v150 offset:18432
	ds_read_b128 v[176:179], v150 offset:19456
	ds_read_b128 v[180:183], v150 offset:20480
	ds_read_b128 v[184:187], v150 offset:21504
	ds_read_b128 v[188:191], v150 offset:22528
	ds_read_b128 v[192:195], v150 offset:23552
	s_add_i32 s71, s44, s7
	v_lshl_add_u64 v[144:145], s[36:37], 0, v[128:129]
	s_mov_b32 m0, s71
	s_nop 0
	global_load_lds_dwordx4 v[144:145], off
	v_lshl_add_u64 v[212:213], s[36:37], 0, v[130:131]
	s_add_i32 m0, s71, 0x2000
	s_nop 0
	global_load_lds_dwordx4 v[212:213], off
	s_mov_b32 m0, s8
	v_lshl_add_u64 v[214:215], s[38:39], 0, v[128:129]
	global_load_lds_dwordx4 v[214:215], off
	v_lshl_add_u64 v[216:217], s[38:39], 0, v[130:131]
	s_mov_b32 m0, s9
	s_nop 0
	global_load_lds_dwordx4 v[216:217], off
	s_add_u32 s72, s36, 0x40000
	s_addc_u32 s73, s37, 0
	s_add_i32 s71, s45, s7
	v_lshl_add_u64 v[254:255], s[72:73], 0, v[128:129]
	s_mov_b32 m0, s71
	s_nop 0
	global_load_lds_dwordx4 v[254:255], off
	v_lshl_add_u64 v[254:255], s[72:73], 0, v[130:131]
	s_add_i32 m0, s71, 0x2000
	s_nop 0
	global_load_lds_dwordx4 v[254:255], off
	s_waitcnt vmcnt(6)
	s_waitcnt lgkmcnt(0)
	s_barrier
; #define PG8_STAGE(bufoff, gbase, voff) do { _Pragma("unroll") for (int _i = 0; _i < 2; ++_i) \
;         __builtin_amdgcn_global_load_lds((const unsigned*)((const char*)(gbase) + (voff)[_i]), (LAS unsigned*)(lds + (bufoff) + ldsw + _i * 8192), 16, 0, 0); } while (0)
; #define PG8_LDA(dst, b, h) do { _Pragma("unroll") for (int m = 0; m < 4; ++m) _Pragma("unroll") for (int k = 0; k < 2; ++k) dst[m][k] = *(const LAS bf16x8*)(lds + PG8_SA(b, h) + aoff + m * 2048 + k * 1024); } while (0)
; #define PG8_LDB(dst, b, h) do { _Pragma("unroll") for (int n = 0; n < 2; ++n) _Pragma("unroll") for (int k = 0; k < 2; ++k) dst[n][k] = *(const LAS bf16x8*)(lds + PG8_SB(b, h) + boff + n * 2048 + k * 1024); } while (0)
; #define PG8_MMA(ai, bj, At, Bt) do { __builtin_amdgcn_s_setprio(1); _Pragma("unroll") for (int m = 0; m < 4; ++m) _Pragma("unroll") for (int n = 0; n < 2; ++n) _Pragma("unroll") for (int k = 0; k < 2; ++k) \
;         acc[ai][bj][m][n] = __builtin_amdgcn_mfma_f32_16x16x32_bf16(Bt[n][k], At[m][k], acc[ai][bj][m][n], 0, 0, 0); __builtin_amdgcn_s_setprio(0); } while (0)
; #define PG8_WAIT_V(n) asm volatile("s_waitcnt vmcnt(" #n ")" ::: "memory")
; #define PG8_WAIT_L(n) asm volatile("s_waitcnt lgkmcnt(" #n ")" ::: "memory")
; #define PG8_BAR __builtin_amdgcn_s_barrier()
; #define PG8_SCHED __builtin_amdgcn_sched_barrier(0)
; template <class Epi>
; __device__ __forceinline__ void gemm_phase(LAS unsigned char* lds, const Gemm g, const StaticOrder& S, const Epi& E) {
;     ...
;             PG8_WAIT_V(6); PG8_BAR; PG8_MMA(1, 1, At, B1); PG8_BAR;
;             PG8_LDB(B0, 1, 0); PG8_SCHED; PG8_LDA(At, 1, 0); PG8_STAGE(PG8_SA(0, 1), a2 + hstepA, voffA);
;             PG8_WAIT_L(8); PG8_BAR; PG8_WAIT_L(0); PG8_MMA(0, 0, At, B0); PG8_BAR; PG8_SCHED;
;             PG8_LDB(B1, 1, 1); PG8_STAGE(PG8_SB(1, 0), b3, voffB);
;             PG8_BAR; PG8_WAIT_L(0); PG8_MMA(0, 1, At, B1); PG8_BAR;
;             PG8_LDA(At, 1, 1); PG8_STAGE(PG8_SA(1, 0), a3, voffA);
	s_setprio 1
	v_mfma_f32_16x16x32_bf16 v[60:63], v[140:143], v[164:167], v[60:63]
	v_mfma_f32_16x16x32_bf16 v[56:59], v[156:159], v[164:167], v[56:59]
	v_mfma_f32_16x16x32_bf16 v[48:51], v[140:143], v[172:175], v[48:51]
	v_mfma_f32_16x16x32_bf16 v[40:43], v[156:159], v[172:175], v[40:43]
	v_mfma_f32_16x16x32_bf16 v[28:31], v[140:143], v[180:183], v[28:31]
	v_mfma_f32_16x16x32_bf16 v[24:27], v[156:159], v[180:183], v[24:27]
	v_mfma_f32_16x16x32_bf16 v[16:19], v[140:143], v[188:191], v[16:19]
	v_mfma_f32_16x16x32_bf16 v[8:11], v[156:159], v[188:191], v[8:11]
	v_mfma_f32_16x16x32_bf16 v[60:63], v[152:155], v[168:171], v[60:63]
	v_mfma_f32_16x16x32_bf16 v[56:59], v[160:163], v[168:171], v[56:59]
	v_mfma_f32_16x16x32_bf16 v[48:51], v[152:155], v[176:179], v[48:51]
	v_mfma_f32_16x16x32_bf16 v[40:43], v[160:163], v[176:179], v[40:43]
	v_mfma_f32_16x16x32_bf16 v[28:31], v[152:155], v[184:187], v[28:31]
	v_mfma_f32_16x16x32_bf16 v[24:27], v[160:163], v[184:187], v[24:27]
	v_mfma_f32_16x16x32_bf16 v[16:19], v[152:155], v[192:195], v[16:19]
	v_mfma_f32_16x16x32_bf16 v[8:11], v[160:163], v[192:195], v[8:11]
	v_mfma_f32_16x16x32_bf16 v[52:55], v[196:199], v[164:167], v[52:55]
	v_mfma_f32_16x16x32_bf16 v[44:47], v[204:207], v[164:167], v[44:47]
	v_mfma_f32_16x16x32_bf16 v[36:39], v[196:199], v[172:175], v[36:39]
	v_mfma_f32_16x16x32_bf16 v[32:35], v[204:207], v[172:175], v[32:35]
	v_mfma_f32_16x16x32_bf16 v[20:23], v[196:199], v[180:183], v[20:23]
	v_mfma_f32_16x16x32_bf16 v[12:15], v[204:207], v[180:183], v[12:15]
	v_mfma_f32_16x16x32_bf16 v[4:7], v[196:199], v[188:191], v[4:7]
	v_mfma_f32_16x16x32_bf16 v[0:3], v[204:207], v[188:191], v[0:3]
	v_mfma_f32_16x16x32_bf16 v[52:55], v[200:203], v[168:171], v[52:55]
	v_mfma_f32_16x16x32_bf16 v[44:47], v[208:211], v[168:171], v[44:47]
	v_mfma_f32_16x16x32_bf16 v[36:39], v[200:203], v[176:179], v[36:39]
	v_mfma_f32_16x16x32_bf16 v[32:35], v[208:211], v[176:179], v[32:35]
	v_mfma_f32_16x16x32_bf16 v[20:23], v[200:203], v[184:187], v[20:23]
	v_mfma_f32_16x16x32_bf16 v[12:15], v[208:211], v[184:187], v[12:15]
	v_mfma_f32_16x16x32_bf16 v[4:7], v[200:203], v[192:195], v[4:7]
	v_mfma_f32_16x16x32_bf16 v[0:3], v[208:211], v[192:195], v[0:3]
	s_setprio 0
	s_add_i32 s71, 0, 0x18000
	v_add_u32_e32 v160, s71, v147
	s_barrier
	ds_read_b128 v[140:143], v160
	ds_read_b128 v[152:155], v160 offset:1024
	ds_read_b128 v[156:159], v160 offset:2048
	ds_read_b128 v[160:163], v160 offset:3072
	s_add_u32 s38, s38, 0x40000
	s_addc_u32 s39, s39, 0
	s_mov_b32 m0, s31
	v_lshl_add_u64 v[196:197], s[38:39], 0, v[128:129]
	ds_read_b128 v[164:167], v150 offset:32768
	ds_read_b128 v[168:171], v150 offset:33792
	ds_read_b128 v[172:175], v150 offset:34816
	ds_read_b128 v[176:179], v150 offset:35840
	ds_read_b128 v[180:183], v150 offset:36864
	ds_read_b128 v[184:187], v150 offset:37888
	ds_read_b128 v[188:191], v150 offset:38912
	ds_read_b128 v[192:195], v150 offset:39936
	global_load_lds_dwordx4 v[196:197], off
	v_lshl_add_u64 v[196:197], s[38:39], 0, v[130:131]
	s_mov_b32 m0, s40
	s_nop 0
	global_load_lds_dwordx4 v[196:197], off
	s_add_i32 s38, 0, 0x1c000
	v_add_u32_e32 v208, s38, v147
	ds_read_b128 v[196:199], v208
	ds_read_b128 v[200:203], v208 offset:1024
	ds_read_b128 v[204:207], v208 offset:2048
	ds_read_b128 v[208:211], v208 offset:3072
	s_waitcnt lgkmcnt(0)
	s_barrier
	s_setprio 1
	v_mfma_f32_16x16x32_bf16 v[124:127], v[140:143], v[164:167], v[124:127]
	v_mfma_f32_16x16x32_bf16 v[120:123], v[156:159], v[164:167], v[120:123]
	v_mfma_f32_16x16x32_bf16 v[112:115], v[140:143], v[172:175], v[112:115]
	v_mfma_f32_16x16x32_bf16 v[104:107], v[156:159], v[172:175], v[104:107]
	v_mfma_f32_16x16x32_bf16 v[92:95], v[140:143], v[180:183], v[92:95]
	v_mfma_f32_16x16x32_bf16 v[88:91], v[156:159], v[180:183], v[88:91]
	v_mfma_f32_16x16x32_bf16 v[80:83], v[140:143], v[188:191], v[80:83]
	v_mfma_f32_16x16x32_bf16 v[72:75], v[156:159], v[188:191], v[72:75]
	v_mfma_f32_16x16x32_bf16 v[124:127], v[152:155], v[168:171], v[124:127]
	v_mfma_f32_16x16x32_bf16 v[120:123], v[160:163], v[168:171], v[120:123]
	v_mfma_f32_16x16x32_bf16 v[112:115], v[152:155], v[176:179], v[112:115]
	v_mfma_f32_16x16x32_bf16 v[104:107], v[160:163], v[176:179], v[104:107]
	v_mfma_f32_16x16x32_bf16 v[92:95], v[152:155], v[184:187], v[92:95]
	v_mfma_f32_16x16x32_bf16 v[88:91], v[160:163], v[184:187], v[88:91]
	v_mfma_f32_16x16x32_bf16 v[80:83], v[152:155], v[192:195], v[80:83]
	v_mfma_f32_16x16x32_bf16 v[72:75], v[160:163], v[192:195], v[72:75]
	v_mfma_f32_16x16x32_bf16 v[116:119], v[196:199], v[164:167], v[116:119]
	v_mfma_f32_16x16x32_bf16 v[108:111], v[204:207], v[164:167], v[108:111]
	v_mfma_f32_16x16x32_bf16 v[100:103], v[196:199], v[172:175], v[100:103]
	v_mfma_f32_16x16x32_bf16 v[96:99], v[204:207], v[172:175], v[96:99]
	v_mfma_f32_16x16x32_bf16 v[84:87], v[196:199], v[180:183], v[84:87]
	v_mfma_f32_16x16x32_bf16 v[76:79], v[204:207], v[180:183], v[76:79]
	v_mfma_f32_16x16x32_bf16 v[68:71], v[196:199], v[188:191], v[68:71]
	v_mfma_f32_16x16x32_bf16 v[64:67], v[204:207], v[188:191], v[64:67]
	v_mfma_f32_16x16x32_bf16 v[116:119], v[200:203], v[168:171], v[116:119]
	v_mfma_f32_16x16x32_bf16 v[108:111], v[208:211], v[168:171], v[108:111]
	v_mfma_f32_16x16x32_bf16 v[100:103], v[200:203], v[176:179], v[100:103]
	v_mfma_f32_16x16x32_bf16 v[96:99], v[208:211], v[176:179], v[96:99]
	v_mfma_f32_16x16x32_bf16 v[84:87], v[200:203], v[184:187], v[84:87]
	v_mfma_f32_16x16x32_bf16 v[76:79], v[208:211], v[184:187], v[76:79]
	v_mfma_f32_16x16x32_bf16 v[68:71], v[200:203], v[192:195], v[68:71]
	v_mfma_f32_16x16x32_bf16 v[64:67], v[208:211], v[192:195], v[64:67]
	s_setprio 0
	s_barrier
; #define PG8_STAGE(bufoff, gbase, voff) do { _Pragma("unroll") for (int _i = 0; _i < 2; ++_i) \
;         __builtin_amdgcn_global_load_lds((const unsigned*)((const char*)(gbase) + (voff)[_i]), (LAS unsigned*)(lds + (bufoff) + ldsw + _i * 8192), 16, 0, 0); } while (0)
; #define PG8_LDA(dst, b, h) do { _Pragma("unroll") for (int m = 0; m < 4; ++m) _Pragma("unroll") for (int k = 0; k < 2; ++k) dst[m][k] = *(const LAS bf16x8*)(lds + PG8_SA(b, h) + aoff + m * 2048 + k * 1024); } while (0)
; #define PG8_BAR __builtin_amdgcn_s_barrier()
; template <class Epi>
; __device__ __forceinline__ void gemm_phase(LAS unsigned char* lds, const Gemm g, const StaticOrder& S, const Epi& E) {
;     ...
;             PG8_LDB(B0, 1, 0); PG8_SCHED; PG8_LDA(At, 1, 0); PG8_STAGE(PG8_SA(0, 1), a2 + hstepA, voffA);
;             PG8_WAIT_L(8); PG8_BAR; PG8_WAIT_L(0); PG8_MMA(0, 0, At, B0); PG8_BAR; PG8_SCHED;
;             PG8_LDB(B1, 1, 1); PG8_STAGE(PG8_SB(1, 0), b3, voffB);
;             PG8_BAR; PG8_WAIT_L(0); PG8_MMA(0, 1, At, B1); PG8_BAR;
;             PG8_LDA(At, 1, 1); PG8_STAGE(PG8_SA(1, 0), a3, voffA);
;             PG8_BAR; PG8_WAIT_L(0); PG8_MMA(1, 0, At, B0); PG8_BAR; PG8_SCHED;
;             PG8_STAGE(PG8_SB(1, 1), b3 + hstepB, voffB);
;             PG8_WAIT_V(6); PG8_BAR; PG8_MMA(1, 1, At, B1); PG8_BAR;
;     __device__ __forceinline__ void operator()(AccRef acc, const Unit& u, int wr, int wc, int fr, int fq) const {
;         const int row0 = u.pm * 256 + wr * 64 + fr, col0 = u.pn * 256 + wc * 32 + 4 * fq;
;         f32x4 sv[2][2], bv[2][2];
; #pragma unroll
;         for (int bj = 0; bj < 2; ++bj)
; #pragma unroll
;             for (int n = 0; n < 2; ++n) {
;                 sv[bj][n] = scale ? *(const f32x4*)(scale + col0 + bj * 128 + n * 16) : (f32x4){1.f, 1.f, 1.f, 1.f};
;                 bv[bj][n] = bias ? *(const f32x4*)(bias + col0 + bj * 128 + n * 16) : (f32x4){0.f, 0.f, 0.f, 0.f}; }
; #pragma unroll
;         for (int ai = 0; ai < 2; ++ai)
; #pragma unroll
;             for (int mh = 0; mh < 2; ++mh) {
;                 f32x4 bs[2][2][2];
; #pragma unroll
;                 for (int m = 0; m < 2; ++m)
; #pragma unroll
;                     for (int bj = 0; bj < 2; ++bj)
; #pragma unroll
;                         for (int n = 0; n < 2; ++n) bs[m][bj][n] = *(const f32x4*)(base + (size_t)(row0 + ai * 128 + (2 * mh + m) * 16) * D + col0 + bj * 128 + n * 16);
	s_nop 1
	ds_read_b128 v[164:167], v150 offset:49152
	ds_read_b128 v[168:171], v150 offset:50176
	ds_read_b128 v[172:175], v150 offset:51200
	ds_read_b128 v[176:179], v150 offset:52224
	ds_read_b128 v[180:183], v150 offset:53248
	ds_read_b128 v[184:187], v150 offset:54272
	ds_read_b128 v[188:191], v150 offset:55296
	ds_read_b128 v[192:195], v150 offset:56320
	s_add_i32 s39, s71, s7
	v_lshl_add_u64 v[254:255], v[144:145], 0, s[12:13]
	s_mov_b32 m0, s39
	s_nop 0
	global_load_lds_dwordx4 v[254:255], off
	v_lshl_add_u64 v[254:255], v[212:213], 0, s[12:13]
	s_add_i32 m0, s39, 0x2000
	s_nop 0
	global_load_lds_dwordx4 v[254:255], off
	s_mov_b32 m0, s42
	v_lshl_add_u64 v[254:255], v[214:215], 0, s[12:13]
	global_load_lds_dwordx4 v[254:255], off
	v_lshl_add_u64 v[144:145], v[216:217], 0, s[12:13]
	s_mov_b32 m0, s43
	s_nop 0
	global_load_lds_dwordx4 v[144:145], off
	s_add_u32 s36, s36, 0x40080
	s_addc_u32 s37, s37, 0
	s_add_i32 s38, s38, s7
	v_lshl_add_u64 v[254:255], s[36:37], 0, v[128:129]
	s_mov_b32 m0, s38
	s_nop 0
	global_load_lds_dwordx4 v[254:255], off
	v_lshl_add_u64 v[254:255], s[36:37], 0, v[130:131]
	s_add_i32 m0, s38, 0x2000
	s_nop 0
	global_load_lds_dwordx4 v[254:255], off
	s_waitcnt vmcnt(6)
	s_waitcnt lgkmcnt(0)
	s_barrier
	s_setprio 1
	v_mfma_f32_16x16x32_bf16 v[60:63], v[140:143], v[164:167], v[60:63]
	v_mfma_f32_16x16x32_bf16 v[56:59], v[156:159], v[164:167], v[56:59]
	v_mfma_f32_16x16x32_bf16 v[48:51], v[140:143], v[172:175], v[48:51]
	v_mfma_f32_16x16x32_bf16 v[40:43], v[156:159], v[172:175], v[40:43]
	v_mfma_f32_16x16x32_bf16 v[28:31], v[140:143], v[180:183], v[28:31]
	v_mfma_f32_16x16x32_bf16 v[24:27], v[156:159], v[180:183], v[24:27]
	v_mfma_f32_16x16x32_bf16 v[16:19], v[140:143], v[188:191], v[16:19]
	v_mfma_f32_16x16x32_bf16 v[8:11], v[156:159], v[188:191], v[8:11]
	v_mfma_f32_16x16x32_bf16 v[60:63], v[152:155], v[168:171], v[60:63]
	v_mfma_f32_16x16x32_bf16 v[56:59], v[160:163], v[168:171], v[56:59]
	v_mfma_f32_16x16x32_bf16 v[48:51], v[152:155], v[176:179], v[48:51]
	v_mfma_f32_16x16x32_bf16 v[40:43], v[160:163], v[176:179], v[40:43]
	v_mfma_f32_16x16x32_bf16 v[28:31], v[152:155], v[184:187], v[28:31]
	v_mfma_f32_16x16x32_bf16 v[24:27], v[160:163], v[184:187], v[24:27]
	v_mfma_f32_16x16x32_bf16 v[16:19], v[152:155], v[192:195], v[16:19]
	v_mfma_f32_16x16x32_bf16 v[8:11], v[160:163], v[192:195], v[8:11]
	v_mfma_f32_16x16x32_bf16 v[52:55], v[196:199], v[164:167], v[52:55]
	v_mfma_f32_16x16x32_bf16 v[44:47], v[204:207], v[164:167], v[44:47]
	v_mfma_f32_16x16x32_bf16 v[36:39], v[196:199], v[172:175], v[36:39]
	v_mfma_f32_16x16x32_bf16 v[32:35], v[204:207], v[172:175], v[32:35]
	v_mfma_f32_16x16x32_bf16 v[20:23], v[196:199], v[180:183], v[20:23]
	v_mfma_f32_16x16x32_bf16 v[12:15], v[204:207], v[180:183], v[12:15]
	v_mfma_f32_16x16x32_bf16 v[4:7], v[196:199], v[188:191], v[4:7]
	v_mfma_f32_16x16x32_bf16 v[0:3], v[204:207], v[188:191], v[0:3]
	v_mfma_f32_16x16x32_bf16 v[52:55], v[200:203], v[168:171], v[52:55]
	v_mfma_f32_16x16x32_bf16 v[44:47], v[208:211], v[168:171], v[44:47]
	v_mfma_f32_16x16x32_bf16 v[36:39], v[200:203], v[176:179], v[36:39]
	v_mfma_f32_16x16x32_bf16 v[32:35], v[208:211], v[176:179], v[32:35]
	v_mfma_f32_16x16x32_bf16 v[20:23], v[200:203], v[184:187], v[20:23]
	v_mfma_f32_16x16x32_bf16 v[12:15], v[208:211], v[184:187], v[12:15]
	v_mfma_f32_16x16x32_bf16 v[4:7], v[200:203], v[192:195], v[4:7]
	v_mfma_f32_16x16x32_bf16 v[0:3], v[208:211], v[192:195], v[0:3]
	s_setprio 0
	s_add_i32 s70, s70, 2
	s_add_u32 s34, s34, 0x100
	s_addc_u32 s35, s35, 0
	s_add_u32 s49, s49, 0x100
	s_addc_u32 s63, s63, 0
	s_cmp_gt_u32 s70, 13
	s_barrier
	s_cbranch_scc0 .LBB0_1820
	v_lshl_or_b32 v144, s46, 8, v148
	v_lshl_add_u32 v145, s30, 8, v146
	v_lshlrev_b32_e32 v144, 2, v144
	v_lshl_add_u32 v145, v145, 12, v144
	v_add_u32_e32 v216, 0x10000, v145
	v_add_u32_e32 v217, 0x20000, v145
	v_add_u32_e32 v218, 0x30000, v145
	v_add_u32_e32 v220, 0x80000, v145
	v_add_u32_e32 v221, 0x90000, v145
	v_add_u32_e32 v222, 0xa0000, v145
	v_add_u32_e32 v223, 0xb0000, v145
	v_and_b32_e32 v235, 8, v146
	v_cmp_ne_u32_e32 vcc, 0, v235
	v_mov_b32_e32 v232, 0xffff8040
	s_nop 0
	v_cndmask_b32_e32 v232, 0, v232, vcc
	v_mov_b32_e32 v233, 64
	v_mov_b32_e32 v235, 0x8000
	v_cndmask_b32_e32 v233, v235, v233, vcc
	v_add_u32_e32 v224, v145, v232
	v_add_u32_e32 v225, v216, v232
	v_add_u32_e32 v226, v217, v232
	v_add_u32_e32 v227, v218, v232
	v_add_u32_e32 v228, v220, v232
	v_add_u32_e32 v229, v221, v232
	v_add_u32_e32 v230, v222, v232
	v_add_u32_e32 v231, v223, v232
	s_and_b64 vcc, exec, s[10:11]
	s_mov_b32 s46, s22
	s_mov_b32 s30, s24
	s_mov_b64 s[36:37], s[28:29]
	s_mov_b64 s[34:35], s[26:27]
	global_load_dwordx4 v[140:143], v224, s[52:53]
	v_add_u32_e32 v144, v145, v233
	global_load_dwordx4 v[152:155], v144, s[52:53]
	global_load_dwordx4 v[156:159], v224, s[52:53] offset:512
	v_add_u32_e32 v144, v145, v233
	global_load_dwordx4 v[160:163], v144, s[52:53] offset:512
	global_load_dwordx4 v[164:167], v225, s[52:53]
	v_add_u32_e32 v144, v216, v233
	global_load_dwordx4 v[168:171], v144, s[52:53]
	global_load_dwordx4 v[172:175], v225, s[52:53] offset:512
	v_add_u32_e32 v144, v216, v233
	global_load_dwordx4 v[176:179], v144, s[52:53] offset:512
	global_load_dwordx4 v[180:183], v226, s[52:53]
	v_add_u32_e32 v144, v217, v233
	global_load_dwordx4 v[184:187], v144, s[52:53]
	global_load_dwordx4 v[188:191], v226, s[52:53] offset:512
	v_add_u32_e32 v144, v217, v233
	global_load_dwordx4 v[192:195], v144, s[52:53] offset:512
	global_load_dwordx4 v[196:199], v227, s[52:53]
	v_add_u32_e32 v144, v218, v233
	global_load_dwordx4 v[200:203], v144, s[52:53]
;     __device__ __forceinline__ void operator()(AccRef acc, const Unit& u, int wr, int wc, int fr, int fq) const {
;     ...
;                         for (int n = 0; n < 2; ++n) bs[m][bj][n] = *(const f32x4*)(base + (size_t)(row0 + ai * 128 + (2 * mh + m) * 16) * D + col0 + bj * 128 + n * 16);
; #pragma unroll
;                 for (int m = 0; m < 2; ++m)
; #pragma unroll
;                     for (int bj = 0; bj < 2; ++bj)
; #pragma unroll
;                         for (int n = 0; n < 2; ++n) *(f32x4*)(out + (size_t)(row0 + ai * 128 + (2 * mh + m) * 16) * D + col0 + bj * 128 + n * 16) = bs[m][bj][n] + sv[bj][n] * (acc[ai][bj][2 * mh + m][n] + bv[bj][n]);
	global_load_dwordx4 v[204:207], v227, s[52:53] offset:512
	v_add_u32_e32 v144, v218, v233
	global_load_dwordx4 v[208:211], v144, s[52:53] offset:512
	v_pk_add_f32 v[124:125], v[124:125], 0 op_sel_hi:[1,0]
	v_pk_add_f32 v[126:127], v[126:127], 0 op_sel_hi:[1,0]
	v_pk_add_f32 v[120:121], v[120:121], 0 op_sel_hi:[1,0]
	v_pk_add_f32 v[122:123], v[122:123], 0 op_sel_hi:[1,0]
	v_pk_add_f32 v[116:117], v[116:117], 0 op_sel_hi:[1,0]
	v_pk_add_f32 v[118:119], v[118:119], 0 op_sel_hi:[1,0]
	v_pk_add_f32 v[108:109], v[108:109], 0 op_sel_hi:[1,0]
	v_pk_add_f32 v[110:111], v[110:111], 0 op_sel_hi:[1,0]
	v_pk_add_f32 v[112:113], v[112:113], 0 op_sel_hi:[1,0]
	v_pk_add_f32 v[114:115], v[114:115], 0 op_sel_hi:[1,0]
	v_pk_add_f32 v[104:105], v[104:105], 0 op_sel_hi:[1,0]
	v_pk_add_f32 v[106:107], v[106:107], 0 op_sel_hi:[1,0]
	v_pk_add_f32 v[100:101], v[100:101], 0 op_sel_hi:[1,0]
	v_pk_add_f32 v[102:103], v[102:103], 0 op_sel_hi:[1,0]
	v_pk_add_f32 v[96:97], v[96:97], 0 op_sel_hi:[1,0]
	v_pk_add_f32 v[98:99], v[98:99], 0 op_sel_hi:[1,0]
	v_pk_add_f32 v[92:93], v[92:93], 0 op_sel_hi:[1,0]
	v_pk_add_f32 v[94:95], v[94:95], 0 op_sel_hi:[1,0]
	v_pk_add_f32 v[88:89], v[88:89], 0 op_sel_hi:[1,0]
	v_pk_add_f32 v[90:91], v[90:91], 0 op_sel_hi:[1,0]
	v_pk_add_f32 v[84:85], v[84:85], 0 op_sel_hi:[1,0]
	v_pk_add_f32 v[86:87], v[86:87], 0 op_sel_hi:[1,0]
	v_pk_add_f32 v[76:77], v[76:77], 0 op_sel_hi:[1,0]
	v_pk_add_f32 v[78:79], v[78:79], 0 op_sel_hi:[1,0]
	v_pk_add_f32 v[80:81], v[80:81], 0 op_sel_hi:[1,0]
	v_pk_add_f32 v[82:83], v[82:83], 0 op_sel_hi:[1,0]
	v_pk_add_f32 v[72:73], v[72:73], 0 op_sel_hi:[1,0]
	v_pk_add_f32 v[74:75], v[74:75], 0 op_sel_hi:[1,0]
	v_pk_add_f32 v[68:69], v[68:69], 0 op_sel_hi:[1,0]
	v_pk_add_f32 v[70:71], v[70:71], 0 op_sel_hi:[1,0]
	v_pk_add_f32 v[64:65], v[64:65], 0 op_sel_hi:[1,0]
	v_pk_add_f32 v[66:67], v[66:67], 0 op_sel_hi:[1,0]
	v_pk_add_f32 v[60:61], v[60:61], 0 op_sel_hi:[1,0]
	v_pk_add_f32 v[62:63], v[62:63], 0 op_sel_hi:[1,0]
	v_pk_add_f32 v[56:57], v[56:57], 0 op_sel_hi:[1,0]
	v_pk_add_f32 v[58:59], v[58:59], 0 op_sel_hi:[1,0]
	v_pk_add_f32 v[52:53], v[52:53], 0 op_sel_hi:[1,0]
	v_pk_add_f32 v[54:55], v[54:55], 0 op_sel_hi:[1,0]
	v_pk_add_f32 v[44:45], v[44:45], 0 op_sel_hi:[1,0]
	v_pk_add_f32 v[46:47], v[46:47], 0 op_sel_hi:[1,0]
	v_pk_add_f32 v[48:49], v[48:49], 0 op_sel_hi:[1,0]
	v_pk_add_f32 v[50:51], v[50:51], 0 op_sel_hi:[1,0]
	v_pk_add_f32 v[40:41], v[40:41], 0 op_sel_hi:[1,0]
	v_pk_add_f32 v[42:43], v[42:43], 0 op_sel_hi:[1,0]
	v_pk_add_f32 v[36:37], v[36:37], 0 op_sel_hi:[1,0]
	v_pk_add_f32 v[38:39], v[38:39], 0 op_sel_hi:[1,0]
	v_pk_add_f32 v[32:33], v[32:33], 0 op_sel_hi:[1,0]
	v_pk_add_f32 v[34:35], v[34:35], 0 op_sel_hi:[1,0]
	v_pk_add_f32 v[28:29], v[28:29], 0 op_sel_hi:[1,0]
	v_pk_add_f32 v[30:31], v[30:31], 0 op_sel_hi:[1,0]
	v_pk_add_f32 v[24:25], v[24:25], 0 op_sel_hi:[1,0]
	v_pk_add_f32 v[26:27], v[26:27], 0 op_sel_hi:[1,0]
	v_pk_add_f32 v[20:21], v[20:21], 0 op_sel_hi:[1,0]
	v_pk_add_f32 v[22:23], v[22:23], 0 op_sel_hi:[1,0]
	v_pk_add_f32 v[12:13], v[12:13], 0 op_sel_hi:[1,0]
	v_pk_add_f32 v[14:15], v[14:15], 0 op_sel_hi:[1,0]
	v_pk_add_f32 v[16:17], v[16:17], 0 op_sel_hi:[1,0]
	v_pk_add_f32 v[18:19], v[18:19], 0 op_sel_hi:[1,0]
	v_pk_add_f32 v[8:9], v[8:9], 0 op_sel_hi:[1,0]
	v_pk_add_f32 v[10:11], v[10:11], 0 op_sel_hi:[1,0]
	v_pk_add_f32 v[4:5], v[4:5], 0 op_sel_hi:[1,0]
	v_pk_add_f32 v[6:7], v[6:7], 0 op_sel_hi:[1,0]
	v_pk_add_f32 v[0:1], v[0:1], 0 op_sel_hi:[1,0]
	v_pk_add_f32 v[2:3], v[2:3], 0 op_sel_hi:[1,0]
	s_waitcnt vmcnt(8)
	v_mov_b32_e32 v212, v124
	v_mov_b32_e32 v213, v125
	v_mov_b32_e32 v214, v126
	v_mov_b32_e32 v215, v127
	s_nop 0
	v_mov_b32_dpp v124, v120 row_shr:8 row_mask:0xf bank_mask:0xc
	v_mov_b32_dpp v125, v121 row_shr:8 row_mask:0xf bank_mask:0xc
	v_mov_b32_dpp v126, v122 row_shr:8 row_mask:0xf bank_mask:0xc
	v_mov_b32_dpp v127, v123 row_shr:8 row_mask:0xf bank_mask:0xc
	v_mov_b32_dpp v120, v212 row_shl:8 row_mask:0xf bank_mask:0x3
	v_mov_b32_dpp v121, v213 row_shl:8 row_mask:0xf bank_mask:0x3
	v_mov_b32_dpp v122, v214 row_shl:8 row_mask:0xf bank_mask:0x3
	v_mov_b32_dpp v123, v215 row_shl:8 row_mask:0xf bank_mask:0x3
	v_mov_b32_e32 v212, v116
	v_mov_b32_e32 v213, v117
	v_mov_b32_e32 v214, v118
	v_mov_b32_e32 v215, v119
	s_nop 0
	v_mov_b32_dpp v116, v108 row_shr:8 row_mask:0xf bank_mask:0xc
	v_mov_b32_dpp v117, v109 row_shr:8 row_mask:0xf bank_mask:0xc
	v_mov_b32_dpp v118, v110 row_shr:8 row_mask:0xf bank_mask:0xc
	v_mov_b32_dpp v119, v111 row_shr:8 row_mask:0xf bank_mask:0xc
	v_mov_b32_dpp v108, v212 row_shl:8 row_mask:0xf bank_mask:0x3
	v_mov_b32_dpp v109, v213 row_shl:8 row_mask:0xf bank_mask:0x3
	v_mov_b32_dpp v110, v214 row_shl:8 row_mask:0xf bank_mask:0x3
	v_mov_b32_dpp v111, v215 row_shl:8 row_mask:0xf bank_mask:0x3
	v_mov_b32_e32 v212, v112
	v_mov_b32_e32 v213, v113
	v_mov_b32_e32 v214, v114
	v_mov_b32_e32 v215, v115
	s_nop 0
	v_mov_b32_dpp v112, v104 row_shr:8 row_mask:0xf bank_mask:0xc
	v_mov_b32_dpp v113, v105 row_shr:8 row_mask:0xf bank_mask:0xc
	v_mov_b32_dpp v114, v106 row_shr:8 row_mask:0xf bank_mask:0xc
	v_mov_b32_dpp v115, v107 row_shr:8 row_mask:0xf bank_mask:0xc
	v_mov_b32_dpp v104, v212 row_shl:8 row_mask:0xf bank_mask:0x3
	v_mov_b32_dpp v105, v213 row_shl:8 row_mask:0xf bank_mask:0x3
	v_mov_b32_dpp v106, v214 row_shl:8 row_mask:0xf bank_mask:0x3
	v_mov_b32_dpp v107, v215 row_shl:8 row_mask:0xf bank_mask:0x3
	v_mov_b32_e32 v212, v100
	v_mov_b32_e32 v213, v101
	v_mov_b32_e32 v214, v102
	v_mov_b32_e32 v215, v103
	s_nop 0
	v_mov_b32_dpp v100, v96 row_shr:8 row_mask:0xf bank_mask:0xc
	v_mov_b32_dpp v101, v97 row_shr:8 row_mask:0xf bank_mask:0xc
;     __device__ __forceinline__ void operator()(AccRef acc, const Unit& u, int wr, int wc, int fr, int fq) const {
;     ...
;                         for (int n = 0; n < 2; ++n) bs[m][bj][n] = *(const f32x4*)(base + (size_t)(row0 + ai * 128 + (2 * mh + m) * 16) * D + col0 + bj * 128 + n * 16);
; #pragma unroll
;                 for (int m = 0; m < 2; ++m)
; #pragma unroll
;                     for (int bj = 0; bj < 2; ++bj)
; #pragma unroll
;                         for (int n = 0; n < 2; ++n) *(f32x4*)(out + (size_t)(row0 + ai * 128 + (2 * mh + m) * 16) * D + col0 + bj * 128 + n * 16) = bs[m][bj][n] + sv[bj][n] * (acc[ai][bj][2 * mh + m][n] + bv[bj][n]);
;                 asm volatile("" ::: "memory"); }
	v_mov_b32_dpp v102, v98 row_shr:8 row_mask:0xf bank_mask:0xc
	v_mov_b32_dpp v103, v99 row_shr:8 row_mask:0xf bank_mask:0xc
	v_mov_b32_dpp v96, v212 row_shl:8 row_mask:0xf bank_mask:0x3
	v_mov_b32_dpp v97, v213 row_shl:8 row_mask:0xf bank_mask:0x3
	v_mov_b32_dpp v98, v214 row_shl:8 row_mask:0xf bank_mask:0x3
	v_mov_b32_dpp v99, v215 row_shl:8 row_mask:0xf bank_mask:0x3
	v_pk_add_f32 v[124:125], v[124:125], v[140:141]
	v_pk_add_f32 v[126:127], v[126:127], v[142:143]
	v_pk_add_f32 v[120:121], v[120:121], v[152:153]
	v_pk_add_f32 v[122:123], v[122:123], v[154:155]
	v_pk_add_f32 v[116:117], v[116:117], v[156:157]
	v_pk_add_f32 v[118:119], v[118:119], v[158:159]
	v_pk_add_f32 v[108:109], v[108:109], v[160:161]
	v_pk_add_f32 v[110:111], v[110:111], v[162:163]
	v_pk_add_f32 v[112:113], v[112:113], v[164:165]
	v_pk_add_f32 v[114:115], v[114:115], v[166:167]
	v_pk_add_f32 v[104:105], v[104:105], v[168:169]
	v_pk_add_f32 v[106:107], v[106:107], v[170:171]
	v_pk_add_f32 v[100:101], v[100:101], v[172:173]
	v_pk_add_f32 v[102:103], v[102:103], v[174:175]
	v_pk_add_f32 v[96:97], v[96:97], v[176:177]
	v_pk_add_f32 v[98:99], v[98:99], v[178:179]
	global_store_dwordx4 v224, v[124:127], s[52:53]
	v_add_u32_e32 v144, v145, v233
	global_store_dwordx4 v144, v[120:123], s[52:53]
	global_store_dwordx4 v224, v[116:119], s[52:53] offset:512
	v_add_u32_e32 v144, v145, v233
	global_store_dwordx4 v144, v[108:111], s[52:53] offset:512
	global_store_dwordx4 v225, v[112:115], s[52:53]
	v_add_u32_e32 v144, v216, v233
	global_store_dwordx4 v144, v[104:107], s[52:53]
	global_store_dwordx4 v225, v[100:103], s[52:53] offset:512
	v_add_u32_e32 v144, v216, v233
	global_store_dwordx4 v144, v[96:99], s[52:53] offset:512
	global_load_dwordx4 v[140:143], v228, s[52:53]
	v_add_u32_e32 v144, v220, v233
	global_load_dwordx4 v[152:155], v144, s[52:53]
	global_load_dwordx4 v[156:159], v228, s[52:53] offset:512
	v_add_u32_e32 v144, v220, v233
	global_load_dwordx4 v[160:163], v144, s[52:53] offset:512
	global_load_dwordx4 v[164:167], v229, s[52:53]
	v_add_u32_e32 v144, v221, v233
	global_load_dwordx4 v[168:171], v144, s[52:53]
	global_load_dwordx4 v[172:175], v229, s[52:53] offset:512
	v_add_u32_e32 v144, v221, v233
	global_load_dwordx4 v[176:179], v144, s[52:53] offset:512
	s_waitcnt vmcnt(16)
	v_mov_b32_e32 v212, v92
	v_mov_b32_e32 v213, v93
	v_mov_b32_e32 v214, v94
	v_mov_b32_e32 v215, v95
	s_nop 0
	v_mov_b32_dpp v92, v88 row_shr:8 row_mask:0xf bank_mask:0xc
	v_mov_b32_dpp v93, v89 row_shr:8 row_mask:0xf bank_mask:0xc
	v_mov_b32_dpp v94, v90 row_shr:8 row_mask:0xf bank_mask:0xc
	v_mov_b32_dpp v95, v91 row_shr:8 row_mask:0xf bank_mask:0xc
	v_mov_b32_dpp v88, v212 row_shl:8 row_mask:0xf bank_mask:0x3
	v_mov_b32_dpp v89, v213 row_shl:8 row_mask:0xf bank_mask:0x3
	v_mov_b32_dpp v90, v214 row_shl:8 row_mask:0xf bank_mask:0x3
	v_mov_b32_dpp v91, v215 row_shl:8 row_mask:0xf bank_mask:0x3
	v_mov_b32_e32 v212, v84
	v_mov_b32_e32 v213, v85
	v_mov_b32_e32 v214, v86
	v_mov_b32_e32 v215, v87
	s_nop 0
	v_mov_b32_dpp v84, v76 row_shr:8 row_mask:0xf bank_mask:0xc
	v_mov_b32_dpp v85, v77 row_shr:8 row_mask:0xf bank_mask:0xc
	v_mov_b32_dpp v86, v78 row_shr:8 row_mask:0xf bank_mask:0xc
	v_mov_b32_dpp v87, v79 row_shr:8 row_mask:0xf bank_mask:0xc
	v_mov_b32_dpp v76, v212 row_shl:8 row_mask:0xf bank_mask:0x3
	v_mov_b32_dpp v77, v213 row_shl:8 row_mask:0xf bank_mask:0x3
	v_mov_b32_dpp v78, v214 row_shl:8 row_mask:0xf bank_mask:0x3
	v_mov_b32_dpp v79, v215 row_shl:8 row_mask:0xf bank_mask:0x3
	v_mov_b32_e32 v212, v80
	v_mov_b32_e32 v213, v81
	v_mov_b32_e32 v214, v82
	v_mov_b32_e32 v215, v83
	s_nop 0
	v_mov_b32_dpp v80, v72 row_shr:8 row_mask:0xf bank_mask:0xc
	v_mov_b32_dpp v81, v73 row_shr:8 row_mask:0xf bank_mask:0xc
	v_mov_b32_dpp v82, v74 row_shr:8 row_mask:0xf bank_mask:0xc
	v_mov_b32_dpp v83, v75 row_shr:8 row_mask:0xf bank_mask:0xc
	v_mov_b32_dpp v72, v212 row_shl:8 row_mask:0xf bank_mask:0x3
	v_mov_b32_dpp v73, v213 row_shl:8 row_mask:0xf bank_mask:0x3
	v_mov_b32_dpp v74, v214 row_shl:8 row_mask:0xf bank_mask:0x3
	v_mov_b32_dpp v75, v215 row_shl:8 row_mask:0xf bank_mask:0x3
	v_mov_b32_e32 v212, v68
	v_mov_b32_e32 v213, v69
	v_mov_b32_e32 v214, v70
	v_mov_b32_e32 v215, v71
	s_nop 0
	v_mov_b32_dpp v68, v64 row_shr:8 row_mask:0xf bank_mask:0xc
	v_mov_b32_dpp v69, v65 row_shr:8 row_mask:0xf bank_mask:0xc
	v_mov_b32_dpp v70, v66 row_shr:8 row_mask:0xf bank_mask:0xc
	v_mov_b32_dpp v71, v67 row_shr:8 row_mask:0xf bank_mask:0xc
	v_mov_b32_dpp v64, v212 row_shl:8 row_mask:0xf bank_mask:0x3
	v_mov_b32_dpp v65, v213 row_shl:8 row_mask:0xf bank_mask:0x3
	v_mov_b32_dpp v66, v214 row_shl:8 row_mask:0xf bank_mask:0x3
	v_mov_b32_dpp v67, v215 row_shl:8 row_mask:0xf bank_mask:0x3
	v_pk_add_f32 v[92:93], v[92:93], v[180:181]
	v_pk_add_f32 v[94:95], v[94:95], v[182:183]
	v_pk_add_f32 v[88:89], v[88:89], v[184:185]
	v_pk_add_f32 v[90:91], v[90:91], v[186:187]
	v_pk_add_f32 v[84:85], v[84:85], v[188:189]
	v_pk_add_f32 v[86:87], v[86:87], v[190:191]
	v_pk_add_f32 v[76:77], v[76:77], v[192:193]
	v_pk_add_f32 v[78:79], v[78:79], v[194:195]
	v_pk_add_f32 v[80:81], v[80:81], v[196:197]
	v_pk_add_f32 v[82:83], v[82:83], v[198:199]
	v_pk_add_f32 v[72:73], v[72:73], v[200:201]
	v_pk_add_f32 v[74:75], v[74:75], v[202:203]
	v_pk_add_f32 v[68:69], v[68:69], v[204:205]
	v_pk_add_f32 v[70:71], v[70:71], v[206:207]
	v_pk_add_f32 v[64:65], v[64:65], v[208:209]
	v_pk_add_f32 v[66:67], v[66:67], v[210:211]
	global_store_dwordx4 v226, v[92:95], s[52:53]
	v_add_u32_e32 v144, v217, v233
	global_store_dwordx4 v144, v[88:91], s[52:53]
	global_store_dwordx4 v226, v[84:87], s[52:53] offset:512
	v_add_u32_e32 v144, v217, v233
	global_store_dwordx4 v144, v[76:79], s[52:53] offset:512
	global_store_dwordx4 v227, v[80:83], s[52:53]
	v_add_u32_e32 v144, v218, v233
	global_store_dwordx4 v144, v[72:75], s[52:53]
	global_store_dwordx4 v227, v[68:71], s[52:53] offset:512
	v_add_u32_e32 v144, v218, v233
	global_store_dwordx4 v144, v[64:67], s[52:53] offset:512
	global_load_dwordx4 v[180:183], v230, s[52:53]
	v_add_u32_e32 v144, v222, v233
	global_load_dwordx4 v[184:187], v144, s[52:53]
	global_load_dwordx4 v[188:191], v230, s[52:53] offset:512
	v_add_u32_e32 v144, v222, v233
	global_load_dwordx4 v[192:195], v144, s[52:53] offset:512
	global_load_dwordx4 v[196:199], v231, s[52:53]
	v_add_u32_e32 v144, v223, v233
	global_load_dwordx4 v[200:203], v144, s[52:53]
	global_load_dwordx4 v[204:207], v231, s[52:53] offset:512
	v_add_u32_e32 v144, v223, v233
	global_load_dwordx4 v[208:211], v144, s[52:53] offset:512
	s_waitcnt vmcnt(16)
;     __device__ __forceinline__ void operator()(AccRef acc, const Unit& u, int wr, int wc, int fr, int fq) const {
;     ...
;                         for (int n = 0; n < 2; ++n) bs[m][bj][n] = *(const f32x4*)(base + (size_t)(row0 + ai * 128 + (2 * mh + m) * 16) * D + col0 + bj * 128 + n * 16);
; #pragma unroll
;                 for (int m = 0; m < 2; ++m)
; #pragma unroll
;                     for (int bj = 0; bj < 2; ++bj)
; #pragma unroll
;                         for (int n = 0; n < 2; ++n) *(f32x4*)(out + (size_t)(row0 + ai * 128 + (2 * mh + m) * 16) * D + col0 + bj * 128 + n * 16) = bs[m][bj][n] + sv[bj][n] * (acc[ai][bj][2 * mh + m][n] + bv[bj][n]);
;                 asm volatile("" ::: "memory"); }
	v_mov_b32_e32 v212, v60
	v_mov_b32_e32 v213, v61
	v_mov_b32_e32 v214, v62
	v_mov_b32_e32 v215, v63
	s_nop 0
	v_mov_b32_dpp v60, v56 row_shr:8 row_mask:0xf bank_mask:0xc
	v_mov_b32_dpp v61, v57 row_shr:8 row_mask:0xf bank_mask:0xc
	v_mov_b32_dpp v62, v58 row_shr:8 row_mask:0xf bank_mask:0xc
	v_mov_b32_dpp v63, v59 row_shr:8 row_mask:0xf bank_mask:0xc
	v_mov_b32_dpp v56, v212 row_shl:8 row_mask:0xf bank_mask:0x3
	v_mov_b32_dpp v57, v213 row_shl:8 row_mask:0xf bank_mask:0x3
	v_mov_b32_dpp v58, v214 row_shl:8 row_mask:0xf bank_mask:0x3
	v_mov_b32_dpp v59, v215 row_shl:8 row_mask:0xf bank_mask:0x3
	v_mov_b32_e32 v212, v52
	v_mov_b32_e32 v213, v53
	v_mov_b32_e32 v214, v54
	v_mov_b32_e32 v215, v55
	s_nop 0
	v_mov_b32_dpp v52, v44 row_shr:8 row_mask:0xf bank_mask:0xc
	v_mov_b32_dpp v53, v45 row_shr:8 row_mask:0xf bank_mask:0xc
	v_mov_b32_dpp v54, v46 row_shr:8 row_mask:0xf bank_mask:0xc
	v_mov_b32_dpp v55, v47 row_shr:8 row_mask:0xf bank_mask:0xc
	v_mov_b32_dpp v44, v212 row_shl:8 row_mask:0xf bank_mask:0x3
	v_mov_b32_dpp v45, v213 row_shl:8 row_mask:0xf bank_mask:0x3
	v_mov_b32_dpp v46, v214 row_shl:8 row_mask:0xf bank_mask:0x3
	v_mov_b32_dpp v47, v215 row_shl:8 row_mask:0xf bank_mask:0x3
	v_mov_b32_e32 v212, v48
	v_mov_b32_e32 v213, v49
	v_mov_b32_e32 v214, v50
	v_mov_b32_e32 v215, v51
	s_nop 0
	v_mov_b32_dpp v48, v40 row_shr:8 row_mask:0xf bank_mask:0xc
	v_mov_b32_dpp v49, v41 row_shr:8 row_mask:0xf bank_mask:0xc
	v_mov_b32_dpp v50, v42 row_shr:8 row_mask:0xf bank_mask:0xc
	v_mov_b32_dpp v51, v43 row_shr:8 row_mask:0xf bank_mask:0xc
	v_mov_b32_dpp v40, v212 row_shl:8 row_mask:0xf bank_mask:0x3
	v_mov_b32_dpp v41, v213 row_shl:8 row_mask:0xf bank_mask:0x3
	v_mov_b32_dpp v42, v214 row_shl:8 row_mask:0xf bank_mask:0x3
	v_mov_b32_dpp v43, v215 row_shl:8 row_mask:0xf bank_mask:0x3
	v_mov_b32_e32 v212, v36
	v_mov_b32_e32 v213, v37
	v_mov_b32_e32 v214, v38
	v_mov_b32_e32 v215, v39
	s_nop 0
	v_mov_b32_dpp v36, v32 row_shr:8 row_mask:0xf bank_mask:0xc
	v_mov_b32_dpp v37, v33 row_shr:8 row_mask:0xf bank_mask:0xc
	v_mov_b32_dpp v38, v34 row_shr:8 row_mask:0xf bank_mask:0xc
	v_mov_b32_dpp v39, v35 row_shr:8 row_mask:0xf bank_mask:0xc
	v_mov_b32_dpp v32, v212 row_shl:8 row_mask:0xf bank_mask:0x3
	v_mov_b32_dpp v33, v213 row_shl:8 row_mask:0xf bank_mask:0x3
	v_mov_b32_dpp v34, v214 row_shl:8 row_mask:0xf bank_mask:0x3
	v_mov_b32_dpp v35, v215 row_shl:8 row_mask:0xf bank_mask:0x3
	v_pk_add_f32 v[60:61], v[60:61], v[140:141]
	v_pk_add_f32 v[62:63], v[62:63], v[142:143]
	v_pk_add_f32 v[56:57], v[56:57], v[152:153]
	v_pk_add_f32 v[58:59], v[58:59], v[154:155]
	v_pk_add_f32 v[52:53], v[52:53], v[156:157]
	v_pk_add_f32 v[54:55], v[54:55], v[158:159]
	v_pk_add_f32 v[44:45], v[44:45], v[160:161]
	v_pk_add_f32 v[46:47], v[46:47], v[162:163]
	v_pk_add_f32 v[48:49], v[48:49], v[164:165]
	v_pk_add_f32 v[50:51], v[50:51], v[166:167]
	v_pk_add_f32 v[40:41], v[40:41], v[168:169]
	v_pk_add_f32 v[42:43], v[42:43], v[170:171]
	v_pk_add_f32 v[36:37], v[36:37], v[172:173]
	v_pk_add_f32 v[38:39], v[38:39], v[174:175]
	v_pk_add_f32 v[32:33], v[32:33], v[176:177]
	v_pk_add_f32 v[34:35], v[34:35], v[178:179]
	global_store_dwordx4 v228, v[60:63], s[52:53]
	v_add_u32_e32 v144, v220, v233
	global_store_dwordx4 v144, v[56:59], s[52:53]
	global_store_dwordx4 v228, v[52:55], s[52:53] offset:512
	v_add_u32_e32 v144, v220, v233
	global_store_dwordx4 v144, v[44:47], s[52:53] offset:512
	global_store_dwordx4 v229, v[48:51], s[52:53]
	v_add_u32_e32 v144, v221, v233
	global_store_dwordx4 v144, v[40:43], s[52:53]
	global_store_dwordx4 v229, v[36:39], s[52:53] offset:512
	v_add_u32_e32 v144, v221, v233
	global_store_dwordx4 v144, v[32:35], s[52:53] offset:512
	s_waitcnt vmcnt(8)
; #define PG8_WAIT_V(n) asm volatile("s_waitcnt vmcnt(" #n ")" ::: "memory")
; #define PG8_BAR __builtin_amdgcn_s_barrier()
; template <class Epi>
; __device__ __forceinline__ void gemm_phase(LAS unsigned char* lds, const Gemm g, const StaticOrder& S, const Epi& E) {
;     ...
;     PG8_WAIT_V(0);
;     if (wr == 0) PG8_BAR;
;     PG8_BAR;
;     __device__ __forceinline__ void operator()(AccRef acc, const Unit& u, int wr, int wc, int fr, int fq) const {
;     ...
;                         for (int n = 0; n < 2; ++n) bs[m][bj][n] = *(const f32x4*)(base + (size_t)(row0 + ai * 128 + (2 * mh + m) * 16) * D + col0 + bj * 128 + n * 16);
; #pragma unroll
;                 for (int m = 0; m < 2; ++m)
; #pragma unroll
;                     for (int bj = 0; bj < 2; ++bj)
; #pragma unroll
;                         for (int n = 0; n < 2; ++n) *(f32x4*)(out + (size_t)(row0 + ai * 128 + (2 * mh + m) * 16) * D + col0 + bj * 128 + n * 16) = bs[m][bj][n] + sv[bj][n] * (acc[ai][bj][2 * mh + m][n] + bv[bj][n]);
;                 asm volatile("" ::: "memory"); }
	v_mov_b32_e32 v212, v28
	v_mov_b32_e32 v213, v29
	v_mov_b32_e32 v214, v30
	v_mov_b32_e32 v215, v31
	s_nop 0
	v_mov_b32_dpp v28, v24 row_shr:8 row_mask:0xf bank_mask:0xc
	v_mov_b32_dpp v29, v25 row_shr:8 row_mask:0xf bank_mask:0xc
	v_mov_b32_dpp v30, v26 row_shr:8 row_mask:0xf bank_mask:0xc
	v_mov_b32_dpp v31, v27 row_shr:8 row_mask:0xf bank_mask:0xc
	v_mov_b32_dpp v24, v212 row_shl:8 row_mask:0xf bank_mask:0x3
	v_mov_b32_dpp v25, v213 row_shl:8 row_mask:0xf bank_mask:0x3
	v_mov_b32_dpp v26, v214 row_shl:8 row_mask:0xf bank_mask:0x3
	v_mov_b32_dpp v27, v215 row_shl:8 row_mask:0xf bank_mask:0x3
	v_mov_b32_e32 v212, v20
	v_mov_b32_e32 v213, v21
	v_mov_b32_e32 v214, v22
	v_mov_b32_e32 v215, v23
	s_nop 0
	v_mov_b32_dpp v20, v12 row_shr:8 row_mask:0xf bank_mask:0xc
	v_mov_b32_dpp v21, v13 row_shr:8 row_mask:0xf bank_mask:0xc
	v_mov_b32_dpp v22, v14 row_shr:8 row_mask:0xf bank_mask:0xc
	v_mov_b32_dpp v23, v15 row_shr:8 row_mask:0xf bank_mask:0xc
	v_mov_b32_dpp v12, v212 row_shl:8 row_mask:0xf bank_mask:0x3
	v_mov_b32_dpp v13, v213 row_shl:8 row_mask:0xf bank_mask:0x3
	v_mov_b32_dpp v14, v214 row_shl:8 row_mask:0xf bank_mask:0x3
	v_mov_b32_dpp v15, v215 row_shl:8 row_mask:0xf bank_mask:0x3
	v_mov_b32_e32 v212, v16
	v_mov_b32_e32 v213, v17
	v_mov_b32_e32 v214, v18
	v_mov_b32_e32 v215, v19
	s_nop 0
	v_mov_b32_dpp v16, v8 row_shr:8 row_mask:0xf bank_mask:0xc
	v_mov_b32_dpp v17, v9 row_shr:8 row_mask:0xf bank_mask:0xc
	v_mov_b32_dpp v18, v10 row_shr:8 row_mask:0xf bank_mask:0xc
	v_mov_b32_dpp v19, v11 row_shr:8 row_mask:0xf bank_mask:0xc
	v_mov_b32_dpp v8, v212 row_shl:8 row_mask:0xf bank_mask:0x3
	v_mov_b32_dpp v9, v213 row_shl:8 row_mask:0xf bank_mask:0x3
	v_mov_b32_dpp v10, v214 row_shl:8 row_mask:0xf bank_mask:0x3
	v_mov_b32_dpp v11, v215 row_shl:8 row_mask:0xf bank_mask:0x3
	v_mov_b32_e32 v212, v4
	v_mov_b32_e32 v213, v5
	v_mov_b32_e32 v214, v6
	v_mov_b32_e32 v215, v7
	s_nop 0
	v_mov_b32_dpp v4, v0 row_shr:8 row_mask:0xf bank_mask:0xc
	v_mov_b32_dpp v5, v1 row_shr:8 row_mask:0xf bank_mask:0xc
	v_mov_b32_dpp v6, v2 row_shr:8 row_mask:0xf bank_mask:0xc
	v_mov_b32_dpp v7, v3 row_shr:8 row_mask:0xf bank_mask:0xc
	v_mov_b32_dpp v0, v212 row_shl:8 row_mask:0xf bank_mask:0x3
	v_mov_b32_dpp v1, v213 row_shl:8 row_mask:0xf bank_mask:0x3
	v_mov_b32_dpp v2, v214 row_shl:8 row_mask:0xf bank_mask:0x3
	v_mov_b32_dpp v3, v215 row_shl:8 row_mask:0xf bank_mask:0x3
	v_pk_add_f32 v[28:29], v[28:29], v[180:181]
	v_pk_add_f32 v[30:31], v[30:31], v[182:183]
	v_pk_add_f32 v[24:25], v[24:25], v[184:185]
	v_pk_add_f32 v[26:27], v[26:27], v[186:187]
	v_pk_add_f32 v[20:21], v[20:21], v[188:189]
	v_pk_add_f32 v[22:23], v[22:23], v[190:191]
	v_pk_add_f32 v[12:13], v[12:13], v[192:193]
	v_pk_add_f32 v[14:15], v[14:15], v[194:195]
	v_pk_add_f32 v[16:17], v[16:17], v[196:197]
	v_pk_add_f32 v[18:19], v[18:19], v[198:199]
	v_pk_add_f32 v[8:9], v[8:9], v[200:201]
	v_pk_add_f32 v[10:11], v[10:11], v[202:203]
	v_pk_add_f32 v[4:5], v[4:5], v[204:205]
	v_pk_add_f32 v[6:7], v[6:7], v[206:207]
	v_pk_add_f32 v[0:1], v[0:1], v[208:209]
	v_pk_add_f32 v[2:3], v[2:3], v[210:211]
	global_store_dwordx4 v230, v[28:31], s[52:53]
	v_add_u32_e32 v144, v222, v233
	global_store_dwordx4 v144, v[24:27], s[52:53]
	global_store_dwordx4 v230, v[20:23], s[52:53] offset:512
	v_add_u32_e32 v144, v222, v233
	global_store_dwordx4 v144, v[12:15], s[52:53] offset:512
	global_store_dwordx4 v231, v[16:19], s[52:53]
	v_add_u32_e32 v144, v223, v233
	global_store_dwordx4 v144, v[8:11], s[52:53]
	global_store_dwordx4 v231, v[4:7], s[52:53] offset:512
	v_add_u32_e32 v144, v223, v233
	global_store_dwordx4 v144, v[0:3], s[52:53] offset:512
	s_cbranch_vccz .LBB0_1813
	s_waitcnt vmcnt(0)
	s_cmpk_gt_u32 s4, 0xff
	s_cbranch_scc1 .LBB0_1824
	s_barrier

; #define PG8_STAGE(bufoff, gbase, voff) do { _Pragma("unroll") for (int _i = 0; _i < 2; ++_i) \
;         __builtin_amdgcn_global_load_lds((const unsigned*)((const char*)(gbase) + (voff)[_i]), (LAS unsigned*)(lds + (bufoff) + ldsw + _i * 8192), 16, 0, 0); } while (0)
; #define PG8_LDA(dst, b, h) do { _Pragma("unroll") for (int m = 0; m < 4; ++m) _Pragma("unroll") for (int k = 0; k < 2; ++k) dst[m][k] = *(const LAS bf16x8*)(lds + PG8_SA(b, h) + aoff + m * 2048 + k * 1024); } while (0)
; #define PG8_LDB(dst, b, h) do { _Pragma("unroll") for (int n = 0; n < 2; ++n) _Pragma("unroll") for (int k = 0; k < 2; ++k) dst[n][k] = *(const LAS bf16x8*)(lds + PG8_SB(b, h) + boff + n * 2048 + k * 1024); } while (0)
; #define PG8_MMA(ai, bj, At, Bt) do { __builtin_amdgcn_s_setprio(1); _Pragma("unroll") for (int m = 0; m < 4; ++m) _Pragma("unroll") for (int n = 0; n < 2; ++n) _Pragma("unroll") for (int k = 0; k < 2; ++k) \
;         acc[ai][bj][m][n] = __builtin_amdgcn_mfma_f32_16x16x32_bf16(Bt[n][k], At[m][k], acc[ai][bj][m][n], 0, 0, 0); __builtin_amdgcn_s_setprio(0); } while (0)
; #define PG8_WAIT_V(n) asm volatile("s_waitcnt vmcnt(" #n ")" ::: "memory")
; #define PG8_WAIT_L(n) asm volatile("s_waitcnt lgkmcnt(" #n ")" ::: "memory")
; template <class Epi>
; __device__ __forceinline__ void gemm_phase(LAS unsigned char* lds, const Gemm g, const StaticOrder& S, const Epi& E) {
;     ...
;         for (int t = 0; t < nt; t += 2) {
;             const bool last = (t == nt - 2);
;             const char* a1 = cA + (size_t)(t + 1) * kstep;
;             const char* a2 = last ? nA : cA + (size_t)(t + 2) * kstep; const char* b2 = last ? nB : cB + (size_t)(t + 2) * kstep;
;             const char* a3 = a2 + kstep; const char* b3 = b2 + kstep;
;             PG8_LDB(B0, 0, 0); PG8_SCHED; PG8_LDA(At, 0, 0); PG8_STAGE(PG8_SA(1, 1), a1 + hstepA, voffA);
;             PG8_WAIT_L(8); PG8_BAR; PG8_WAIT_L(0); PG8_MMA(0, 0, At, B0); PG8_BAR; PG8_SCHED;
;             PG8_LDB(B1, 0, 1); PG8_STAGE(PG8_SB(0, 0), b2, voffB);
;             PG8_BAR; PG8_WAIT_L(0); PG8_MMA(0, 1, At, B1); PG8_BAR;
;             PG8_LDA(At, 0, 1); PG8_STAGE(PG8_SA(0, 0), a2, voffA);
;             PG8_BAR; PG8_WAIT_L(0); PG8_MMA(1, 0, At, B0); PG8_BAR; PG8_SCHED;
;             PG8_STAGE(PG8_SB(0, 1), b2 + hstepB, voffB);
;             PG8_WAIT_V(6); PG8_BAR; PG8_MMA(1, 1, At, B1); PG8_BAR;
.LBB0_2042:
	ds_read_b128 v[140:143], v149
	ds_read_b128 v[152:155], v149 offset:1024
	ds_read_b128 v[156:159], v149 offset:2048
	ds_read_b128 v[160:163], v149 offset:3072
	s_add_u32 s20, s18, 0x100
	s_addc_u32 s21, s19, 0
	s_cmp_eq_u32 s46, 40
	s_cselect_b32 s25, s5, s21
	s_cselect_b32 s24, s4, s20
	s_cselect_b32 s23, s7, s45
	s_cselect_b32 s22, s6, s44
	v_lshl_add_u64 v[144:145], s[18:19], 0, v[132:133]
	s_add_i32 m0, s30, 0xc000
	ds_read_b128 v[164:167], v150
	ds_read_b128 v[168:171], v150 offset:1024
	ds_read_b128 v[172:175], v150 offset:2048
	ds_read_b128 v[176:179], v150 offset:3072
	ds_read_b128 v[180:183], v150 offset:4096
	ds_read_b128 v[184:187], v150 offset:5120
	ds_read_b128 v[188:191], v150 offset:6144
	ds_read_b128 v[192:195], v150 offset:7168
	global_load_lds_dwordx4 v[144:145], off
	v_lshl_add_u64 v[144:145], s[18:19], 0, v[134:135]
	s_add_i32 m0, s30, 0xe000
	s_nop 0
	global_load_lds_dwordx4 v[144:145], off
	ds_read_b128 v[196:199], v151
	ds_read_b128 v[200:203], v151 offset:1024
	ds_read_b128 v[204:207], v151 offset:2048
	ds_read_b128 v[208:211], v151 offset:3072
	s_waitcnt lgkmcnt(0)
	s_barrier
	s_setprio 1
	v_mfma_f32_16x16x32_bf16 v[124:127], v[140:143], v[164:167], v[124:127]
	v_mfma_f32_16x16x32_bf16 v[120:123], v[156:159], v[164:167], v[120:123]
	v_mfma_f32_16x16x32_bf16 v[112:115], v[140:143], v[172:175], v[112:115]
	v_mfma_f32_16x16x32_bf16 v[104:107], v[156:159], v[172:175], v[104:107]
	v_mfma_f32_16x16x32_bf16 v[92:95], v[140:143], v[180:183], v[92:95]
	v_mfma_f32_16x16x32_bf16 v[88:91], v[156:159], v[180:183], v[88:91]
	v_mfma_f32_16x16x32_bf16 v[80:83], v[140:143], v[188:191], v[80:83]
	v_mfma_f32_16x16x32_bf16 v[72:75], v[156:159], v[188:191], v[72:75]
	v_mfma_f32_16x16x32_bf16 v[124:127], v[152:155], v[168:171], v[124:127]
	v_mfma_f32_16x16x32_bf16 v[120:123], v[160:163], v[168:171], v[120:123]
	v_mfma_f32_16x16x32_bf16 v[112:115], v[152:155], v[176:179], v[112:115]
	v_mfma_f32_16x16x32_bf16 v[104:107], v[160:163], v[176:179], v[104:107]
	v_mfma_f32_16x16x32_bf16 v[92:95], v[152:155], v[184:187], v[92:95]
	v_mfma_f32_16x16x32_bf16 v[88:91], v[160:163], v[184:187], v[88:91]
	v_mfma_f32_16x16x32_bf16 v[80:83], v[152:155], v[192:195], v[80:83]
	v_mfma_f32_16x16x32_bf16 v[72:75], v[160:163], v[192:195], v[72:75]
	v_mfma_f32_16x16x32_bf16 v[116:119], v[196:199], v[164:167], v[116:119]
	v_mfma_f32_16x16x32_bf16 v[108:111], v[204:207], v[164:167], v[108:111]
	v_mfma_f32_16x16x32_bf16 v[100:103], v[196:199], v[172:175], v[100:103]
	v_mfma_f32_16x16x32_bf16 v[96:99], v[204:207], v[172:175], v[96:99]
	v_mfma_f32_16x16x32_bf16 v[84:87], v[196:199], v[180:183], v[84:87]
	v_mfma_f32_16x16x32_bf16 v[76:79], v[204:207], v[180:183], v[76:79]
	v_mfma_f32_16x16x32_bf16 v[68:71], v[196:199], v[188:191], v[68:71]
	v_mfma_f32_16x16x32_bf16 v[64:67], v[204:207], v[188:191], v[64:67]
	v_mfma_f32_16x16x32_bf16 v[116:119], v[200:203], v[168:171], v[116:119]
	v_mfma_f32_16x16x32_bf16 v[108:111], v[208:211], v[168:171], v[108:111]
	v_mfma_f32_16x16x32_bf16 v[100:103], v[200:203], v[176:179], v[100:103]
	v_mfma_f32_16x16x32_bf16 v[96:99], v[208:211], v[176:179], v[96:99]
	v_mfma_f32_16x16x32_bf16 v[84:87], v[200:203], v[184:187], v[84:87]
	v_mfma_f32_16x16x32_bf16 v[76:79], v[208:211], v[184:187], v[76:79]
	v_mfma_f32_16x16x32_bf16 v[68:71], v[200:203], v[192:195], v[68:71]
	v_mfma_f32_16x16x32_bf16 v[64:67], v[208:211], v[192:195], v[64:67]
	s_setprio 0
	s_barrier
	s_nop 1
	ds_read_b128 v[164:167], v150 offset:16384
	ds_read_b128 v[168:171], v150 offset:17408
	ds_read_b128 v[172:175], v150 offset:18432
	ds_read_b128 v[176:179], v150 offset:19456
	ds_read_b128 v[180:183], v150 offset:20480
	ds_read_b128 v[184:187], v150 offset:21504
	ds_read_b128 v[188:191], v150 offset:22528
	ds_read_b128 v[192:195], v150 offset:23552
	s_add_i32 s18, s38, s29
	v_lshl_add_u64 v[144:145], s[22:23], 0, v[128:129]
	s_mov_b32 m0, s18
	s_nop 0
	global_load_lds_dwordx4 v[144:145], off
	v_lshl_add_u64 v[212:213], s[22:23], 0, v[130:131]
	s_add_i32 m0, s18, 0x2000
	s_nop 0
	global_load_lds_dwordx4 v[212:213], off
	s_mov_b32 m0, s30
	v_lshl_add_u64 v[214:215], s[24:25], 0, v[128:129]
	global_load_lds_dwordx4 v[214:215], off
	v_lshl_add_u64 v[216:217], s[24:25], 0, v[130:131]
	s_mov_b32 m0, s31
	s_nop 0
	global_load_lds_dwordx4 v[216:217], off
	s_add_u32 s18, s22, 0xb0000
	s_addc_u32 s19, s23, 0
	s_add_i32 s47, s39, s29
	v_lshl_add_u64 v[254:255], s[18:19], 0, v[128:129]
	s_mov_b32 m0, s47
	s_nop 0
	global_load_lds_dwordx4 v[254:255], off
	v_lshl_add_u64 v[254:255], s[18:19], 0, v[130:131]
	s_add_i32 m0, s47, 0x2000
	s_nop 0
	global_load_lds_dwordx4 v[254:255], off
	s_waitcnt vmcnt(6)
	s_waitcnt lgkmcnt(0)
	s_barrier
; #define PG8_STAGE(bufoff, gbase, voff) do { _Pragma("unroll") for (int _i = 0; _i < 2; ++_i) \
;         __builtin_amdgcn_global_load_lds((const unsigned*)((const char*)(gbase) + (voff)[_i]), (LAS unsigned*)(lds + (bufoff) + ldsw + _i * 8192), 16, 0, 0); } while (0)
; #define PG8_LDA(dst, b, h) do { _Pragma("unroll") for (int m = 0; m < 4; ++m) _Pragma("unroll") for (int k = 0; k < 2; ++k) dst[m][k] = *(const LAS bf16x8*)(lds + PG8_SA(b, h) + aoff + m * 2048 + k * 1024); } while (0)
; #define PG8_LDB(dst, b, h) do { _Pragma("unroll") for (int n = 0; n < 2; ++n) _Pragma("unroll") for (int k = 0; k < 2; ++k) dst[n][k] = *(const LAS bf16x8*)(lds + PG8_SB(b, h) + boff + n * 2048 + k * 1024); } while (0)
; #define PG8_MMA(ai, bj, At, Bt) do { __builtin_amdgcn_s_setprio(1); _Pragma("unroll") for (int m = 0; m < 4; ++m) _Pragma("unroll") for (int n = 0; n < 2; ++n) _Pragma("unroll") for (int k = 0; k < 2; ++k) \
;         acc[ai][bj][m][n] = __builtin_amdgcn_mfma_f32_16x16x32_bf16(Bt[n][k], At[m][k], acc[ai][bj][m][n], 0, 0, 0); __builtin_amdgcn_s_setprio(0); } while (0)
; #define PG8_WAIT_V(n) asm volatile("s_waitcnt vmcnt(" #n ")" ::: "memory")
; #define PG8_WAIT_L(n) asm volatile("s_waitcnt lgkmcnt(" #n ")" ::: "memory")
; #define PG8_BAR __builtin_amdgcn_s_barrier()
; #define PG8_SCHED __builtin_amdgcn_sched_barrier(0)
; template <class Epi>
; __device__ __forceinline__ void gemm_phase(LAS unsigned char* lds, const Gemm g, const StaticOrder& S, const Epi& E) {
;     ...
;             PG8_WAIT_V(6); PG8_BAR; PG8_MMA(1, 1, At, B1); PG8_BAR;
;             PG8_LDB(B0, 1, 0); PG8_SCHED; PG8_LDA(At, 1, 0); PG8_STAGE(PG8_SA(0, 1), a2 + hstepA, voffA);
;             PG8_WAIT_L(8); PG8_BAR; PG8_WAIT_L(0); PG8_MMA(0, 0, At, B0); PG8_BAR; PG8_SCHED;
;             PG8_LDB(B1, 1, 1); PG8_STAGE(PG8_SB(1, 0), b3, voffB);
;             PG8_BAR; PG8_WAIT_L(0); PG8_MMA(0, 1, At, B1); PG8_BAR;
;             PG8_LDA(At, 1, 1); PG8_STAGE(PG8_SA(1, 0), a3, voffA);
	s_setprio 1
	v_mfma_f32_16x16x32_bf16 v[60:63], v[140:143], v[164:167], v[60:63]
	v_mfma_f32_16x16x32_bf16 v[56:59], v[156:159], v[164:167], v[56:59]
	v_mfma_f32_16x16x32_bf16 v[48:51], v[140:143], v[172:175], v[48:51]
	v_mfma_f32_16x16x32_bf16 v[40:43], v[156:159], v[172:175], v[40:43]
	v_mfma_f32_16x16x32_bf16 v[28:31], v[140:143], v[180:183], v[28:31]
	v_mfma_f32_16x16x32_bf16 v[24:27], v[156:159], v[180:183], v[24:27]
	v_mfma_f32_16x16x32_bf16 v[16:19], v[140:143], v[188:191], v[16:19]
	v_mfma_f32_16x16x32_bf16 v[8:11], v[156:159], v[188:191], v[8:11]
	v_mfma_f32_16x16x32_bf16 v[60:63], v[152:155], v[168:171], v[60:63]
	v_mfma_f32_16x16x32_bf16 v[56:59], v[160:163], v[168:171], v[56:59]
	v_mfma_f32_16x16x32_bf16 v[48:51], v[152:155], v[176:179], v[48:51]
	v_mfma_f32_16x16x32_bf16 v[40:43], v[160:163], v[176:179], v[40:43]
	v_mfma_f32_16x16x32_bf16 v[28:31], v[152:155], v[184:187], v[28:31]
	v_mfma_f32_16x16x32_bf16 v[24:27], v[160:163], v[184:187], v[24:27]
	v_mfma_f32_16x16x32_bf16 v[16:19], v[152:155], v[192:195], v[16:19]
	v_mfma_f32_16x16x32_bf16 v[8:11], v[160:163], v[192:195], v[8:11]
	v_mfma_f32_16x16x32_bf16 v[52:55], v[196:199], v[164:167], v[52:55]
	v_mfma_f32_16x16x32_bf16 v[44:47], v[204:207], v[164:167], v[44:47]
	v_mfma_f32_16x16x32_bf16 v[36:39], v[196:199], v[172:175], v[36:39]
	v_mfma_f32_16x16x32_bf16 v[32:35], v[204:207], v[172:175], v[32:35]
	v_mfma_f32_16x16x32_bf16 v[20:23], v[196:199], v[180:183], v[20:23]
	v_mfma_f32_16x16x32_bf16 v[12:15], v[204:207], v[180:183], v[12:15]
	v_mfma_f32_16x16x32_bf16 v[4:7], v[196:199], v[188:191], v[4:7]
	v_mfma_f32_16x16x32_bf16 v[0:3], v[204:207], v[188:191], v[0:3]
	v_mfma_f32_16x16x32_bf16 v[52:55], v[200:203], v[168:171], v[52:55]
	v_mfma_f32_16x16x32_bf16 v[44:47], v[208:211], v[168:171], v[44:47]
	v_mfma_f32_16x16x32_bf16 v[36:39], v[200:203], v[176:179], v[36:39]
	v_mfma_f32_16x16x32_bf16 v[32:35], v[208:211], v[176:179], v[32:35]
	v_mfma_f32_16x16x32_bf16 v[20:23], v[200:203], v[184:187], v[20:23]
	v_mfma_f32_16x16x32_bf16 v[12:15], v[208:211], v[184:187], v[12:15]
	v_mfma_f32_16x16x32_bf16 v[4:7], v[200:203], v[192:195], v[4:7]
	v_mfma_f32_16x16x32_bf16 v[0:3], v[208:211], v[192:195], v[0:3]
	s_setprio 0
	s_add_i32 s47, 0, 0x18000
	v_add_u32_e32 v160, s47, v147
	s_barrier
	ds_read_b128 v[140:143], v160
	ds_read_b128 v[152:155], v160 offset:1024
	ds_read_b128 v[156:159], v160 offset:2048
	ds_read_b128 v[160:163], v160 offset:3072
	s_add_u32 s18, s24, 0xb0000
	s_addc_u32 s19, s25, 0
	s_mov_b32 m0, s33
	v_lshl_add_u64 v[196:197], s[18:19], 0, v[128:129]
	ds_read_b128 v[164:167], v150 offset:32768
	ds_read_b128 v[168:171], v150 offset:33792
	ds_read_b128 v[172:175], v150 offset:34816
	ds_read_b128 v[176:179], v150 offset:35840
	ds_read_b128 v[180:183], v150 offset:36864
	ds_read_b128 v[184:187], v150 offset:37888
	ds_read_b128 v[188:191], v150 offset:38912
	ds_read_b128 v[192:195], v150 offset:39936
	global_load_lds_dwordx4 v[196:197], off
	v_lshl_add_u64 v[196:197], s[18:19], 0, v[130:131]
	s_mov_b32 m0, s34
	s_nop 0
	global_load_lds_dwordx4 v[196:197], off
	s_add_i32 s24, 0, 0x1c000
	v_add_u32_e32 v208, s24, v147
	ds_read_b128 v[196:199], v208
	ds_read_b128 v[200:203], v208 offset:1024
	ds_read_b128 v[204:207], v208 offset:2048
	ds_read_b128 v[208:211], v208 offset:3072
	s_waitcnt lgkmcnt(0)
	s_barrier
	s_setprio 1
	v_mfma_f32_16x16x32_bf16 v[124:127], v[140:143], v[164:167], v[124:127]
	v_mfma_f32_16x16x32_bf16 v[120:123], v[156:159], v[164:167], v[120:123]
	v_mfma_f32_16x16x32_bf16 v[112:115], v[140:143], v[172:175], v[112:115]
	v_mfma_f32_16x16x32_bf16 v[104:107], v[156:159], v[172:175], v[104:107]
	v_mfma_f32_16x16x32_bf16 v[92:95], v[140:143], v[180:183], v[92:95]
	v_mfma_f32_16x16x32_bf16 v[88:91], v[156:159], v[180:183], v[88:91]
	v_mfma_f32_16x16x32_bf16 v[80:83], v[140:143], v[188:191], v[80:83]
	v_mfma_f32_16x16x32_bf16 v[72:75], v[156:159], v[188:191], v[72:75]
	v_mfma_f32_16x16x32_bf16 v[124:127], v[152:155], v[168:171], v[124:127]
	v_mfma_f32_16x16x32_bf16 v[120:123], v[160:163], v[168:171], v[120:123]
	v_mfma_f32_16x16x32_bf16 v[112:115], v[152:155], v[176:179], v[112:115]
	v_mfma_f32_16x16x32_bf16 v[104:107], v[160:163], v[176:179], v[104:107]
	v_mfma_f32_16x16x32_bf16 v[92:95], v[152:155], v[184:187], v[92:95]
	v_mfma_f32_16x16x32_bf16 v[88:91], v[160:163], v[184:187], v[88:91]
	v_mfma_f32_16x16x32_bf16 v[80:83], v[152:155], v[192:195], v[80:83]
	v_mfma_f32_16x16x32_bf16 v[72:75], v[160:163], v[192:195], v[72:75]
	v_mfma_f32_16x16x32_bf16 v[116:119], v[196:199], v[164:167], v[116:119]
	v_mfma_f32_16x16x32_bf16 v[108:111], v[204:207], v[164:167], v[108:111]
	v_mfma_f32_16x16x32_bf16 v[100:103], v[196:199], v[172:175], v[100:103]
	v_mfma_f32_16x16x32_bf16 v[96:99], v[204:207], v[172:175], v[96:99]
	v_mfma_f32_16x16x32_bf16 v[84:87], v[196:199], v[180:183], v[84:87]
	v_mfma_f32_16x16x32_bf16 v[76:79], v[204:207], v[180:183], v[76:79]
	v_mfma_f32_16x16x32_bf16 v[68:71], v[196:199], v[188:191], v[68:71]
	v_mfma_f32_16x16x32_bf16 v[64:67], v[204:207], v[188:191], v[64:67]
	v_mfma_f32_16x16x32_bf16 v[116:119], v[200:203], v[168:171], v[116:119]
	v_mfma_f32_16x16x32_bf16 v[108:111], v[208:211], v[168:171], v[108:111]
	v_mfma_f32_16x16x32_bf16 v[100:103], v[200:203], v[176:179], v[100:103]
	v_mfma_f32_16x16x32_bf16 v[96:99], v[208:211], v[176:179], v[96:99]
	v_mfma_f32_16x16x32_bf16 v[84:87], v[200:203], v[184:187], v[84:87]
	v_mfma_f32_16x16x32_bf16 v[76:79], v[208:211], v[184:187], v[76:79]
	v_mfma_f32_16x16x32_bf16 v[68:71], v[200:203], v[192:195], v[68:71]
	v_mfma_f32_16x16x32_bf16 v[64:67], v[208:211], v[192:195], v[64:67]
	s_setprio 0
	s_barrier
; #define PG8_STAGE(bufoff, gbase, voff) do { _Pragma("unroll") for (int _i = 0; _i < 2; ++_i) \
;         __builtin_amdgcn_global_load_lds((const unsigned*)((const char*)(gbase) + (voff)[_i]), (LAS unsigned*)(lds + (bufoff) + ldsw + _i * 8192), 16, 0, 0); } while (0)
; #define PG8_LDA(dst, b, h) do { _Pragma("unroll") for (int m = 0; m < 4; ++m) _Pragma("unroll") for (int k = 0; k < 2; ++k) dst[m][k] = *(const LAS bf16x8*)(lds + PG8_SA(b, h) + aoff + m * 2048 + k * 1024); } while (0)
; #define PG8_BAR __builtin_amdgcn_s_barrier()
; template <class Epi>
; __device__ __forceinline__ void gemm_phase(LAS unsigned char* lds, const Gemm g, const StaticOrder& S, const Epi& E) {
;     ...
;             PG8_LDB(B0, 1, 0); PG8_SCHED; PG8_LDA(At, 1, 0); PG8_STAGE(PG8_SA(0, 1), a2 + hstepA, voffA);
;             PG8_WAIT_L(8); PG8_BAR; PG8_WAIT_L(0); PG8_MMA(0, 0, At, B0); PG8_BAR; PG8_SCHED;
;             PG8_LDB(B1, 1, 1); PG8_STAGE(PG8_SB(1, 0), b3, voffB);
;             PG8_BAR; PG8_WAIT_L(0); PG8_MMA(0, 1, At, B1); PG8_BAR;
;             PG8_LDA(At, 1, 1); PG8_STAGE(PG8_SA(1, 0), a3, voffA);
;             PG8_BAR; PG8_WAIT_L(0); PG8_MMA(1, 0, At, B0); PG8_BAR; PG8_SCHED;
;             PG8_STAGE(PG8_SB(1, 1), b3 + hstepB, voffB);
;             PG8_WAIT_V(6); PG8_BAR; PG8_MMA(1, 1, At, B1); PG8_BAR;
;     __device__ __forceinline__ void operator()(AccRef acc, const Unit& u, int wr, int wc, int fr, int fq) const {
;         const int row0 = u.pm * 256 + wr * 64 + fr, col0 = u.pn * 256 + wc * 32 + 4 * fq;
;         f32x4 sv[2][2], bv[2][2];
; #pragma unroll
;         for (int bj = 0; bj < 2; ++bj)
; #pragma unroll
;             for (int n = 0; n < 2; ++n) {
;                 sv[bj][n] = scale ? *(const f32x4*)(scale + col0 + bj * 128 + n * 16) : (f32x4){1.f, 1.f, 1.f, 1.f};
;                 bv[bj][n] = bias ? *(const f32x4*)(bias + col0 + bj * 128 + n * 16) : (f32x4){0.f, 0.f, 0.f, 0.f}; }
; #pragma unroll
;         for (int ai = 0; ai < 2; ++ai)
; #pragma unroll
;             for (int mh = 0; mh < 2; ++mh) {
;                 f32x4 bs[2][2][2];
; #pragma unroll
;                 for (int m = 0; m < 2; ++m)
; #pragma unroll
;                     for (int bj = 0; bj < 2; ++bj)
; #pragma unroll
;                         for (int n = 0; n < 2; ++n) bs[m][bj][n] = *(const f32x4*)(base + (size_t)(row0 + ai * 128 + (2 * mh + m) * 16) * D + col0 + bj * 128 + n * 16);
	s_nop 1
	ds_read_b128 v[164:167], v150 offset:49152
	ds_read_b128 v[168:171], v150 offset:50176
	ds_read_b128 v[172:175], v150 offset:51200
	ds_read_b128 v[176:179], v150 offset:52224
	ds_read_b128 v[180:183], v150 offset:53248
	ds_read_b128 v[184:187], v150 offset:54272
	ds_read_b128 v[188:191], v150 offset:55296
	ds_read_b128 v[192:195], v150 offset:56320
	s_add_i32 s18, s47, s29
	v_lshl_add_u64 v[254:255], v[144:145], 0, s[10:11]
	s_mov_b32 m0, s18
	s_nop 0
	global_load_lds_dwordx4 v[254:255], off
	v_lshl_add_u64 v[254:255], v[212:213], 0, s[10:11]
	s_add_i32 m0, s18, 0x2000
	s_nop 0
	global_load_lds_dwordx4 v[254:255], off
	s_mov_b32 m0, s36
	v_lshl_add_u64 v[254:255], v[214:215], 0, s[10:11]
	global_load_lds_dwordx4 v[254:255], off
	v_lshl_add_u64 v[144:145], v[216:217], 0, s[10:11]
	s_mov_b32 m0, s37
	s_nop 0
	global_load_lds_dwordx4 v[144:145], off
	s_add_u32 s18, s22, 0xb0080
	s_addc_u32 s19, s23, 0
	s_add_i32 s22, s24, s29
	v_lshl_add_u64 v[254:255], s[18:19], 0, v[128:129]
	s_mov_b32 m0, s22
	s_nop 0
	global_load_lds_dwordx4 v[254:255], off
	v_lshl_add_u64 v[254:255], s[18:19], 0, v[130:131]
	s_add_i32 m0, s22, 0x2000
	s_nop 0
	global_load_lds_dwordx4 v[254:255], off
	s_waitcnt vmcnt(6)
	s_waitcnt lgkmcnt(0)
	s_barrier
	s_setprio 1
	v_mfma_f32_16x16x32_bf16 v[60:63], v[140:143], v[164:167], v[60:63]
	v_mfma_f32_16x16x32_bf16 v[56:59], v[156:159], v[164:167], v[56:59]
	v_mfma_f32_16x16x32_bf16 v[48:51], v[140:143], v[172:175], v[48:51]
	v_mfma_f32_16x16x32_bf16 v[40:43], v[156:159], v[172:175], v[40:43]
	v_mfma_f32_16x16x32_bf16 v[28:31], v[140:143], v[180:183], v[28:31]
	v_mfma_f32_16x16x32_bf16 v[24:27], v[156:159], v[180:183], v[24:27]
	v_mfma_f32_16x16x32_bf16 v[16:19], v[140:143], v[188:191], v[16:19]
	v_mfma_f32_16x16x32_bf16 v[8:11], v[156:159], v[188:191], v[8:11]
	v_mfma_f32_16x16x32_bf16 v[60:63], v[152:155], v[168:171], v[60:63]
	v_mfma_f32_16x16x32_bf16 v[56:59], v[160:163], v[168:171], v[56:59]
	v_mfma_f32_16x16x32_bf16 v[48:51], v[152:155], v[176:179], v[48:51]
	v_mfma_f32_16x16x32_bf16 v[40:43], v[160:163], v[176:179], v[40:43]
	v_mfma_f32_16x16x32_bf16 v[28:31], v[152:155], v[184:187], v[28:31]
	v_mfma_f32_16x16x32_bf16 v[24:27], v[160:163], v[184:187], v[24:27]
	v_mfma_f32_16x16x32_bf16 v[16:19], v[152:155], v[192:195], v[16:19]
	v_mfma_f32_16x16x32_bf16 v[8:11], v[160:163], v[192:195], v[8:11]
	v_mfma_f32_16x16x32_bf16 v[52:55], v[196:199], v[164:167], v[52:55]
	v_mfma_f32_16x16x32_bf16 v[44:47], v[204:207], v[164:167], v[44:47]
	v_mfma_f32_16x16x32_bf16 v[36:39], v[196:199], v[172:175], v[36:39]
	v_mfma_f32_16x16x32_bf16 v[32:35], v[204:207], v[172:175], v[32:35]
	v_mfma_f32_16x16x32_bf16 v[20:23], v[196:199], v[180:183], v[20:23]
	v_mfma_f32_16x16x32_bf16 v[12:15], v[204:207], v[180:183], v[12:15]
	v_mfma_f32_16x16x32_bf16 v[4:7], v[196:199], v[188:191], v[4:7]
	v_mfma_f32_16x16x32_bf16 v[0:3], v[204:207], v[188:191], v[0:3]
	v_mfma_f32_16x16x32_bf16 v[52:55], v[200:203], v[168:171], v[52:55]
	v_mfma_f32_16x16x32_bf16 v[44:47], v[208:211], v[168:171], v[44:47]
	v_mfma_f32_16x16x32_bf16 v[36:39], v[200:203], v[176:179], v[36:39]
	v_mfma_f32_16x16x32_bf16 v[32:35], v[208:211], v[176:179], v[32:35]
	v_mfma_f32_16x16x32_bf16 v[20:23], v[200:203], v[184:187], v[20:23]
	v_mfma_f32_16x16x32_bf16 v[12:15], v[208:211], v[184:187], v[12:15]
	v_mfma_f32_16x16x32_bf16 v[4:7], v[200:203], v[192:195], v[4:7]
	v_mfma_f32_16x16x32_bf16 v[0:3], v[208:211], v[192:195], v[0:3]
	s_setprio 0
	s_add_i32 s46, s46, 2
	s_add_u32 s44, s44, 0x100
	s_addc_u32 s45, s45, 0
	s_cmp_gt_u32 s46, 41
	s_mov_b64 s[18:19], s[20:21]
	s_barrier
	s_cbranch_scc0 .LBB0_2042
	v_lshl_or_b32 v144, s42, 8, v148
	v_lshl_add_u32 v145, s43, 8, v146
	v_lshlrev_b32_e32 v144, 2, v144
	v_lshl_add_u32 v145, v145, 12, v144
	v_add_u32_e32 v216, 0x10000, v145
	v_add_u32_e32 v217, 0x20000, v145
	v_add_u32_e32 v218, 0x30000, v145
	v_add_u32_e32 v220, 0x80000, v145
	v_add_u32_e32 v221, 0x90000, v145
	v_add_u32_e32 v222, 0xa0000, v145
	v_add_u32_e32 v223, 0xb0000, v145
	v_and_b32_e32 v235, 8, v146
	v_cmp_ne_u32_e32 vcc, 0, v235
	v_mov_b32_e32 v232, 0xffff8040
	s_nop 0
	v_cndmask_b32_e32 v232, 0, v232, vcc
	v_mov_b32_e32 v233, 64
	v_mov_b32_e32 v235, 0x8000
	v_cndmask_b32_e32 v233, v235, v233, vcc
	v_add_u32_e32 v224, v145, v232
	v_add_u32_e32 v225, v216, v232
	v_add_u32_e32 v226, v217, v232
	v_add_u32_e32 v227, v218, v232
	v_add_u32_e32 v228, v220, v232
	v_add_u32_e32 v229, v221, v232
	v_add_u32_e32 v230, v222, v232
	v_add_u32_e32 v231, v223, v232
	s_and_b64 vcc, exec, s[0:1]
	s_mov_b32 s42, s40
	s_mov_b32 s43, s41
	s_mov_b64 s[20:21], s[6:7]
	s_mov_b64 s[18:19], s[4:5]
	global_load_dwordx4 v[140:143], v224, s[52:53]
	v_add_u32_e32 v144, v145, v233
	global_load_dwordx4 v[152:155], v144, s[52:53]
	global_load_dwordx4 v[156:159], v224, s[52:53] offset:512
	v_add_u32_e32 v144, v145, v233
	global_load_dwordx4 v[160:163], v144, s[52:53] offset:512
	global_load_dwordx4 v[164:167], v225, s[52:53]
	v_add_u32_e32 v144, v216, v233
	global_load_dwordx4 v[168:171], v144, s[52:53]
	global_load_dwordx4 v[172:175], v225, s[52:53] offset:512
	v_add_u32_e32 v144, v216, v233
	global_load_dwordx4 v[176:179], v144, s[52:53] offset:512
	global_load_dwordx4 v[180:183], v226, s[52:53]
	v_add_u32_e32 v144, v217, v233
	global_load_dwordx4 v[184:187], v144, s[52:53]
	global_load_dwordx4 v[188:191], v226, s[52:53] offset:512
	v_add_u32_e32 v144, v217, v233
	global_load_dwordx4 v[192:195], v144, s[52:53] offset:512
	global_load_dwordx4 v[196:199], v227, s[52:53]
	v_add_u32_e32 v144, v218, v233
	global_load_dwordx4 v[200:203], v144, s[52:53]
	global_load_dwordx4 v[204:207], v227, s[52:53] offset:512
;     __device__ __forceinline__ void operator()(AccRef acc, const Unit& u, int wr, int wc, int fr, int fq) const {
;     ...
;                         for (int n = 0; n < 2; ++n) bs[m][bj][n] = *(const f32x4*)(base + (size_t)(row0 + ai * 128 + (2 * mh + m) * 16) * D + col0 + bj * 128 + n * 16);
; #pragma unroll
;                 for (int m = 0; m < 2; ++m)
; #pragma unroll
;                     for (int bj = 0; bj < 2; ++bj)
; #pragma unroll
;                         for (int n = 0; n < 2; ++n) *(f32x4*)(out + (size_t)(row0 + ai * 128 + (2 * mh + m) * 16) * D + col0 + bj * 128 + n * 16) = bs[m][bj][n] + sv[bj][n] * (acc[ai][bj][2 * mh + m][n] + bv[bj][n]);
	v_add_u32_e32 v144, v218, v233
	global_load_dwordx4 v[208:211], v144, s[52:53] offset:512
	v_pk_add_f32 v[124:125], v[124:125], 0 op_sel_hi:[1,0]
	v_pk_add_f32 v[126:127], v[126:127], 0 op_sel_hi:[1,0]
	v_pk_add_f32 v[120:121], v[120:121], 0 op_sel_hi:[1,0]
	v_pk_add_f32 v[122:123], v[122:123], 0 op_sel_hi:[1,0]
	v_pk_add_f32 v[116:117], v[116:117], 0 op_sel_hi:[1,0]
	v_pk_add_f32 v[118:119], v[118:119], 0 op_sel_hi:[1,0]
	v_pk_add_f32 v[108:109], v[108:109], 0 op_sel_hi:[1,0]
	v_pk_add_f32 v[110:111], v[110:111], 0 op_sel_hi:[1,0]
	v_pk_add_f32 v[112:113], v[112:113], 0 op_sel_hi:[1,0]
	v_pk_add_f32 v[114:115], v[114:115], 0 op_sel_hi:[1,0]
	v_pk_add_f32 v[104:105], v[104:105], 0 op_sel_hi:[1,0]
	v_pk_add_f32 v[106:107], v[106:107], 0 op_sel_hi:[1,0]
	v_pk_add_f32 v[100:101], v[100:101], 0 op_sel_hi:[1,0]
	v_pk_add_f32 v[102:103], v[102:103], 0 op_sel_hi:[1,0]
	v_pk_add_f32 v[96:97], v[96:97], 0 op_sel_hi:[1,0]
	v_pk_add_f32 v[98:99], v[98:99], 0 op_sel_hi:[1,0]
	v_pk_add_f32 v[92:93], v[92:93], 0 op_sel_hi:[1,0]
	v_pk_add_f32 v[94:95], v[94:95], 0 op_sel_hi:[1,0]
	v_pk_add_f32 v[88:89], v[88:89], 0 op_sel_hi:[1,0]
	v_pk_add_f32 v[90:91], v[90:91], 0 op_sel_hi:[1,0]
	v_pk_add_f32 v[84:85], v[84:85], 0 op_sel_hi:[1,0]
	v_pk_add_f32 v[86:87], v[86:87], 0 op_sel_hi:[1,0]
	v_pk_add_f32 v[76:77], v[76:77], 0 op_sel_hi:[1,0]
	v_pk_add_f32 v[78:79], v[78:79], 0 op_sel_hi:[1,0]
	v_pk_add_f32 v[80:81], v[80:81], 0 op_sel_hi:[1,0]
	v_pk_add_f32 v[82:83], v[82:83], 0 op_sel_hi:[1,0]
	v_pk_add_f32 v[72:73], v[72:73], 0 op_sel_hi:[1,0]
	v_pk_add_f32 v[74:75], v[74:75], 0 op_sel_hi:[1,0]
	v_pk_add_f32 v[68:69], v[68:69], 0 op_sel_hi:[1,0]
	v_pk_add_f32 v[70:71], v[70:71], 0 op_sel_hi:[1,0]
	v_pk_add_f32 v[64:65], v[64:65], 0 op_sel_hi:[1,0]
	v_pk_add_f32 v[66:67], v[66:67], 0 op_sel_hi:[1,0]
	v_pk_add_f32 v[60:61], v[60:61], 0 op_sel_hi:[1,0]
	v_pk_add_f32 v[62:63], v[62:63], 0 op_sel_hi:[1,0]
	v_pk_add_f32 v[56:57], v[56:57], 0 op_sel_hi:[1,0]
	v_pk_add_f32 v[58:59], v[58:59], 0 op_sel_hi:[1,0]
	v_pk_add_f32 v[52:53], v[52:53], 0 op_sel_hi:[1,0]
	v_pk_add_f32 v[54:55], v[54:55], 0 op_sel_hi:[1,0]
	v_pk_add_f32 v[44:45], v[44:45], 0 op_sel_hi:[1,0]
	v_pk_add_f32 v[46:47], v[46:47], 0 op_sel_hi:[1,0]
	v_pk_add_f32 v[48:49], v[48:49], 0 op_sel_hi:[1,0]
	v_pk_add_f32 v[50:51], v[50:51], 0 op_sel_hi:[1,0]
	v_pk_add_f32 v[40:41], v[40:41], 0 op_sel_hi:[1,0]
	v_pk_add_f32 v[42:43], v[42:43], 0 op_sel_hi:[1,0]
	v_pk_add_f32 v[36:37], v[36:37], 0 op_sel_hi:[1,0]
	v_pk_add_f32 v[38:39], v[38:39], 0 op_sel_hi:[1,0]
	v_pk_add_f32 v[32:33], v[32:33], 0 op_sel_hi:[1,0]
	v_pk_add_f32 v[34:35], v[34:35], 0 op_sel_hi:[1,0]
	v_pk_add_f32 v[28:29], v[28:29], 0 op_sel_hi:[1,0]
	v_pk_add_f32 v[30:31], v[30:31], 0 op_sel_hi:[1,0]
	v_pk_add_f32 v[24:25], v[24:25], 0 op_sel_hi:[1,0]
	v_pk_add_f32 v[26:27], v[26:27], 0 op_sel_hi:[1,0]
	v_pk_add_f32 v[20:21], v[20:21], 0 op_sel_hi:[1,0]
	v_pk_add_f32 v[22:23], v[22:23], 0 op_sel_hi:[1,0]
	v_pk_add_f32 v[12:13], v[12:13], 0 op_sel_hi:[1,0]
	v_pk_add_f32 v[14:15], v[14:15], 0 op_sel_hi:[1,0]
	v_pk_add_f32 v[16:17], v[16:17], 0 op_sel_hi:[1,0]
	v_pk_add_f32 v[18:19], v[18:19], 0 op_sel_hi:[1,0]
	v_pk_add_f32 v[8:9], v[8:9], 0 op_sel_hi:[1,0]
	v_pk_add_f32 v[10:11], v[10:11], 0 op_sel_hi:[1,0]
	v_pk_add_f32 v[4:5], v[4:5], 0 op_sel_hi:[1,0]
	v_pk_add_f32 v[6:7], v[6:7], 0 op_sel_hi:[1,0]
	v_pk_add_f32 v[0:1], v[0:1], 0 op_sel_hi:[1,0]
	v_pk_add_f32 v[2:3], v[2:3], 0 op_sel_hi:[1,0]
	s_waitcnt vmcnt(8)
	v_mov_b32_e32 v212, v124
	v_mov_b32_e32 v213, v125
	v_mov_b32_e32 v214, v126
	v_mov_b32_e32 v215, v127
	s_nop 0
	v_mov_b32_dpp v124, v120 row_shr:8 row_mask:0xf bank_mask:0xc
	v_mov_b32_dpp v125, v121 row_shr:8 row_mask:0xf bank_mask:0xc
	v_mov_b32_dpp v126, v122 row_shr:8 row_mask:0xf bank_mask:0xc
	v_mov_b32_dpp v127, v123 row_shr:8 row_mask:0xf bank_mask:0xc
	v_mov_b32_dpp v120, v212 row_shl:8 row_mask:0xf bank_mask:0x3
	v_mov_b32_dpp v121, v213 row_shl:8 row_mask:0xf bank_mask:0x3
	v_mov_b32_dpp v122, v214 row_shl:8 row_mask:0xf bank_mask:0x3
	v_mov_b32_dpp v123, v215 row_shl:8 row_mask:0xf bank_mask:0x3
	v_mov_b32_e32 v212, v116
	v_mov_b32_e32 v213, v117
	v_mov_b32_e32 v214, v118
	v_mov_b32_e32 v215, v119
	s_nop 0
	v_mov_b32_dpp v116, v108 row_shr:8 row_mask:0xf bank_mask:0xc
	v_mov_b32_dpp v117, v109 row_shr:8 row_mask:0xf bank_mask:0xc
	v_mov_b32_dpp v118, v110 row_shr:8 row_mask:0xf bank_mask:0xc
	v_mov_b32_dpp v119, v111 row_shr:8 row_mask:0xf bank_mask:0xc
	v_mov_b32_dpp v108, v212 row_shl:8 row_mask:0xf bank_mask:0x3
	v_mov_b32_dpp v109, v213 row_shl:8 row_mask:0xf bank_mask:0x3
	v_mov_b32_dpp v110, v214 row_shl:8 row_mask:0xf bank_mask:0x3
	v_mov_b32_dpp v111, v215 row_shl:8 row_mask:0xf bank_mask:0x3
	v_mov_b32_e32 v212, v112
	v_mov_b32_e32 v213, v113
	v_mov_b32_e32 v214, v114
	v_mov_b32_e32 v215, v115
	s_nop 0
	v_mov_b32_dpp v112, v104 row_shr:8 row_mask:0xf bank_mask:0xc
	v_mov_b32_dpp v113, v105 row_shr:8 row_mask:0xf bank_mask:0xc
	v_mov_b32_dpp v114, v106 row_shr:8 row_mask:0xf bank_mask:0xc
	v_mov_b32_dpp v115, v107 row_shr:8 row_mask:0xf bank_mask:0xc
	v_mov_b32_dpp v104, v212 row_shl:8 row_mask:0xf bank_mask:0x3
	v_mov_b32_dpp v105, v213 row_shl:8 row_mask:0xf bank_mask:0x3
	v_mov_b32_dpp v106, v214 row_shl:8 row_mask:0xf bank_mask:0x3
	v_mov_b32_dpp v107, v215 row_shl:8 row_mask:0xf bank_mask:0x3
	v_mov_b32_e32 v212, v100
	v_mov_b32_e32 v213, v101
	v_mov_b32_e32 v214, v102
	v_mov_b32_e32 v215, v103
	s_nop 0
	v_mov_b32_dpp v100, v96 row_shr:8 row_mask:0xf bank_mask:0xc
	v_mov_b32_dpp v101, v97 row_shr:8 row_mask:0xf bank_mask:0xc
	v_mov_b32_dpp v102, v98 row_shr:8 row_mask:0xf bank_mask:0xc
;     __device__ __forceinline__ void operator()(AccRef acc, const Unit& u, int wr, int wc, int fr, int fq) const {
;     ...
;                         for (int n = 0; n < 2; ++n) bs[m][bj][n] = *(const f32x4*)(base + (size_t)(row0 + ai * 128 + (2 * mh + m) * 16) * D + col0 + bj * 128 + n * 16);
; #pragma unroll
;                 for (int m = 0; m < 2; ++m)
; #pragma unroll
;                     for (int bj = 0; bj < 2; ++bj)
; #pragma unroll
;                         for (int n = 0; n < 2; ++n) *(f32x4*)(out + (size_t)(row0 + ai * 128 + (2 * mh + m) * 16) * D + col0 + bj * 128 + n * 16) = bs[m][bj][n] + sv[bj][n] * (acc[ai][bj][2 * mh + m][n] + bv[bj][n]);
;                 asm volatile("" ::: "memory"); }
	v_mov_b32_dpp v103, v99 row_shr:8 row_mask:0xf bank_mask:0xc
	v_mov_b32_dpp v96, v212 row_shl:8 row_mask:0xf bank_mask:0x3
	v_mov_b32_dpp v97, v213 row_shl:8 row_mask:0xf bank_mask:0x3
	v_mov_b32_dpp v98, v214 row_shl:8 row_mask:0xf bank_mask:0x3
	v_mov_b32_dpp v99, v215 row_shl:8 row_mask:0xf bank_mask:0x3
	v_pk_add_f32 v[124:125], v[124:125], v[140:141]
	v_pk_add_f32 v[126:127], v[126:127], v[142:143]
	v_pk_add_f32 v[120:121], v[120:121], v[152:153]
	v_pk_add_f32 v[122:123], v[122:123], v[154:155]
	v_pk_add_f32 v[116:117], v[116:117], v[156:157]
	v_pk_add_f32 v[118:119], v[118:119], v[158:159]
	v_pk_add_f32 v[108:109], v[108:109], v[160:161]
	v_pk_add_f32 v[110:111], v[110:111], v[162:163]
	v_pk_add_f32 v[112:113], v[112:113], v[164:165]
	v_pk_add_f32 v[114:115], v[114:115], v[166:167]
	v_pk_add_f32 v[104:105], v[104:105], v[168:169]
	v_pk_add_f32 v[106:107], v[106:107], v[170:171]
	v_pk_add_f32 v[100:101], v[100:101], v[172:173]
	v_pk_add_f32 v[102:103], v[102:103], v[174:175]
	v_pk_add_f32 v[96:97], v[96:97], v[176:177]
	v_pk_add_f32 v[98:99], v[98:99], v[178:179]
	global_store_dwordx4 v224, v[124:127], s[52:53]
	v_add_u32_e32 v144, v145, v233
	global_store_dwordx4 v144, v[120:123], s[52:53]
	global_store_dwordx4 v224, v[116:119], s[52:53] offset:512
	v_add_u32_e32 v144, v145, v233
	global_store_dwordx4 v144, v[108:111], s[52:53] offset:512
	global_store_dwordx4 v225, v[112:115], s[52:53]
	v_add_u32_e32 v144, v216, v233
	global_store_dwordx4 v144, v[104:107], s[52:53]
	global_store_dwordx4 v225, v[100:103], s[52:53] offset:512
	v_add_u32_e32 v144, v216, v233
	global_store_dwordx4 v144, v[96:99], s[52:53] offset:512
	global_load_dwordx4 v[140:143], v228, s[52:53]
	v_add_u32_e32 v144, v220, v233
	global_load_dwordx4 v[152:155], v144, s[52:53]
	global_load_dwordx4 v[156:159], v228, s[52:53] offset:512
	v_add_u32_e32 v144, v220, v233
	global_load_dwordx4 v[160:163], v144, s[52:53] offset:512
	global_load_dwordx4 v[164:167], v229, s[52:53]
	v_add_u32_e32 v144, v221, v233
	global_load_dwordx4 v[168:171], v144, s[52:53]
	global_load_dwordx4 v[172:175], v229, s[52:53] offset:512
	v_add_u32_e32 v144, v221, v233
	global_load_dwordx4 v[176:179], v144, s[52:53] offset:512
	s_waitcnt vmcnt(16)
	v_mov_b32_e32 v212, v92
	v_mov_b32_e32 v213, v93
	v_mov_b32_e32 v214, v94
	v_mov_b32_e32 v215, v95
	s_nop 0
	v_mov_b32_dpp v92, v88 row_shr:8 row_mask:0xf bank_mask:0xc
	v_mov_b32_dpp v93, v89 row_shr:8 row_mask:0xf bank_mask:0xc
	v_mov_b32_dpp v94, v90 row_shr:8 row_mask:0xf bank_mask:0xc
	v_mov_b32_dpp v95, v91 row_shr:8 row_mask:0xf bank_mask:0xc
	v_mov_b32_dpp v88, v212 row_shl:8 row_mask:0xf bank_mask:0x3
	v_mov_b32_dpp v89, v213 row_shl:8 row_mask:0xf bank_mask:0x3
	v_mov_b32_dpp v90, v214 row_shl:8 row_mask:0xf bank_mask:0x3
	v_mov_b32_dpp v91, v215 row_shl:8 row_mask:0xf bank_mask:0x3
	v_mov_b32_e32 v212, v84
	v_mov_b32_e32 v213, v85
	v_mov_b32_e32 v214, v86
	v_mov_b32_e32 v215, v87
	s_nop 0
	v_mov_b32_dpp v84, v76 row_shr:8 row_mask:0xf bank_mask:0xc
	v_mov_b32_dpp v85, v77 row_shr:8 row_mask:0xf bank_mask:0xc
	v_mov_b32_dpp v86, v78 row_shr:8 row_mask:0xf bank_mask:0xc
	v_mov_b32_dpp v87, v79 row_shr:8 row_mask:0xf bank_mask:0xc
	v_mov_b32_dpp v76, v212 row_shl:8 row_mask:0xf bank_mask:0x3
	v_mov_b32_dpp v77, v213 row_shl:8 row_mask:0xf bank_mask:0x3
	v_mov_b32_dpp v78, v214 row_shl:8 row_mask:0xf bank_mask:0x3
	v_mov_b32_dpp v79, v215 row_shl:8 row_mask:0xf bank_mask:0x3
	v_mov_b32_e32 v212, v80
	v_mov_b32_e32 v213, v81
	v_mov_b32_e32 v214, v82
	v_mov_b32_e32 v215, v83
	s_nop 0
	v_mov_b32_dpp v80, v72 row_shr:8 row_mask:0xf bank_mask:0xc
	v_mov_b32_dpp v81, v73 row_shr:8 row_mask:0xf bank_mask:0xc
	v_mov_b32_dpp v82, v74 row_shr:8 row_mask:0xf bank_mask:0xc
	v_mov_b32_dpp v83, v75 row_shr:8 row_mask:0xf bank_mask:0xc
	v_mov_b32_dpp v72, v212 row_shl:8 row_mask:0xf bank_mask:0x3
	v_mov_b32_dpp v73, v213 row_shl:8 row_mask:0xf bank_mask:0x3
	v_mov_b32_dpp v74, v214 row_shl:8 row_mask:0xf bank_mask:0x3
	v_mov_b32_dpp v75, v215 row_shl:8 row_mask:0xf bank_mask:0x3
	v_mov_b32_e32 v212, v68
	v_mov_b32_e32 v213, v69
	v_mov_b32_e32 v214, v70
	v_mov_b32_e32 v215, v71
	s_nop 0
	v_mov_b32_dpp v68, v64 row_shr:8 row_mask:0xf bank_mask:0xc
	v_mov_b32_dpp v69, v65 row_shr:8 row_mask:0xf bank_mask:0xc
	v_mov_b32_dpp v70, v66 row_shr:8 row_mask:0xf bank_mask:0xc
	v_mov_b32_dpp v71, v67 row_shr:8 row_mask:0xf bank_mask:0xc
	v_mov_b32_dpp v64, v212 row_shl:8 row_mask:0xf bank_mask:0x3
	v_mov_b32_dpp v65, v213 row_shl:8 row_mask:0xf bank_mask:0x3
	v_mov_b32_dpp v66, v214 row_shl:8 row_mask:0xf bank_mask:0x3
	v_mov_b32_dpp v67, v215 row_shl:8 row_mask:0xf bank_mask:0x3
	v_pk_add_f32 v[92:93], v[92:93], v[180:181]
	v_pk_add_f32 v[94:95], v[94:95], v[182:183]
	v_pk_add_f32 v[88:89], v[88:89], v[184:185]
	v_pk_add_f32 v[90:91], v[90:91], v[186:187]
	v_pk_add_f32 v[84:85], v[84:85], v[188:189]
	v_pk_add_f32 v[86:87], v[86:87], v[190:191]
	v_pk_add_f32 v[76:77], v[76:77], v[192:193]
	v_pk_add_f32 v[78:79], v[78:79], v[194:195]
	v_pk_add_f32 v[80:81], v[80:81], v[196:197]
	v_pk_add_f32 v[82:83], v[82:83], v[198:199]
	v_pk_add_f32 v[72:73], v[72:73], v[200:201]
	v_pk_add_f32 v[74:75], v[74:75], v[202:203]
	v_pk_add_f32 v[68:69], v[68:69], v[204:205]
	v_pk_add_f32 v[70:71], v[70:71], v[206:207]
	v_pk_add_f32 v[64:65], v[64:65], v[208:209]
	v_pk_add_f32 v[66:67], v[66:67], v[210:211]
	global_store_dwordx4 v226, v[92:95], s[52:53]
	v_add_u32_e32 v144, v217, v233
	global_store_dwordx4 v144, v[88:91], s[52:53]
	global_store_dwordx4 v226, v[84:87], s[52:53] offset:512
	v_add_u32_e32 v144, v217, v233
	global_store_dwordx4 v144, v[76:79], s[52:53] offset:512
	global_store_dwordx4 v227, v[80:83], s[52:53]
	v_add_u32_e32 v144, v218, v233
	global_store_dwordx4 v144, v[72:75], s[52:53]
	global_store_dwordx4 v227, v[68:71], s[52:53] offset:512
	v_add_u32_e32 v144, v218, v233
	global_store_dwordx4 v144, v[64:67], s[52:53] offset:512
	global_load_dwordx4 v[180:183], v230, s[52:53]
	v_add_u32_e32 v144, v222, v233
	global_load_dwordx4 v[184:187], v144, s[52:53]
	global_load_dwordx4 v[188:191], v230, s[52:53] offset:512
	v_add_u32_e32 v144, v222, v233
	global_load_dwordx4 v[192:195], v144, s[52:53] offset:512
	global_load_dwordx4 v[196:199], v231, s[52:53]
	v_add_u32_e32 v144, v223, v233
	global_load_dwordx4 v[200:203], v144, s[52:53]
	global_load_dwordx4 v[204:207], v231, s[52:53] offset:512
	v_add_u32_e32 v144, v223, v233
	global_load_dwordx4 v[208:211], v144, s[52:53] offset:512
	s_waitcnt vmcnt(16)
;     __device__ __forceinline__ void operator()(AccRef acc, const Unit& u, int wr, int wc, int fr, int fq) const {
;     ...
;                         for (int n = 0; n < 2; ++n) bs[m][bj][n] = *(const f32x4*)(base + (size_t)(row0 + ai * 128 + (2 * mh + m) * 16) * D + col0 + bj * 128 + n * 16);
; #pragma unroll
;                 for (int m = 0; m < 2; ++m)
; #pragma unroll
;                     for (int bj = 0; bj < 2; ++bj)
; #pragma unroll
;                         for (int n = 0; n < 2; ++n) *(f32x4*)(out + (size_t)(row0 + ai * 128 + (2 * mh + m) * 16) * D + col0 + bj * 128 + n * 16) = bs[m][bj][n] + sv[bj][n] * (acc[ai][bj][2 * mh + m][n] + bv[bj][n]);
;                 asm volatile("" ::: "memory"); }
	v_mov_b32_e32 v212, v60
	v_mov_b32_e32 v213, v61
	v_mov_b32_e32 v214, v62
	v_mov_b32_e32 v215, v63
	s_nop 0
	v_mov_b32_dpp v60, v56 row_shr:8 row_mask:0xf bank_mask:0xc
	v_mov_b32_dpp v61, v57 row_shr:8 row_mask:0xf bank_mask:0xc
	v_mov_b32_dpp v62, v58 row_shr:8 row_mask:0xf bank_mask:0xc
	v_mov_b32_dpp v63, v59 row_shr:8 row_mask:0xf bank_mask:0xc
	v_mov_b32_dpp v56, v212 row_shl:8 row_mask:0xf bank_mask:0x3
	v_mov_b32_dpp v57, v213 row_shl:8 row_mask:0xf bank_mask:0x3
	v_mov_b32_dpp v58, v214 row_shl:8 row_mask:0xf bank_mask:0x3
	v_mov_b32_dpp v59, v215 row_shl:8 row_mask:0xf bank_mask:0x3
	v_mov_b32_e32 v212, v52
	v_mov_b32_e32 v213, v53
	v_mov_b32_e32 v214, v54
	v_mov_b32_e32 v215, v55
	s_nop 0
	v_mov_b32_dpp v52, v44 row_shr:8 row_mask:0xf bank_mask:0xc
	v_mov_b32_dpp v53, v45 row_shr:8 row_mask:0xf bank_mask:0xc
	v_mov_b32_dpp v54, v46 row_shr:8 row_mask:0xf bank_mask:0xc
	v_mov_b32_dpp v55, v47 row_shr:8 row_mask:0xf bank_mask:0xc
	v_mov_b32_dpp v44, v212 row_shl:8 row_mask:0xf bank_mask:0x3
	v_mov_b32_dpp v45, v213 row_shl:8 row_mask:0xf bank_mask:0x3
	v_mov_b32_dpp v46, v214 row_shl:8 row_mask:0xf bank_mask:0x3
	v_mov_b32_dpp v47, v215 row_shl:8 row_mask:0xf bank_mask:0x3
	v_mov_b32_e32 v212, v48
	v_mov_b32_e32 v213, v49
	v_mov_b32_e32 v214, v50
	v_mov_b32_e32 v215, v51
	s_nop 0
	v_mov_b32_dpp v48, v40 row_shr:8 row_mask:0xf bank_mask:0xc
	v_mov_b32_dpp v49, v41 row_shr:8 row_mask:0xf bank_mask:0xc
	v_mov_b32_dpp v50, v42 row_shr:8 row_mask:0xf bank_mask:0xc
	v_mov_b32_dpp v51, v43 row_shr:8 row_mask:0xf bank_mask:0xc
	v_mov_b32_dpp v40, v212 row_shl:8 row_mask:0xf bank_mask:0x3
	v_mov_b32_dpp v41, v213 row_shl:8 row_mask:0xf bank_mask:0x3
	v_mov_b32_dpp v42, v214 row_shl:8 row_mask:0xf bank_mask:0x3
	v_mov_b32_dpp v43, v215 row_shl:8 row_mask:0xf bank_mask:0x3
	v_mov_b32_e32 v212, v36
	v_mov_b32_e32 v213, v37
	v_mov_b32_e32 v214, v38
	v_mov_b32_e32 v215, v39
	s_nop 0
	v_mov_b32_dpp v36, v32 row_shr:8 row_mask:0xf bank_mask:0xc
	v_mov_b32_dpp v37, v33 row_shr:8 row_mask:0xf bank_mask:0xc
	v_mov_b32_dpp v38, v34 row_shr:8 row_mask:0xf bank_mask:0xc
	v_mov_b32_dpp v39, v35 row_shr:8 row_mask:0xf bank_mask:0xc
	v_mov_b32_dpp v32, v212 row_shl:8 row_mask:0xf bank_mask:0x3
	v_mov_b32_dpp v33, v213 row_shl:8 row_mask:0xf bank_mask:0x3
	v_mov_b32_dpp v34, v214 row_shl:8 row_mask:0xf bank_mask:0x3
	v_mov_b32_dpp v35, v215 row_shl:8 row_mask:0xf bank_mask:0x3
	v_pk_add_f32 v[60:61], v[60:61], v[140:141]
	v_pk_add_f32 v[62:63], v[62:63], v[142:143]
	v_pk_add_f32 v[56:57], v[56:57], v[152:153]
	v_pk_add_f32 v[58:59], v[58:59], v[154:155]
	v_pk_add_f32 v[52:53], v[52:53], v[156:157]
	v_pk_add_f32 v[54:55], v[54:55], v[158:159]
	v_pk_add_f32 v[44:45], v[44:45], v[160:161]
	v_pk_add_f32 v[46:47], v[46:47], v[162:163]
	v_pk_add_f32 v[48:49], v[48:49], v[164:165]
	v_pk_add_f32 v[50:51], v[50:51], v[166:167]
	v_pk_add_f32 v[40:41], v[40:41], v[168:169]
	v_pk_add_f32 v[42:43], v[42:43], v[170:171]
	v_pk_add_f32 v[36:37], v[36:37], v[172:173]
	v_pk_add_f32 v[38:39], v[38:39], v[174:175]
	v_pk_add_f32 v[32:33], v[32:33], v[176:177]
	v_pk_add_f32 v[34:35], v[34:35], v[178:179]
	global_store_dwordx4 v228, v[60:63], s[52:53]
	v_add_u32_e32 v144, v220, v233
	global_store_dwordx4 v144, v[56:59], s[52:53]
	global_store_dwordx4 v228, v[52:55], s[52:53] offset:512
	v_add_u32_e32 v144, v220, v233
	global_store_dwordx4 v144, v[44:47], s[52:53] offset:512
	global_store_dwordx4 v229, v[48:51], s[52:53]
	v_add_u32_e32 v144, v221, v233
	global_store_dwordx4 v144, v[40:43], s[52:53]
	global_store_dwordx4 v229, v[36:39], s[52:53] offset:512
	v_add_u32_e32 v144, v221, v233
	global_store_dwordx4 v144, v[32:35], s[52:53] offset:512
	s_waitcnt vmcnt(8)
; #define PG8_WAIT_V(n) asm volatile("s_waitcnt vmcnt(" #n ")" ::: "memory")
; #define PG8_BAR __builtin_amdgcn_s_barrier()
; template <class Epi>
; __device__ __forceinline__ void gemm_phase(LAS unsigned char* lds, const Gemm g, const StaticOrder& S, const Epi& E) {
;     ...
;     PG8_WAIT_V(0);
;     if (wr == 0) PG8_BAR;
;     PG8_BAR;
;     __device__ __forceinline__ void operator()(AccRef acc, const Unit& u, int wr, int wc, int fr, int fq) const {
;     ...
;                         for (int n = 0; n < 2; ++n) bs[m][bj][n] = *(const f32x4*)(base + (size_t)(row0 + ai * 128 + (2 * mh + m) * 16) * D + col0 + bj * 128 + n * 16);
; #pragma unroll
;                 for (int m = 0; m < 2; ++m)
; #pragma unroll
;                     for (int bj = 0; bj < 2; ++bj)
; #pragma unroll
;                         for (int n = 0; n < 2; ++n) *(f32x4*)(out + (size_t)(row0 + ai * 128 + (2 * mh + m) * 16) * D + col0 + bj * 128 + n * 16) = bs[m][bj][n] + sv[bj][n] * (acc[ai][bj][2 * mh + m][n] + bv[bj][n]);
;                 asm volatile("" ::: "memory"); }
	v_mov_b32_e32 v212, v28
	v_mov_b32_e32 v213, v29
	v_mov_b32_e32 v214, v30
	v_mov_b32_e32 v215, v31
	s_nop 0
	v_mov_b32_dpp v28, v24 row_shr:8 row_mask:0xf bank_mask:0xc
	v_mov_b32_dpp v29, v25 row_shr:8 row_mask:0xf bank_mask:0xc
	v_mov_b32_dpp v30, v26 row_shr:8 row_mask:0xf bank_mask:0xc
	v_mov_b32_dpp v31, v27 row_shr:8 row_mask:0xf bank_mask:0xc
	v_mov_b32_dpp v24, v212 row_shl:8 row_mask:0xf bank_mask:0x3
	v_mov_b32_dpp v25, v213 row_shl:8 row_mask:0xf bank_mask:0x3
	v_mov_b32_dpp v26, v214 row_shl:8 row_mask:0xf bank_mask:0x3
	v_mov_b32_dpp v27, v215 row_shl:8 row_mask:0xf bank_mask:0x3
	v_mov_b32_e32 v212, v20
	v_mov_b32_e32 v213, v21
	v_mov_b32_e32 v214, v22
	v_mov_b32_e32 v215, v23
	s_nop 0
	v_mov_b32_dpp v20, v12 row_shr:8 row_mask:0xf bank_mask:0xc
	v_mov_b32_dpp v21, v13 row_shr:8 row_mask:0xf bank_mask:0xc
	v_mov_b32_dpp v22, v14 row_shr:8 row_mask:0xf bank_mask:0xc
	v_mov_b32_dpp v23, v15 row_shr:8 row_mask:0xf bank_mask:0xc
	v_mov_b32_dpp v12, v212 row_shl:8 row_mask:0xf bank_mask:0x3
	v_mov_b32_dpp v13, v213 row_shl:8 row_mask:0xf bank_mask:0x3
	v_mov_b32_dpp v14, v214 row_shl:8 row_mask:0xf bank_mask:0x3
	v_mov_b32_dpp v15, v215 row_shl:8 row_mask:0xf bank_mask:0x3
	v_mov_b32_e32 v212, v16
	v_mov_b32_e32 v213, v17
	v_mov_b32_e32 v214, v18
	v_mov_b32_e32 v215, v19
	s_nop 0
	v_mov_b32_dpp v16, v8 row_shr:8 row_mask:0xf bank_mask:0xc
	v_mov_b32_dpp v17, v9 row_shr:8 row_mask:0xf bank_mask:0xc
	v_mov_b32_dpp v18, v10 row_shr:8 row_mask:0xf bank_mask:0xc
	v_mov_b32_dpp v19, v11 row_shr:8 row_mask:0xf bank_mask:0xc
	v_mov_b32_dpp v8, v212 row_shl:8 row_mask:0xf bank_mask:0x3
	v_mov_b32_dpp v9, v213 row_shl:8 row_mask:0xf bank_mask:0x3
	v_mov_b32_dpp v10, v214 row_shl:8 row_mask:0xf bank_mask:0x3
	v_mov_b32_dpp v11, v215 row_shl:8 row_mask:0xf bank_mask:0x3
	v_mov_b32_e32 v212, v4
	v_mov_b32_e32 v213, v5
	v_mov_b32_e32 v214, v6
	v_mov_b32_e32 v215, v7
	s_nop 0
	v_mov_b32_dpp v4, v0 row_shr:8 row_mask:0xf bank_mask:0xc
	v_mov_b32_dpp v5, v1 row_shr:8 row_mask:0xf bank_mask:0xc
	v_mov_b32_dpp v6, v2 row_shr:8 row_mask:0xf bank_mask:0xc
	v_mov_b32_dpp v7, v3 row_shr:8 row_mask:0xf bank_mask:0xc
	v_mov_b32_dpp v0, v212 row_shl:8 row_mask:0xf bank_mask:0x3
	v_mov_b32_dpp v1, v213 row_shl:8 row_mask:0xf bank_mask:0x3
	v_mov_b32_dpp v2, v214 row_shl:8 row_mask:0xf bank_mask:0x3
	v_mov_b32_dpp v3, v215 row_shl:8 row_mask:0xf bank_mask:0x3
	v_pk_add_f32 v[28:29], v[28:29], v[180:181]
	v_pk_add_f32 v[30:31], v[30:31], v[182:183]
	v_pk_add_f32 v[24:25], v[24:25], v[184:185]
	v_pk_add_f32 v[26:27], v[26:27], v[186:187]
	v_pk_add_f32 v[20:21], v[20:21], v[188:189]
	v_pk_add_f32 v[22:23], v[22:23], v[190:191]
	v_pk_add_f32 v[12:13], v[12:13], v[192:193]
	v_pk_add_f32 v[14:15], v[14:15], v[194:195]
	v_pk_add_f32 v[16:17], v[16:17], v[196:197]
	v_pk_add_f32 v[18:19], v[18:19], v[198:199]
	v_pk_add_f32 v[8:9], v[8:9], v[200:201]
	v_pk_add_f32 v[10:11], v[10:11], v[202:203]
	v_pk_add_f32 v[4:5], v[4:5], v[204:205]
	v_pk_add_f32 v[6:7], v[6:7], v[206:207]
	v_pk_add_f32 v[0:1], v[0:1], v[208:209]
	v_pk_add_f32 v[2:3], v[2:3], v[210:211]
	global_store_dwordx4 v230, v[28:31], s[52:53]
	v_add_u32_e32 v144, v222, v233
	global_store_dwordx4 v144, v[24:27], s[52:53]
	global_store_dwordx4 v230, v[20:23], s[52:53] offset:512
	v_add_u32_e32 v144, v222, v233
	global_store_dwordx4 v144, v[12:15], s[52:53] offset:512
	global_store_dwordx4 v231, v[16:19], s[52:53]
	v_add_u32_e32 v144, v223, v233
	global_store_dwordx4 v144, v[8:11], s[52:53]
	global_store_dwordx4 v231, v[4:7], s[52:53] offset:512
	v_add_u32_e32 v144, v223, v233
	global_store_dwordx4 v144, v[0:3], s[52:53] offset:512
	s_cbranch_vccz .LBB0_2031
	s_waitcnt vmcnt(0)
	s_cmpk_gt_u32 s26, 0xff
	s_cbranch_scc1 .LBB0_2046
	s_barrier
